# accumulator re-layout permlane swaps of 3 of 4 column blocks interleaved into the final k-step's MFMA stream
# speedup vs baseline: 1.0147x; 1.0098x over previous
.Lg16_proj_k:
	s_add_i32 s3, s1, 2
	s_lshl_b32 s96, s3, 13
	s_add_i32 m0, vcc_lo, 16384
	v_lshl_add_u64 v[160:161], v[188:189], 0, s[96:97]
	global_load_lds_dwordx4 v[160:161], off
	global_load_lds_dwordx4 v[160:161], off offset:1024
	ds_read_b128 v[236:239], v196 offset:0
	ds_read_b128 v[240:243], v196 offset:1024
	ds_read_b128 v[244:247], v196 offset:2048
	ds_read_b128 v[248:251], v196 offset:3072
	s_add_i32 s3, s1, 2
	s_lshl_b32 s96, s3, 11
	v_lshl_add_u64 v[198:199], v[184:185], 0, s[96:97]
	v_lshl_add_u64 v[200:201], v[186:187], 0, s[96:97]
	s_waitcnt vmcnt(8) lgkmcnt(3)
	v_mfma_f32_16x16x32_bf16 v[16:19], v[128:131], v[236:239], v[16:19]
	v_mfma_f32_16x16x32_bf16 v[24:27], v[132:135], v[236:239], v[24:27]
	v_mfma_f32_16x16x32_bf16 v[0:3], v[136:139], v[236:239], v[0:3]
	v_mfma_f32_16x16x32_bf16 v[8:11], v[140:143], v[236:239], v[8:11]
	ds_read_b128 v[236:239], v196 offset:4096
	s_waitcnt lgkmcnt(3)
	v_mfma_f32_16x16x32_bf16 v[20:23], v[128:131], v[240:243], v[20:23]
	v_mfma_f32_16x16x32_bf16 v[28:31], v[132:135], v[240:243], v[28:31]
	v_mfma_f32_16x16x32_bf16 v[4:7], v[136:139], v[240:243], v[4:7]
	v_mfma_f32_16x16x32_bf16 v[12:15], v[140:143], v[240:243], v[12:15]
	ds_read_b128 v[240:243], v196 offset:5120
	s_waitcnt lgkmcnt(3)
	v_mfma_f32_16x16x32_bf16 v[112:115], v[128:131], v[244:247], v[112:115]
	v_mfma_f32_16x16x32_bf16 v[120:123], v[132:135], v[244:247], v[120:123]
	v_mfma_f32_16x16x32_bf16 v[96:99], v[136:139], v[244:247], v[96:99]
	v_mfma_f32_16x16x32_bf16 v[104:107], v[140:143], v[244:247], v[104:107]
	ds_read_b128 v[244:247], v196 offset:6144
	s_waitcnt lgkmcnt(3)
	v_mfma_f32_16x16x32_bf16 v[116:119], v[128:131], v[248:251], v[116:119]
	v_mfma_f32_16x16x32_bf16 v[124:127], v[132:135], v[248:251], v[124:127]
	v_mfma_f32_16x16x32_bf16 v[100:103], v[136:139], v[248:251], v[100:103]
	v_mfma_f32_16x16x32_bf16 v[108:111], v[140:143], v[248:251], v[108:111]
	ds_read_b128 v[248:251], v196 offset:7168
	s_waitcnt lgkmcnt(3)
	v_mfma_f32_16x16x32_bf16 v[80:83], v[128:131], v[236:239], v[80:83]
	v_mfma_f32_16x16x32_bf16 v[88:91], v[132:135], v[236:239], v[88:91]
	v_mfma_f32_16x16x32_bf16 v[48:51], v[136:139], v[236:239], v[48:51]
	v_mfma_f32_16x16x32_bf16 v[56:59], v[140:143], v[236:239], v[56:59]
	s_waitcnt lgkmcnt(2)
	v_mfma_f32_16x16x32_bf16 v[84:87], v[128:131], v[240:243], v[84:87]
	v_mfma_f32_16x16x32_bf16 v[92:95], v[132:135], v[240:243], v[92:95]
	v_mfma_f32_16x16x32_bf16 v[52:55], v[136:139], v[240:243], v[52:55]
	v_mfma_f32_16x16x32_bf16 v[60:63], v[140:143], v[240:243], v[60:63]
	s_waitcnt lgkmcnt(1)
	v_mfma_f32_16x16x32_bf16 v[64:67], v[128:131], v[244:247], v[64:67]
	v_mfma_f32_16x16x32_bf16 v[72:75], v[132:135], v[244:247], v[72:75]
	v_mfma_f32_16x16x32_bf16 v[32:35], v[136:139], v[244:247], v[32:35]
	v_mfma_f32_16x16x32_bf16 v[40:43], v[140:143], v[244:247], v[40:43]
	s_waitcnt lgkmcnt(0)
	v_mfma_f32_16x16x32_bf16 v[68:71], v[128:131], v[248:251], v[68:71]
	v_mfma_f32_16x16x32_bf16 v[76:79], v[132:135], v[248:251], v[76:79]
	v_mfma_f32_16x16x32_bf16 v[36:39], v[136:139], v[248:251], v[36:39]
	v_mfma_f32_16x16x32_bf16 v[44:47], v[140:143], v[248:251], v[44:47]
	global_load_dwordx4 v[128:131], v[198:199], off
	global_load_dwordx4 v[132:135], v[198:199], off offset:256
	global_load_dwordx4 v[136:139], v[200:201], off
	global_load_dwordx4 v[140:143], v[200:201], off offset:256
	s_waitcnt vmcnt(10)
	s_barrier
	s_add_i32 s3, s1, 3
	s_lshl_b32 s96, s3, 13
	s_mov_b32 m0, vcc_lo
	v_lshl_add_u64 v[160:161], v[188:189], 0, s[96:97]
	global_load_lds_dwordx4 v[160:161], off
	global_load_lds_dwordx4 v[160:161], off offset:1024
	ds_read_b128 v[236:239], v196 offset:8192
	ds_read_b128 v[240:243], v196 offset:9216
	ds_read_b128 v[244:247], v196 offset:10240
	ds_read_b128 v[248:251], v196 offset:11264
	s_add_i32 s3, s1, 3
	s_lshl_b32 s96, s3, 11
	v_lshl_add_u64 v[198:199], v[184:185], 0, s[96:97]
	v_lshl_add_u64 v[200:201], v[186:187], 0, s[96:97]
	s_waitcnt vmcnt(8) lgkmcnt(3)
	v_mfma_f32_16x16x32_bf16 v[16:19], v[144:147], v[236:239], v[16:19]
	v_mfma_f32_16x16x32_bf16 v[24:27], v[148:151], v[236:239], v[24:27]
	v_mfma_f32_16x16x32_bf16 v[0:3], v[152:155], v[236:239], v[0:3]
	v_mfma_f32_16x16x32_bf16 v[8:11], v[156:159], v[236:239], v[8:11]
	ds_read_b128 v[236:239], v196 offset:12288
	s_waitcnt lgkmcnt(3)
	v_mfma_f32_16x16x32_bf16 v[20:23], v[144:147], v[240:243], v[20:23]
	v_mfma_f32_16x16x32_bf16 v[28:31], v[148:151], v[240:243], v[28:31]
	v_mfma_f32_16x16x32_bf16 v[4:7], v[152:155], v[240:243], v[4:7]
	v_mfma_f32_16x16x32_bf16 v[12:15], v[156:159], v[240:243], v[12:15]
	ds_read_b128 v[240:243], v196 offset:13312
	s_waitcnt lgkmcnt(3)
	v_mfma_f32_16x16x32_bf16 v[112:115], v[144:147], v[244:247], v[112:115]
	v_mfma_f32_16x16x32_bf16 v[120:123], v[148:151], v[244:247], v[120:123]
	v_mfma_f32_16x16x32_bf16 v[96:99], v[152:155], v[244:247], v[96:99]
	v_mfma_f32_16x16x32_bf16 v[104:107], v[156:159], v[244:247], v[104:107]
	ds_read_b128 v[244:247], v196 offset:14336
	s_waitcnt lgkmcnt(3)
	v_mfma_f32_16x16x32_bf16 v[116:119], v[144:147], v[248:251], v[116:119]
	v_mfma_f32_16x16x32_bf16 v[124:127], v[148:151], v[248:251], v[124:127]
	v_mfma_f32_16x16x32_bf16 v[100:103], v[152:155], v[248:251], v[100:103]
	v_mfma_f32_16x16x32_bf16 v[108:111], v[156:159], v[248:251], v[108:111]
	ds_read_b128 v[248:251], v196 offset:15360
	s_waitcnt lgkmcnt(3)
	v_mfma_f32_16x16x32_bf16 v[80:83], v[144:147], v[236:239], v[80:83]
	v_mfma_f32_16x16x32_bf16 v[88:91], v[148:151], v[236:239], v[88:91]
	v_mfma_f32_16x16x32_bf16 v[48:51], v[152:155], v[236:239], v[48:51]
	v_mfma_f32_16x16x32_bf16 v[56:59], v[156:159], v[236:239], v[56:59]
	s_waitcnt lgkmcnt(2)
	v_mfma_f32_16x16x32_bf16 v[84:87], v[144:147], v[240:243], v[84:87]
	v_mfma_f32_16x16x32_bf16 v[92:95], v[148:151], v[240:243], v[92:95]
	v_mfma_f32_16x16x32_bf16 v[52:55], v[152:155], v[240:243], v[52:55]
	v_mfma_f32_16x16x32_bf16 v[60:63], v[156:159], v[240:243], v[60:63]
	s_waitcnt lgkmcnt(1)
	v_mfma_f32_16x16x32_bf16 v[64:67], v[144:147], v[244:247], v[64:67]
	v_mfma_f32_16x16x32_bf16 v[72:75], v[148:151], v[244:247], v[72:75]
	v_mfma_f32_16x16x32_bf16 v[32:35], v[152:155], v[244:247], v[32:35]
	v_mfma_f32_16x16x32_bf16 v[40:43], v[156:159], v[244:247], v[40:43]
	s_waitcnt lgkmcnt(0)
	v_mfma_f32_16x16x32_bf16 v[68:71], v[144:147], v[248:251], v[68:71]
	v_mfma_f32_16x16x32_bf16 v[76:79], v[148:151], v[248:251], v[76:79]
	v_mfma_f32_16x16x32_bf16 v[36:39], v[152:155], v[248:251], v[36:39]
	v_mfma_f32_16x16x32_bf16 v[44:47], v[156:159], v[248:251], v[44:47]
	global_load_dwordx4 v[144:147], v[198:199], off
	global_load_dwordx4 v[148:151], v[198:199], off offset:256
	global_load_dwordx4 v[152:155], v[200:201], off
	global_load_dwordx4 v[156:159], v[200:201], off offset:256
	s_waitcnt vmcnt(10)
	s_barrier
	s_add_i32 s3, s1, 4
	s_lshl_b32 s96, s3, 13
	s_add_i32 m0, vcc_lo, 8192
	v_lshl_add_u64 v[160:161], v[188:189], 0, s[96:97]
	global_load_lds_dwordx4 v[160:161], off
	global_load_lds_dwordx4 v[160:161], off offset:1024
	ds_read_b128 v[236:239], v196 offset:16384
	ds_read_b128 v[240:243], v196 offset:17408
	ds_read_b128 v[244:247], v196 offset:18432
	ds_read_b128 v[248:251], v196 offset:19456
	s_add_i32 s3, s1, 4
	s_lshl_b32 s96, s3, 11
	v_lshl_add_u64 v[198:199], v[184:185], 0, s[96:97]
	v_lshl_add_u64 v[200:201], v[186:187], 0, s[96:97]
	s_waitcnt vmcnt(8) lgkmcnt(3)
	v_mfma_f32_16x16x32_bf16 v[16:19], v[128:131], v[236:239], v[16:19]
	v_mfma_f32_16x16x32_bf16 v[24:27], v[132:135], v[236:239], v[24:27]
	v_mfma_f32_16x16x32_bf16 v[0:3], v[136:139], v[236:239], v[0:3]
	v_mfma_f32_16x16x32_bf16 v[8:11], v[140:143], v[236:239], v[8:11]
	ds_read_b128 v[236:239], v196 offset:20480
	s_waitcnt lgkmcnt(3)
	v_mfma_f32_16x16x32_bf16 v[20:23], v[128:131], v[240:243], v[20:23]
	v_mfma_f32_16x16x32_bf16 v[28:31], v[132:135], v[240:243], v[28:31]
	v_mfma_f32_16x16x32_bf16 v[4:7], v[136:139], v[240:243], v[4:7]
	v_mfma_f32_16x16x32_bf16 v[12:15], v[140:143], v[240:243], v[12:15]
	ds_read_b128 v[240:243], v196 offset:21504
	s_waitcnt lgkmcnt(3)
	v_mfma_f32_16x16x32_bf16 v[112:115], v[128:131], v[244:247], v[112:115]
	v_mfma_f32_16x16x32_bf16 v[120:123], v[132:135], v[244:247], v[120:123]
	v_mfma_f32_16x16x32_bf16 v[96:99], v[136:139], v[244:247], v[96:99]
	v_mfma_f32_16x16x32_bf16 v[104:107], v[140:143], v[244:247], v[104:107]
	ds_read_b128 v[244:247], v196 offset:22528
	s_waitcnt lgkmcnt(3)
	v_mfma_f32_16x16x32_bf16 v[116:119], v[128:131], v[248:251], v[116:119]
	v_mfma_f32_16x16x32_bf16 v[124:127], v[132:135], v[248:251], v[124:127]
	v_mfma_f32_16x16x32_bf16 v[100:103], v[136:139], v[248:251], v[100:103]
	v_mfma_f32_16x16x32_bf16 v[108:111], v[140:143], v[248:251], v[108:111]
	ds_read_b128 v[248:251], v196 offset:23552
	s_waitcnt lgkmcnt(3)
	v_mfma_f32_16x16x32_bf16 v[80:83], v[128:131], v[236:239], v[80:83]
	v_mfma_f32_16x16x32_bf16 v[88:91], v[132:135], v[236:239], v[88:91]
	v_mfma_f32_16x16x32_bf16 v[48:51], v[136:139], v[236:239], v[48:51]
	v_mfma_f32_16x16x32_bf16 v[56:59], v[140:143], v[236:239], v[56:59]
	s_waitcnt lgkmcnt(2)
	v_mfma_f32_16x16x32_bf16 v[84:87], v[128:131], v[240:243], v[84:87]
	v_mfma_f32_16x16x32_bf16 v[92:95], v[132:135], v[240:243], v[92:95]
	v_mfma_f32_16x16x32_bf16 v[52:55], v[136:139], v[240:243], v[52:55]
	v_mfma_f32_16x16x32_bf16 v[60:63], v[140:143], v[240:243], v[60:63]
	s_waitcnt lgkmcnt(1)
	v_mfma_f32_16x16x32_bf16 v[64:67], v[128:131], v[244:247], v[64:67]
	v_mfma_f32_16x16x32_bf16 v[72:75], v[132:135], v[244:247], v[72:75]
	v_mfma_f32_16x16x32_bf16 v[32:35], v[136:139], v[244:247], v[32:35]
	v_mfma_f32_16x16x32_bf16 v[40:43], v[140:143], v[244:247], v[40:43]
	s_waitcnt lgkmcnt(0)
	v_mfma_f32_16x16x32_bf16 v[68:71], v[128:131], v[248:251], v[68:71]
	v_mfma_f32_16x16x32_bf16 v[76:79], v[132:135], v[248:251], v[76:79]
	v_mfma_f32_16x16x32_bf16 v[36:39], v[136:139], v[248:251], v[36:39]
	v_mfma_f32_16x16x32_bf16 v[44:47], v[140:143], v[248:251], v[44:47]
	global_load_dwordx4 v[128:131], v[198:199], off
	global_load_dwordx4 v[132:135], v[198:199], off offset:256
	global_load_dwordx4 v[136:139], v[200:201], off
	global_load_dwordx4 v[140:143], v[200:201], off offset:256
	s_waitcnt vmcnt(10)
	s_barrier
	s_add_i32 s3, s1, 5
	s_lshl_b32 s96, s3, 13
	s_add_i32 m0, vcc_lo, 16384
	v_lshl_add_u64 v[160:161], v[188:189], 0, s[96:97]
	global_load_lds_dwordx4 v[160:161], off
	global_load_lds_dwordx4 v[160:161], off offset:1024
	ds_read_b128 v[236:239], v196 offset:0
	ds_read_b128 v[240:243], v196 offset:1024
	ds_read_b128 v[244:247], v196 offset:2048
	ds_read_b128 v[248:251], v196 offset:3072
	s_add_i32 s3, s1, 5
	s_lshl_b32 s96, s3, 11
	v_lshl_add_u64 v[198:199], v[184:185], 0, s[96:97]
	v_lshl_add_u64 v[200:201], v[186:187], 0, s[96:97]
	s_waitcnt vmcnt(8) lgkmcnt(3)
	v_mfma_f32_16x16x32_bf16 v[16:19], v[144:147], v[236:239], v[16:19]
	v_mfma_f32_16x16x32_bf16 v[24:27], v[148:151], v[236:239], v[24:27]
	v_mfma_f32_16x16x32_bf16 v[0:3], v[152:155], v[236:239], v[0:3]
	v_mfma_f32_16x16x32_bf16 v[8:11], v[156:159], v[236:239], v[8:11]
	ds_read_b128 v[236:239], v196 offset:4096
	s_waitcnt lgkmcnt(3)
	v_mfma_f32_16x16x32_bf16 v[20:23], v[144:147], v[240:243], v[20:23]
	v_mfma_f32_16x16x32_bf16 v[28:31], v[148:151], v[240:243], v[28:31]
	v_mfma_f32_16x16x32_bf16 v[4:7], v[152:155], v[240:243], v[4:7]
	v_mfma_f32_16x16x32_bf16 v[12:15], v[156:159], v[240:243], v[12:15]
	ds_read_b128 v[240:243], v196 offset:5120
	s_waitcnt lgkmcnt(3)
	v_mfma_f32_16x16x32_bf16 v[112:115], v[144:147], v[244:247], v[112:115]
	v_mfma_f32_16x16x32_bf16 v[120:123], v[148:151], v[244:247], v[120:123]
	v_mfma_f32_16x16x32_bf16 v[96:99], v[152:155], v[244:247], v[96:99]
	v_mfma_f32_16x16x32_bf16 v[104:107], v[156:159], v[244:247], v[104:107]
	ds_read_b128 v[244:247], v196 offset:6144
	s_waitcnt lgkmcnt(3)
	v_mfma_f32_16x16x32_bf16 v[116:119], v[144:147], v[248:251], v[116:119]
	v_mfma_f32_16x16x32_bf16 v[124:127], v[148:151], v[248:251], v[124:127]
	v_mfma_f32_16x16x32_bf16 v[100:103], v[152:155], v[248:251], v[100:103]
	v_mfma_f32_16x16x32_bf16 v[108:111], v[156:159], v[248:251], v[108:111]
	ds_read_b128 v[248:251], v196 offset:7168
	s_waitcnt lgkmcnt(3)
	v_mfma_f32_16x16x32_bf16 v[80:83], v[144:147], v[236:239], v[80:83]
	v_mfma_f32_16x16x32_bf16 v[88:91], v[148:151], v[236:239], v[88:91]
	v_mfma_f32_16x16x32_bf16 v[48:51], v[152:155], v[236:239], v[48:51]
	v_mfma_f32_16x16x32_bf16 v[56:59], v[156:159], v[236:239], v[56:59]
	s_waitcnt lgkmcnt(2)
	v_mfma_f32_16x16x32_bf16 v[84:87], v[144:147], v[240:243], v[84:87]
	v_mfma_f32_16x16x32_bf16 v[92:95], v[148:151], v[240:243], v[92:95]
	v_mfma_f32_16x16x32_bf16 v[52:55], v[152:155], v[240:243], v[52:55]
	v_mfma_f32_16x16x32_bf16 v[60:63], v[156:159], v[240:243], v[60:63]
	s_waitcnt lgkmcnt(1)
	v_mfma_f32_16x16x32_bf16 v[64:67], v[144:147], v[244:247], v[64:67]
	v_mfma_f32_16x16x32_bf16 v[72:75], v[148:151], v[244:247], v[72:75]
	v_mfma_f32_16x16x32_bf16 v[32:35], v[152:155], v[244:247], v[32:35]
	v_mfma_f32_16x16x32_bf16 v[40:43], v[156:159], v[244:247], v[40:43]
	s_waitcnt lgkmcnt(0)
	v_mfma_f32_16x16x32_bf16 v[68:71], v[144:147], v[248:251], v[68:71]
	v_mfma_f32_16x16x32_bf16 v[76:79], v[148:151], v[248:251], v[76:79]
	v_mfma_f32_16x16x32_bf16 v[36:39], v[152:155], v[248:251], v[36:39]
	v_mfma_f32_16x16x32_bf16 v[44:47], v[156:159], v[248:251], v[44:47]
	global_load_dwordx4 v[144:147], v[198:199], off
	global_load_dwordx4 v[148:151], v[198:199], off offset:256
	global_load_dwordx4 v[152:155], v[200:201], off
	global_load_dwordx4 v[156:159], v[200:201], off offset:256
	s_waitcnt vmcnt(10)
	s_barrier
	s_add_i32 s3, s1, 6
	s_lshl_b32 s96, s3, 13
	s_mov_b32 m0, vcc_lo
	v_lshl_add_u64 v[160:161], v[188:189], 0, s[96:97]
	global_load_lds_dwordx4 v[160:161], off
	global_load_lds_dwordx4 v[160:161], off offset:1024
	ds_read_b128 v[236:239], v196 offset:8192
	ds_read_b128 v[240:243], v196 offset:9216
	ds_read_b128 v[244:247], v196 offset:10240
	ds_read_b128 v[248:251], v196 offset:11264
	s_add_i32 s3, s1, 6
	s_lshl_b32 s96, s3, 11
	v_lshl_add_u64 v[198:199], v[184:185], 0, s[96:97]
	v_lshl_add_u64 v[200:201], v[186:187], 0, s[96:97]
	s_waitcnt vmcnt(8) lgkmcnt(3)
	v_mfma_f32_16x16x32_bf16 v[16:19], v[128:131], v[236:239], v[16:19]
	v_mfma_f32_16x16x32_bf16 v[24:27], v[132:135], v[236:239], v[24:27]
	v_mfma_f32_16x16x32_bf16 v[0:3], v[136:139], v[236:239], v[0:3]
	v_mfma_f32_16x16x32_bf16 v[8:11], v[140:143], v[236:239], v[8:11]
	ds_read_b128 v[236:239], v196 offset:12288
	s_waitcnt lgkmcnt(3)
	v_mfma_f32_16x16x32_bf16 v[20:23], v[128:131], v[240:243], v[20:23]
	v_mfma_f32_16x16x32_bf16 v[28:31], v[132:135], v[240:243], v[28:31]
	v_mfma_f32_16x16x32_bf16 v[4:7], v[136:139], v[240:243], v[4:7]
	v_mfma_f32_16x16x32_bf16 v[12:15], v[140:143], v[240:243], v[12:15]
	ds_read_b128 v[240:243], v196 offset:13312
	s_waitcnt lgkmcnt(3)
	v_mfma_f32_16x16x32_bf16 v[112:115], v[128:131], v[244:247], v[112:115]
	v_mfma_f32_16x16x32_bf16 v[120:123], v[132:135], v[244:247], v[120:123]
	v_mfma_f32_16x16x32_bf16 v[96:99], v[136:139], v[244:247], v[96:99]
	v_mfma_f32_16x16x32_bf16 v[104:107], v[140:143], v[244:247], v[104:107]
	ds_read_b128 v[244:247], v196 offset:14336
	s_waitcnt lgkmcnt(3)
	v_mfma_f32_16x16x32_bf16 v[116:119], v[128:131], v[248:251], v[116:119]
	v_mfma_f32_16x16x32_bf16 v[124:127], v[132:135], v[248:251], v[124:127]
	v_mfma_f32_16x16x32_bf16 v[100:103], v[136:139], v[248:251], v[100:103]
	v_mfma_f32_16x16x32_bf16 v[108:111], v[140:143], v[248:251], v[108:111]
	ds_read_b128 v[248:251], v196 offset:15360
	s_waitcnt lgkmcnt(3)
	v_mfma_f32_16x16x32_bf16 v[80:83], v[128:131], v[236:239], v[80:83]
	v_mfma_f32_16x16x32_bf16 v[88:91], v[132:135], v[236:239], v[88:91]
	v_mfma_f32_16x16x32_bf16 v[48:51], v[136:139], v[236:239], v[48:51]
	v_mfma_f32_16x16x32_bf16 v[56:59], v[140:143], v[236:239], v[56:59]
	s_waitcnt lgkmcnt(2)
	v_mfma_f32_16x16x32_bf16 v[84:87], v[128:131], v[240:243], v[84:87]
	v_mfma_f32_16x16x32_bf16 v[92:95], v[132:135], v[240:243], v[92:95]
	v_mfma_f32_16x16x32_bf16 v[52:55], v[136:139], v[240:243], v[52:55]
	v_mfma_f32_16x16x32_bf16 v[60:63], v[140:143], v[240:243], v[60:63]
	s_waitcnt lgkmcnt(1)
	v_mfma_f32_16x16x32_bf16 v[64:67], v[128:131], v[244:247], v[64:67]
	v_mfma_f32_16x16x32_bf16 v[72:75], v[132:135], v[244:247], v[72:75]
	v_mfma_f32_16x16x32_bf16 v[32:35], v[136:139], v[244:247], v[32:35]
	v_mfma_f32_16x16x32_bf16 v[40:43], v[140:143], v[244:247], v[40:43]
	s_waitcnt lgkmcnt(0)
	v_mfma_f32_16x16x32_bf16 v[68:71], v[128:131], v[248:251], v[68:71]
	v_mfma_f32_16x16x32_bf16 v[76:79], v[132:135], v[248:251], v[76:79]
	v_mfma_f32_16x16x32_bf16 v[36:39], v[136:139], v[248:251], v[36:39]
	v_mfma_f32_16x16x32_bf16 v[44:47], v[140:143], v[248:251], v[44:47]
	global_load_dwordx4 v[128:131], v[198:199], off
	global_load_dwordx4 v[132:135], v[198:199], off offset:256
	global_load_dwordx4 v[136:139], v[200:201], off
	global_load_dwordx4 v[140:143], v[200:201], off offset:256
	s_waitcnt vmcnt(10)
	s_barrier
	s_add_i32 s3, s1, 7
	s_lshl_b32 s96, s3, 13
	s_add_i32 m0, vcc_lo, 8192
	v_lshl_add_u64 v[160:161], v[188:189], 0, s[96:97]
	global_load_lds_dwordx4 v[160:161], off
	global_load_lds_dwordx4 v[160:161], off offset:1024
	ds_read_b128 v[236:239], v196 offset:16384
	ds_read_b128 v[240:243], v196 offset:17408
	ds_read_b128 v[244:247], v196 offset:18432
	ds_read_b128 v[248:251], v196 offset:19456
	s_add_i32 s3, s1, 7
	s_lshl_b32 s96, s3, 11
	v_lshl_add_u64 v[198:199], v[184:185], 0, s[96:97]
	v_lshl_add_u64 v[200:201], v[186:187], 0, s[96:97]
	s_waitcnt vmcnt(8) lgkmcnt(3)
	v_mfma_f32_16x16x32_bf16 v[16:19], v[144:147], v[236:239], v[16:19]
	v_mfma_f32_16x16x32_bf16 v[24:27], v[148:151], v[236:239], v[24:27]
	v_mfma_f32_16x16x32_bf16 v[0:3], v[152:155], v[236:239], v[0:3]
	v_mfma_f32_16x16x32_bf16 v[8:11], v[156:159], v[236:239], v[8:11]
	ds_read_b128 v[236:239], v196 offset:20480
	s_waitcnt lgkmcnt(3)
	v_mfma_f32_16x16x32_bf16 v[20:23], v[144:147], v[240:243], v[20:23]
	v_mfma_f32_16x16x32_bf16 v[28:31], v[148:151], v[240:243], v[28:31]
	v_mfma_f32_16x16x32_bf16 v[4:7], v[152:155], v[240:243], v[4:7]
	v_mfma_f32_16x16x32_bf16 v[12:15], v[156:159], v[240:243], v[12:15]
	ds_read_b128 v[240:243], v196 offset:21504
	s_waitcnt lgkmcnt(3)
	v_mfma_f32_16x16x32_bf16 v[112:115], v[144:147], v[244:247], v[112:115]
	v_mfma_f32_16x16x32_bf16 v[120:123], v[148:151], v[244:247], v[120:123]
	v_mfma_f32_16x16x32_bf16 v[96:99], v[152:155], v[244:247], v[96:99]
	v_mfma_f32_16x16x32_bf16 v[104:107], v[156:159], v[244:247], v[104:107]
	ds_read_b128 v[244:247], v196 offset:22528
	s_waitcnt lgkmcnt(3)
	v_mfma_f32_16x16x32_bf16 v[116:119], v[144:147], v[248:251], v[116:119]
	v_mfma_f32_16x16x32_bf16 v[124:127], v[148:151], v[248:251], v[124:127]
	v_mfma_f32_16x16x32_bf16 v[100:103], v[152:155], v[248:251], v[100:103]
	v_mfma_f32_16x16x32_bf16 v[108:111], v[156:159], v[248:251], v[108:111]
	ds_read_b128 v[248:251], v196 offset:23552
	s_waitcnt lgkmcnt(3)
	v_mfma_f32_16x16x32_bf16 v[80:83], v[144:147], v[236:239], v[80:83]
	v_mfma_f32_16x16x32_bf16 v[88:91], v[148:151], v[236:239], v[88:91]
	v_mfma_f32_16x16x32_bf16 v[48:51], v[152:155], v[236:239], v[48:51]
	v_mfma_f32_16x16x32_bf16 v[56:59], v[156:159], v[236:239], v[56:59]
	s_waitcnt lgkmcnt(2)
	v_mfma_f32_16x16x32_bf16 v[84:87], v[144:147], v[240:243], v[84:87]
	v_mfma_f32_16x16x32_bf16 v[92:95], v[148:151], v[240:243], v[92:95]
	v_mfma_f32_16x16x32_bf16 v[52:55], v[152:155], v[240:243], v[52:55]
	v_mfma_f32_16x16x32_bf16 v[60:63], v[156:159], v[240:243], v[60:63]
	s_waitcnt lgkmcnt(1)
	v_mfma_f32_16x16x32_bf16 v[64:67], v[144:147], v[244:247], v[64:67]
	v_mfma_f32_16x16x32_bf16 v[72:75], v[148:151], v[244:247], v[72:75]
	v_mfma_f32_16x16x32_bf16 v[32:35], v[152:155], v[244:247], v[32:35]
	v_mfma_f32_16x16x32_bf16 v[40:43], v[156:159], v[244:247], v[40:43]
	s_waitcnt lgkmcnt(0)
	v_mfma_f32_16x16x32_bf16 v[68:71], v[144:147], v[248:251], v[68:71]
	v_mfma_f32_16x16x32_bf16 v[76:79], v[148:151], v[248:251], v[76:79]
	v_mfma_f32_16x16x32_bf16 v[36:39], v[152:155], v[248:251], v[36:39]
	v_mfma_f32_16x16x32_bf16 v[44:47], v[156:159], v[248:251], v[44:47]
	global_load_dwordx4 v[144:147], v[198:199], off
	global_load_dwordx4 v[148:151], v[198:199], off offset:256
	global_load_dwordx4 v[152:155], v[200:201], off
	global_load_dwordx4 v[156:159], v[200:201], off offset:256
	s_waitcnt vmcnt(10)
	s_barrier
	s_add_i32 s1, s1, 6
	s_cmp_lt_u32 s1, 30
	s_cbranch_scc1 .Lg16_proj_k
	ds_read_b128 v[236:239], v196 offset:0
	ds_read_b128 v[240:243], v196 offset:1024
	ds_read_b128 v[244:247], v196 offset:2048
	ds_read_b128 v[248:251], v196 offset:3072
	s_waitcnt vmcnt(6) lgkmcnt(3)
	v_mfma_f32_16x16x32_bf16 v[16:19], v[128:131], v[236:239], v[16:19]
	v_mfma_f32_16x16x32_bf16 v[24:27], v[132:135], v[236:239], v[24:27]
	v_mfma_f32_16x16x32_bf16 v[0:3], v[136:139], v[236:239], v[0:3]
	v_mfma_f32_16x16x32_bf16 v[8:11], v[140:143], v[236:239], v[8:11]
	ds_read_b128 v[236:239], v196 offset:4096
	s_waitcnt lgkmcnt(3)
	v_mfma_f32_16x16x32_bf16 v[20:23], v[128:131], v[240:243], v[20:23]
	v_mfma_f32_16x16x32_bf16 v[28:31], v[132:135], v[240:243], v[28:31]
	v_mfma_f32_16x16x32_bf16 v[4:7], v[136:139], v[240:243], v[4:7]
	v_mfma_f32_16x16x32_bf16 v[12:15], v[140:143], v[240:243], v[12:15]
	ds_read_b128 v[240:243], v196 offset:5120
	s_waitcnt lgkmcnt(3)
	v_mfma_f32_16x16x32_bf16 v[112:115], v[128:131], v[244:247], v[112:115]
	v_mfma_f32_16x16x32_bf16 v[120:123], v[132:135], v[244:247], v[120:123]
	v_mfma_f32_16x16x32_bf16 v[96:99], v[136:139], v[244:247], v[96:99]
	v_mfma_f32_16x16x32_bf16 v[104:107], v[140:143], v[244:247], v[104:107]
	ds_read_b128 v[244:247], v196 offset:6144
	s_waitcnt lgkmcnt(3)
	v_mfma_f32_16x16x32_bf16 v[116:119], v[128:131], v[248:251], v[116:119]
	v_mfma_f32_16x16x32_bf16 v[124:127], v[132:135], v[248:251], v[124:127]
	v_mfma_f32_16x16x32_bf16 v[100:103], v[136:139], v[248:251], v[100:103]
	v_mfma_f32_16x16x32_bf16 v[108:111], v[140:143], v[248:251], v[108:111]
	ds_read_b128 v[248:251], v196 offset:7168
	s_waitcnt lgkmcnt(3)
	v_mfma_f32_16x16x32_bf16 v[80:83], v[128:131], v[236:239], v[80:83]
	v_mfma_f32_16x16x32_bf16 v[88:91], v[132:135], v[236:239], v[88:91]
	v_mfma_f32_16x16x32_bf16 v[48:51], v[136:139], v[236:239], v[48:51]
	v_mfma_f32_16x16x32_bf16 v[56:59], v[140:143], v[236:239], v[56:59]
	s_waitcnt lgkmcnt(2)
	v_mfma_f32_16x16x32_bf16 v[84:87], v[128:131], v[240:243], v[84:87]
	v_mfma_f32_16x16x32_bf16 v[92:95], v[132:135], v[240:243], v[92:95]
	v_mfma_f32_16x16x32_bf16 v[52:55], v[136:139], v[240:243], v[52:55]
	v_mfma_f32_16x16x32_bf16 v[60:63], v[140:143], v[240:243], v[60:63]
	s_waitcnt lgkmcnt(1)
	v_mfma_f32_16x16x32_bf16 v[64:67], v[128:131], v[244:247], v[64:67]
	v_mfma_f32_16x16x32_bf16 v[72:75], v[132:135], v[244:247], v[72:75]
	v_mfma_f32_16x16x32_bf16 v[32:35], v[136:139], v[244:247], v[32:35]
	v_mfma_f32_16x16x32_bf16 v[40:43], v[140:143], v[244:247], v[40:43]
	s_waitcnt lgkmcnt(0)
	v_mfma_f32_16x16x32_bf16 v[68:71], v[128:131], v[248:251], v[68:71]
	v_mfma_f32_16x16x32_bf16 v[76:79], v[132:135], v[248:251], v[76:79]
	v_mfma_f32_16x16x32_bf16 v[36:39], v[136:139], v[248:251], v[36:39]
	v_mfma_f32_16x16x32_bf16 v[44:47], v[140:143], v[248:251], v[44:47]
	s_waitcnt vmcnt(4)
	s_barrier
	ds_read_b128 v[236:239], v196 offset:8192
	ds_read_b128 v[240:243], v196 offset:9216
	ds_read_b128 v[244:247], v196 offset:10240
	ds_read_b128 v[248:251], v196 offset:11264
	s_waitcnt vmcnt(0) lgkmcnt(3)
	v_mfma_f32_16x16x32_bf16 v[16:19], v[144:147], v[236:239], v[16:19]
	v_mfma_f32_16x16x32_bf16 v[24:27], v[148:151], v[236:239], v[24:27]
	v_mfma_f32_16x16x32_bf16 v[0:3], v[152:155], v[236:239], v[0:3]
	v_mfma_f32_16x16x32_bf16 v[8:11], v[156:159], v[236:239], v[8:11]
	ds_read_b128 v[236:239], v196 offset:12288
	s_waitcnt lgkmcnt(3)
	v_mfma_f32_16x16x32_bf16 v[20:23], v[144:147], v[240:243], v[20:23]
	v_mfma_f32_16x16x32_bf16 v[28:31], v[148:151], v[240:243], v[28:31]
	v_mfma_f32_16x16x32_bf16 v[4:7], v[152:155], v[240:243], v[4:7]
	v_mfma_f32_16x16x32_bf16 v[12:15], v[156:159], v[240:243], v[12:15]
	ds_read_b128 v[240:243], v196 offset:13312
	s_waitcnt lgkmcnt(3)
	v_mfma_f32_16x16x32_bf16 v[112:115], v[144:147], v[244:247], v[112:115]
	v_mfma_f32_16x16x32_bf16 v[120:123], v[148:151], v[244:247], v[120:123]
	v_mfma_f32_16x16x32_bf16 v[96:99], v[152:155], v[244:247], v[96:99]
	v_mfma_f32_16x16x32_bf16 v[104:107], v[156:159], v[244:247], v[104:107]
	ds_read_b128 v[244:247], v196 offset:14336
	s_waitcnt lgkmcnt(3)
	v_mfma_f32_16x16x32_bf16 v[116:119], v[144:147], v[248:251], v[116:119]
	v_mfma_f32_16x16x32_bf16 v[124:127], v[148:151], v[248:251], v[124:127]
	v_mfma_f32_16x16x32_bf16 v[100:103], v[152:155], v[248:251], v[100:103]
	v_mfma_f32_16x16x32_bf16 v[108:111], v[156:159], v[248:251], v[108:111]
	ds_read_b128 v[248:251], v196 offset:15360
	v_permlane16_swap_b32_e32 v16, v20
	v_permlane16_swap_b32_e32 v17, v21
	v_permlane16_swap_b32_e32 v18, v22
	v_permlane16_swap_b32_e32 v19, v23
	v_permlane16_swap_b32_e32 v24, v28
	v_permlane16_swap_b32_e32 v25, v29
	v_permlane16_swap_b32_e32 v26, v30
	v_permlane16_swap_b32_e32 v27, v31
	v_permlane16_swap_b32_e32 v0, v4
	v_permlane16_swap_b32_e32 v1, v5
	v_permlane16_swap_b32_e32 v2, v6
	v_permlane16_swap_b32_e32 v3, v7
	v_permlane16_swap_b32_e32 v8, v12
	v_permlane16_swap_b32_e32 v9, v13
	v_permlane16_swap_b32_e32 v10, v14
	v_permlane16_swap_b32_e32 v11, v15
	v_permlane32_swap_b32_e32 v16, v20
	v_permlane32_swap_b32_e32 v17, v21
	v_permlane32_swap_b32_e32 v18, v22
	v_permlane32_swap_b32_e32 v19, v23
	v_permlane32_swap_b32_e32 v24, v28
	v_permlane32_swap_b32_e32 v25, v29
	v_permlane32_swap_b32_e32 v26, v30
	v_permlane32_swap_b32_e32 v27, v31
	v_permlane32_swap_b32_e32 v0, v4
	v_permlane32_swap_b32_e32 v1, v5
	v_permlane32_swap_b32_e32 v2, v6
	v_permlane32_swap_b32_e32 v3, v7
	v_permlane32_swap_b32_e32 v8, v12
	v_permlane32_swap_b32_e32 v9, v13
	v_permlane32_swap_b32_e32 v10, v14
	v_permlane32_swap_b32_e32 v11, v15
	s_waitcnt lgkmcnt(3)
	v_mfma_f32_16x16x32_bf16 v[80:83], v[144:147], v[236:239], v[80:83]
	v_mfma_f32_16x16x32_bf16 v[88:91], v[148:151], v[236:239], v[88:91]
	v_mfma_f32_16x16x32_bf16 v[48:51], v[152:155], v[236:239], v[48:51]
	v_mfma_f32_16x16x32_bf16 v[56:59], v[156:159], v[236:239], v[56:59]
	s_waitcnt lgkmcnt(2)
	v_mfma_f32_16x16x32_bf16 v[84:87], v[144:147], v[240:243], v[84:87]
	v_mfma_f32_16x16x32_bf16 v[92:95], v[148:151], v[240:243], v[92:95]
	v_mfma_f32_16x16x32_bf16 v[52:55], v[152:155], v[240:243], v[52:55]
	v_mfma_f32_16x16x32_bf16 v[60:63], v[156:159], v[240:243], v[60:63]
	v_permlane16_swap_b32_e32 v112, v116
	v_permlane16_swap_b32_e32 v113, v117
	v_permlane16_swap_b32_e32 v114, v118
	v_permlane16_swap_b32_e32 v115, v119
	v_permlane16_swap_b32_e32 v120, v124
	v_permlane16_swap_b32_e32 v121, v125
	v_permlane16_swap_b32_e32 v122, v126
	v_permlane16_swap_b32_e32 v123, v127
	v_permlane16_swap_b32_e32 v96, v100
	v_permlane16_swap_b32_e32 v97, v101
	v_permlane16_swap_b32_e32 v98, v102
	v_permlane16_swap_b32_e32 v99, v103
	v_permlane16_swap_b32_e32 v104, v108
	v_permlane16_swap_b32_e32 v105, v109
	v_permlane16_swap_b32_e32 v106, v110
	v_permlane16_swap_b32_e32 v107, v111
	v_permlane32_swap_b32_e32 v112, v116
	v_permlane32_swap_b32_e32 v113, v117
	v_permlane32_swap_b32_e32 v114, v118
	v_permlane32_swap_b32_e32 v115, v119
	v_permlane32_swap_b32_e32 v120, v124
	v_permlane32_swap_b32_e32 v121, v125
	v_permlane32_swap_b32_e32 v122, v126
	v_permlane32_swap_b32_e32 v123, v127
	v_permlane32_swap_b32_e32 v96, v100
	v_permlane32_swap_b32_e32 v97, v101
	v_permlane32_swap_b32_e32 v98, v102
	v_permlane32_swap_b32_e32 v99, v103
	v_permlane32_swap_b32_e32 v104, v108
	v_permlane32_swap_b32_e32 v105, v109
	v_permlane32_swap_b32_e32 v106, v110
	v_permlane32_swap_b32_e32 v107, v111
	s_waitcnt lgkmcnt(1)
	v_mfma_f32_16x16x32_bf16 v[64:67], v[144:147], v[244:247], v[64:67]
	v_mfma_f32_16x16x32_bf16 v[72:75], v[148:151], v[244:247], v[72:75]
	v_mfma_f32_16x16x32_bf16 v[32:35], v[152:155], v[244:247], v[32:35]
	v_mfma_f32_16x16x32_bf16 v[40:43], v[156:159], v[244:247], v[40:43]
	s_waitcnt lgkmcnt(0)
	v_mfma_f32_16x16x32_bf16 v[68:71], v[144:147], v[248:251], v[68:71]
	v_mfma_f32_16x16x32_bf16 v[76:79], v[148:151], v[248:251], v[76:79]
	v_mfma_f32_16x16x32_bf16 v[36:39], v[152:155], v[248:251], v[36:39]
	v_mfma_f32_16x16x32_bf16 v[44:47], v[156:159], v[248:251], v[44:47]
	v_permlane16_swap_b32_e32 v80, v84
	v_permlane16_swap_b32_e32 v81, v85
	v_permlane16_swap_b32_e32 v82, v86
	v_permlane16_swap_b32_e32 v83, v87
	v_permlane16_swap_b32_e32 v88, v92
	v_permlane16_swap_b32_e32 v89, v93
	v_permlane16_swap_b32_e32 v90, v94
	v_permlane16_swap_b32_e32 v91, v95
	v_permlane16_swap_b32_e32 v48, v52
	v_permlane16_swap_b32_e32 v49, v53
	v_permlane16_swap_b32_e32 v50, v54
	v_permlane16_swap_b32_e32 v51, v55
	v_permlane16_swap_b32_e32 v56, v60
	v_permlane16_swap_b32_e32 v57, v61
	v_permlane16_swap_b32_e32 v58, v62
	v_permlane16_swap_b32_e32 v59, v63
	v_permlane32_swap_b32_e32 v80, v84
	v_permlane32_swap_b32_e32 v81, v85
	v_permlane32_swap_b32_e32 v82, v86
	v_permlane32_swap_b32_e32 v83, v87
	v_permlane32_swap_b32_e32 v88, v92
	v_permlane32_swap_b32_e32 v89, v93
	v_permlane32_swap_b32_e32 v90, v94
	v_permlane32_swap_b32_e32 v91, v95
	v_permlane32_swap_b32_e32 v48, v52
	v_permlane32_swap_b32_e32 v49, v53
	v_permlane32_swap_b32_e32 v50, v54
	v_permlane32_swap_b32_e32 v51, v55
	v_permlane32_swap_b32_e32 v56, v60
	v_permlane32_swap_b32_e32 v57, v61
	v_permlane32_swap_b32_e32 v58, v62
	v_permlane32_swap_b32_e32 v59, v63
	s_barrier
	s_nop 7
	v_permlane16_swap_b32_e32 v64, v68
	v_permlane16_swap_b32_e32 v65, v69
	v_permlane16_swap_b32_e32 v66, v70
	v_permlane16_swap_b32_e32 v67, v71
	v_permlane16_swap_b32_e32 v72, v76
	v_permlane16_swap_b32_e32 v73, v77
	v_permlane16_swap_b32_e32 v74, v78
	v_permlane16_swap_b32_e32 v75, v79
	v_permlane16_swap_b32_e32 v32, v36
	v_permlane16_swap_b32_e32 v33, v37
	v_permlane16_swap_b32_e32 v34, v38
	v_permlane16_swap_b32_e32 v35, v39
	v_permlane16_swap_b32_e32 v40, v44
	v_permlane16_swap_b32_e32 v41, v45
	v_permlane16_swap_b32_e32 v42, v46
	v_permlane16_swap_b32_e32 v43, v47
	v_permlane32_swap_b32_e32 v64, v68
	v_permlane32_swap_b32_e32 v65, v69
	v_permlane32_swap_b32_e32 v66, v70
	v_permlane32_swap_b32_e32 v67, v71
	v_permlane32_swap_b32_e32 v72, v76
	v_permlane32_swap_b32_e32 v73, v77
	v_permlane32_swap_b32_e32 v74, v78
	v_permlane32_swap_b32_e32 v75, v79
	v_permlane32_swap_b32_e32 v32, v36
	v_permlane32_swap_b32_e32 v33, v37
	v_permlane32_swap_b32_e32 v34, v38
	v_permlane32_swap_b32_e32 v35, v39
	v_permlane32_swap_b32_e32 v40, v44
	v_permlane32_swap_b32_e32 v41, v45
	v_permlane32_swap_b32_e32 v42, v46
	v_permlane32_swap_b32_e32 v43, v47
	s_waitcnt vmcnt(0)
	s_lshl_b32 s12, s2, 8
	s_cmp_eq_u32 s0, 23
	s_mov_b64 s[2:3], -1
	s_cbranch_scc1 .LBB0_347
	s_movk_i32 s1, 0x2400
	s_waitcnt vmcnt(6)
	v_and_b32_e32 v130, 0xffffffc0, v181
	s_cmp_gt_i32 s0, 10
	v_mul_lo_u32 v129, v233, s1
	v_and_b32_e32 v128, 56, v234
	v_add_u32_e32 v131, s12, v130
	s_cselect_b64 s[2:3], -1, 0
	s_cmp_gt_u32 s0, 19
	v_mul_u32_u24_e32 v130, 0x120, v183
	s_waitcnt vmcnt(0)
	v_lshl_or_b32 v132, v128, 1, v129
	v_lshl_or_b32 v128, s0, 7, v128
	s_cselect_b64 s[0:1], -1, 0
	v_lshl_add_u32 v129, v130, 1, v129
	v_lshl_or_b32 v130, v231, 1, v129
	v_cvt_pk_bf16_f32 v112, v112, s0
	ds_write_b16 v130, v112 offset:64
	v_cvt_pk_bf16_f32 v112, v17, s0
	v_cvt_pk_bf16_f32 v96, v96, s0
	ds_write_b16 v130, v112 offset:144
	v_cvt_pk_bf16_f32 v112, v113, s0
	ds_write_b16 v130, v96 offset:4672
	v_cvt_pk_bf16_f32 v96, v1, s0
	ds_write_b16 v130, v112 offset:208
	v_cvt_pk_bf16_f32 v112, v18, s0
	ds_write_b16 v130, v96 offset:4752
	v_cvt_pk_bf16_f32 v96, v97, s0
	ds_write_b16 v130, v112 offset:288
	v_cvt_pk_bf16_f32 v112, v114, s0
	ds_write_b16 v130, v96 offset:4816
	v_cvt_pk_bf16_f32 v96, v2, s0
	ds_write_b16 v130, v112 offset:352
	v_cvt_pk_bf16_f32 v112, v19, s0
	ds_write_b16 v130, v96 offset:4896
	v_cvt_pk_bf16_f32 v96, v98, s0
	ds_write_b16 v130, v112 offset:432
	v_cvt_pk_bf16_f32 v112, v115, s0
	ds_write_b16 v130, v96 offset:4960
	v_cvt_pk_bf16_f32 v96, v3, s0
	ds_write_b16 v130, v112 offset:496
	v_cvt_pk_bf16_f32 v112, v20, s0
	ds_write_b16 v130, v96 offset:5040
	v_cvt_pk_bf16_f32 v96, v99, s0
	ds_write_b16 v130, v112 offset:1152
	v_cvt_pk_bf16_f32 v112, v116, s0
	ds_write_b16 v130, v96 offset:5104
	v_cvt_pk_bf16_f32 v96, v4, s0
	ds_write_b16 v130, v112 offset:1216
	v_cvt_pk_bf16_f32 v112, v21, s0
	ds_write_b16 v130, v96 offset:5760
	v_cvt_pk_bf16_f32 v96, v100, s0
	ds_write_b16 v130, v112 offset:1296
	v_cvt_pk_bf16_f32 v112, v117, s0
	ds_write_b16 v130, v96 offset:5824
	v_cvt_pk_bf16_f32 v96, v5, s0
	ds_write_b16 v130, v112 offset:1360
	v_cvt_pk_bf16_f32 v112, v22, s0
	ds_write_b16 v130, v96 offset:5904
	v_cvt_pk_bf16_f32 v96, v101, s0
	ds_write_b16 v130, v112 offset:1440
	v_cvt_pk_bf16_f32 v112, v118, s0
	ds_write_b16 v130, v96 offset:5968
	v_cvt_pk_bf16_f32 v96, v6, s0
	ds_write_b16 v130, v112 offset:1504
	v_cvt_pk_bf16_f32 v112, v23, s0
	ds_write_b16 v130, v96 offset:6048
	v_cvt_pk_bf16_f32 v96, v102, s0
	ds_write_b16 v130, v112 offset:1584
	v_cvt_pk_bf16_f32 v112, v119, s0
	ds_write_b16 v130, v96 offset:6112
	v_cvt_pk_bf16_f32 v96, v7, s0
	ds_write_b16 v130, v112 offset:1648
	v_cvt_pk_bf16_f32 v112, v24, s0
	ds_write_b16 v130, v96 offset:6192
	v_cvt_pk_bf16_f32 v96, v103, s0
	ds_write_b16 v130, v112 offset:2304
	v_cvt_pk_bf16_f32 v112, v120, s0
	ds_write_b16 v130, v96 offset:6256
	v_cvt_pk_bf16_f32 v96, v8, s0
	ds_write_b16 v130, v112 offset:2368
	v_cvt_pk_bf16_f32 v112, v25, s0
	ds_write_b16 v130, v96 offset:6912
	v_cvt_pk_bf16_f32 v96, v104, s0
	ds_write_b16 v130, v112 offset:2448
	v_cvt_pk_bf16_f32 v112, v121, s0
	ds_write_b16 v130, v96 offset:6976
	v_cvt_pk_bf16_f32 v96, v9, s0
	ds_write_b16 v130, v112 offset:2512
	v_cvt_pk_bf16_f32 v112, v26, s0
	ds_write_b16 v130, v96 offset:7056
	v_cvt_pk_bf16_f32 v96, v105, s0
	ds_write_b16 v130, v112 offset:2592
	v_cvt_pk_bf16_f32 v112, v122, s0
	ds_write_b16 v130, v96 offset:7120
	v_cvt_pk_bf16_f32 v96, v10, s0
	ds_write_b16 v130, v112 offset:2656
	v_cvt_pk_bf16_f32 v112, v27, s0
	ds_write_b16 v130, v96 offset:7200
	v_cvt_pk_bf16_f32 v96, v106, s0
	ds_write_b16 v130, v112 offset:2736
	v_cvt_pk_bf16_f32 v112, v123, s0
	ds_write_b16 v130, v96 offset:7264
	v_cvt_pk_bf16_f32 v96, v11, s0
	ds_write_b16 v130, v112 offset:2800
	v_cvt_pk_bf16_f32 v112, v28, s0
	ds_write_b16 v130, v96 offset:7344
	v_cvt_pk_bf16_f32 v96, v107, s0
	ds_write_b16 v130, v112 offset:3456
	v_cvt_pk_bf16_f32 v112, v124, s0
	ds_write_b16 v130, v96 offset:7408
	v_cvt_pk_bf16_f32 v96, v12, s0
	ds_write_b16 v130, v112 offset:3520
	v_cvt_pk_bf16_f32 v112, v29, s0
	ds_write_b16 v130, v96 offset:8064
	v_cvt_pk_bf16_f32 v96, v108, s0
	ds_write_b16 v130, v112 offset:3600
	v_cvt_pk_bf16_f32 v112, v125, s0
	ds_write_b16 v130, v96 offset:8128
	v_cvt_pk_bf16_f32 v96, v13, s0
	ds_write_b16 v130, v112 offset:3664
	v_cvt_pk_bf16_f32 v112, v30, s0
	ds_write_b16 v130, v96 offset:8208
	v_cvt_pk_bf16_f32 v96, v109, s0
	ds_write_b16 v130, v112 offset:3744
	v_cvt_pk_bf16_f32 v112, v126, s0
	ds_write_b16 v130, v96 offset:8272
	v_cvt_pk_bf16_f32 v96, v14, s0
	ds_write_b16 v130, v112 offset:3808
	v_cvt_pk_bf16_f32 v112, v31, s0
	ds_write_b16 v130, v96 offset:8352
	v_cvt_pk_bf16_f32 v96, v110, s0
	ds_write_b16 v130, v112 offset:3888
	v_cvt_pk_bf16_f32 v112, v127, s0
	ds_write_b16 v130, v96 offset:8416
	v_cvt_pk_bf16_f32 v96, v15, s0
	v_cvt_pk_bf16_f32 v133, v16, s0
	ds_write_b16 v130, v112 offset:3952
	v_cvt_pk_bf16_f32 v112, v0, s0
	ds_write_b16 v130, v96 offset:8496
	v_cvt_pk_bf16_f32 v96, v111, s0
	ds_write_b16 v130, v133
	ds_write_b16 v130, v112 offset:4608
	ds_write_b16 v130, v96 offset:8560
	v_lshrrev_b32_e32 v109, 3, v232
	s_waitcnt lgkmcnt(0)
	v_mad_u32_u24 v96, v109, s42, v132
	ds_read_b128 v[96:99], v96
	v_mov_b32_e32 v176, v128
	v_or_b32_e32 v110, v131, v109
	s_mov_b64 s[4:5], -1
	s_and_b64 vcc, exec, s[2:3]
	s_cbranch_vccz .LBB0_224
	s_and_b64 vcc, exec, s[0:1]
	s_cbranch_vccz .LBB0_221
	v_readlane_b32 s16, v254, 15
	v_readlane_b32 s18, v254, 17
	v_readlane_b32 s19, v254, 18
	v_readlane_b32 s17, v254, 16
	v_readlane_b32 s20, v254, 19
	v_mov_b64_e32 v[100:101], s[18:19]
	v_mad_i64_i32 v[100:101], s[4:5], v110, s89, v[100:101]
	s_movk_i32 s4, 0xec00
	v_lshl_add_u64 v[100:101], v[176:177], 1, v[100:101]
	s_mov_b32 s5, -1
	v_readlane_b32 s21, v254, 20
	v_readlane_b32 s22, v254, 21
	v_readlane_b32 s23, v254, 22
	v_readlane_b32 s24, v254, 23
	v_readlane_b32 s25, v254, 24
	v_readlane_b32 s26, v254, 25
	v_readlane_b32 s27, v254, 26
	v_readlane_b32 s28, v254, 27
	v_readlane_b32 s29, v254, 28
	v_readlane_b32 s30, v254, 29
	v_readlane_b32 s31, v254, 30
	v_lshl_add_u64 v[100:101], v[100:101], 0, s[4:5]
	s_mov_b64 s[4:5], 0

.Lg16_out_k:
	s_add_i32 s9, s3, 2
	s_lshl_b32 s96, s9, 13
	s_add_i32 m0, vcc_lo, 16384
	v_lshl_add_u64 v[160:161], v[188:189], 0, s[96:97]
	global_load_lds_dwordx4 v[160:161], off
	global_load_lds_dwordx4 v[160:161], off offset:1024
	ds_read_b128 v[196:199], v246 offset:0
	ds_read_b128 v[200:203], v246 offset:1024
	ds_read_b128 v[204:207], v246 offset:2048
	ds_read_b128 v[242:245], v246 offset:3072
	s_add_i32 s9, s3, 2
	s_lshl_b32 s96, s9, 11
	v_lshl_add_u64 v[248:249], v[184:185], 0, s[96:97]
	v_lshl_add_u64 v[250:251], v[186:187], 0, s[96:97]
	s_waitcnt vmcnt(8) lgkmcnt(3)
	v_mfma_f32_16x16x32_bf16 v[112:115], v[128:131], v[196:199], v[112:115]
	v_mfma_f32_16x16x32_bf16 v[120:123], v[132:135], v[196:199], v[120:123]
	v_mfma_f32_16x16x32_bf16 v[48:51], v[136:139], v[196:199], v[48:51]
	v_mfma_f32_16x16x32_bf16 v[56:59], v[140:143], v[196:199], v[56:59]
	ds_read_b128 v[196:199], v246 offset:4096
	s_waitcnt lgkmcnt(3)
	v_mfma_f32_16x16x32_bf16 v[116:119], v[128:131], v[200:203], v[116:119]
	v_mfma_f32_16x16x32_bf16 v[124:127], v[132:135], v[200:203], v[124:127]
	v_mfma_f32_16x16x32_bf16 v[52:55], v[136:139], v[200:203], v[52:55]
	v_mfma_f32_16x16x32_bf16 v[60:63], v[140:143], v[200:203], v[60:63]
	ds_read_b128 v[200:203], v246 offset:5120
	s_waitcnt lgkmcnt(3)
	v_mfma_f32_16x16x32_bf16 v[96:99], v[128:131], v[204:207], v[96:99]
	v_mfma_f32_16x16x32_bf16 v[104:107], v[132:135], v[204:207], v[104:107]
	v_mfma_f32_16x16x32_bf16 v[32:35], v[136:139], v[204:207], v[32:35]
	v_mfma_f32_16x16x32_bf16 v[40:43], v[140:143], v[204:207], v[40:43]
	ds_read_b128 v[204:207], v246 offset:6144
	s_waitcnt lgkmcnt(3)
	v_mfma_f32_16x16x32_bf16 v[100:103], v[128:131], v[242:245], v[100:103]
	v_mfma_f32_16x16x32_bf16 v[108:111], v[132:135], v[242:245], v[108:111]
	v_mfma_f32_16x16x32_bf16 v[36:39], v[136:139], v[242:245], v[36:39]
	v_mfma_f32_16x16x32_bf16 v[44:47], v[140:143], v[242:245], v[44:47]
	ds_read_b128 v[242:245], v246 offset:7168
	s_waitcnt lgkmcnt(3)
	v_mfma_f32_16x16x32_bf16 v[80:83], v[128:131], v[196:199], v[80:83]
	v_mfma_f32_16x16x32_bf16 v[88:91], v[132:135], v[196:199], v[88:91]
	v_mfma_f32_16x16x32_bf16 v[16:19], v[136:139], v[196:199], v[16:19]
	v_mfma_f32_16x16x32_bf16 v[24:27], v[140:143], v[196:199], v[24:27]
	s_waitcnt lgkmcnt(2)
	v_mfma_f32_16x16x32_bf16 v[84:87], v[128:131], v[200:203], v[84:87]
	v_mfma_f32_16x16x32_bf16 v[92:95], v[132:135], v[200:203], v[92:95]
	v_mfma_f32_16x16x32_bf16 v[20:23], v[136:139], v[200:203], v[20:23]
	v_mfma_f32_16x16x32_bf16 v[28:31], v[140:143], v[200:203], v[28:31]
	s_waitcnt lgkmcnt(1)
	v_mfma_f32_16x16x32_bf16 v[64:67], v[128:131], v[204:207], v[64:67]
	v_mfma_f32_16x16x32_bf16 v[72:75], v[132:135], v[204:207], v[72:75]
	v_mfma_f32_16x16x32_bf16 v[0:3], v[136:139], v[204:207], v[0:3]
	v_mfma_f32_16x16x32_bf16 v[8:11], v[140:143], v[204:207], v[8:11]
	s_waitcnt lgkmcnt(0)
	v_mfma_f32_16x16x32_bf16 v[68:71], v[128:131], v[242:245], v[68:71]
	v_mfma_f32_16x16x32_bf16 v[76:79], v[132:135], v[242:245], v[76:79]
	v_mfma_f32_16x16x32_bf16 v[4:7], v[136:139], v[242:245], v[4:7]
	v_mfma_f32_16x16x32_bf16 v[12:15], v[140:143], v[242:245], v[12:15]
	global_load_dwordx4 v[128:131], v[248:249], off
	global_load_dwordx4 v[132:135], v[248:249], off offset:256
	global_load_dwordx4 v[136:139], v[250:251], off
	global_load_dwordx4 v[140:143], v[250:251], off offset:256
	s_waitcnt vmcnt(10)
	s_barrier
	s_add_i32 s9, s3, 3
	s_lshl_b32 s96, s9, 13
	s_mov_b32 m0, vcc_lo
	v_lshl_add_u64 v[160:161], v[188:189], 0, s[96:97]
	global_load_lds_dwordx4 v[160:161], off
	global_load_lds_dwordx4 v[160:161], off offset:1024
	ds_read_b128 v[196:199], v246 offset:8192
	ds_read_b128 v[200:203], v246 offset:9216
	ds_read_b128 v[204:207], v246 offset:10240
	ds_read_b128 v[242:245], v246 offset:11264
	s_add_i32 s9, s3, 3
	s_lshl_b32 s96, s9, 11
	v_lshl_add_u64 v[248:249], v[184:185], 0, s[96:97]
	v_lshl_add_u64 v[250:251], v[186:187], 0, s[96:97]
	s_waitcnt vmcnt(8) lgkmcnt(3)
	v_mfma_f32_16x16x32_bf16 v[112:115], v[144:147], v[196:199], v[112:115]
	v_mfma_f32_16x16x32_bf16 v[120:123], v[148:151], v[196:199], v[120:123]
	v_mfma_f32_16x16x32_bf16 v[48:51], v[152:155], v[196:199], v[48:51]
	v_mfma_f32_16x16x32_bf16 v[56:59], v[156:159], v[196:199], v[56:59]
	ds_read_b128 v[196:199], v246 offset:12288
	s_waitcnt lgkmcnt(3)
	v_mfma_f32_16x16x32_bf16 v[116:119], v[144:147], v[200:203], v[116:119]
	v_mfma_f32_16x16x32_bf16 v[124:127], v[148:151], v[200:203], v[124:127]
	v_mfma_f32_16x16x32_bf16 v[52:55], v[152:155], v[200:203], v[52:55]
	v_mfma_f32_16x16x32_bf16 v[60:63], v[156:159], v[200:203], v[60:63]
	ds_read_b128 v[200:203], v246 offset:13312
	s_waitcnt lgkmcnt(3)
	v_mfma_f32_16x16x32_bf16 v[96:99], v[144:147], v[204:207], v[96:99]
	v_mfma_f32_16x16x32_bf16 v[104:107], v[148:151], v[204:207], v[104:107]
	v_mfma_f32_16x16x32_bf16 v[32:35], v[152:155], v[204:207], v[32:35]
	v_mfma_f32_16x16x32_bf16 v[40:43], v[156:159], v[204:207], v[40:43]
	ds_read_b128 v[204:207], v246 offset:14336
	s_waitcnt lgkmcnt(3)
	v_mfma_f32_16x16x32_bf16 v[100:103], v[144:147], v[242:245], v[100:103]
	v_mfma_f32_16x16x32_bf16 v[108:111], v[148:151], v[242:245], v[108:111]
	v_mfma_f32_16x16x32_bf16 v[36:39], v[152:155], v[242:245], v[36:39]
	v_mfma_f32_16x16x32_bf16 v[44:47], v[156:159], v[242:245], v[44:47]
	ds_read_b128 v[242:245], v246 offset:15360
	s_waitcnt lgkmcnt(3)
	v_mfma_f32_16x16x32_bf16 v[80:83], v[144:147], v[196:199], v[80:83]
	v_mfma_f32_16x16x32_bf16 v[88:91], v[148:151], v[196:199], v[88:91]
	v_mfma_f32_16x16x32_bf16 v[16:19], v[152:155], v[196:199], v[16:19]
	v_mfma_f32_16x16x32_bf16 v[24:27], v[156:159], v[196:199], v[24:27]
	s_waitcnt lgkmcnt(2)
	v_mfma_f32_16x16x32_bf16 v[84:87], v[144:147], v[200:203], v[84:87]
	v_mfma_f32_16x16x32_bf16 v[92:95], v[148:151], v[200:203], v[92:95]
	v_mfma_f32_16x16x32_bf16 v[20:23], v[152:155], v[200:203], v[20:23]
	v_mfma_f32_16x16x32_bf16 v[28:31], v[156:159], v[200:203], v[28:31]
	s_waitcnt lgkmcnt(1)
	v_mfma_f32_16x16x32_bf16 v[64:67], v[144:147], v[204:207], v[64:67]
	v_mfma_f32_16x16x32_bf16 v[72:75], v[148:151], v[204:207], v[72:75]
	v_mfma_f32_16x16x32_bf16 v[0:3], v[152:155], v[204:207], v[0:3]
	v_mfma_f32_16x16x32_bf16 v[8:11], v[156:159], v[204:207], v[8:11]
	s_waitcnt lgkmcnt(0)
	v_mfma_f32_16x16x32_bf16 v[68:71], v[144:147], v[242:245], v[68:71]
	v_mfma_f32_16x16x32_bf16 v[76:79], v[148:151], v[242:245], v[76:79]
	v_mfma_f32_16x16x32_bf16 v[4:7], v[152:155], v[242:245], v[4:7]
	v_mfma_f32_16x16x32_bf16 v[12:15], v[156:159], v[242:245], v[12:15]
	global_load_dwordx4 v[144:147], v[248:249], off
	global_load_dwordx4 v[148:151], v[248:249], off offset:256
	global_load_dwordx4 v[152:155], v[250:251], off
	global_load_dwordx4 v[156:159], v[250:251], off offset:256
	s_waitcnt vmcnt(10)
	s_barrier
	s_add_i32 s9, s3, 4
	s_lshl_b32 s96, s9, 13
	s_add_i32 m0, vcc_lo, 8192
	v_lshl_add_u64 v[160:161], v[188:189], 0, s[96:97]
	global_load_lds_dwordx4 v[160:161], off
	global_load_lds_dwordx4 v[160:161], off offset:1024
	ds_read_b128 v[196:199], v246 offset:16384
	ds_read_b128 v[200:203], v246 offset:17408
	ds_read_b128 v[204:207], v246 offset:18432
	ds_read_b128 v[242:245], v246 offset:19456
	s_add_i32 s9, s3, 4
	s_lshl_b32 s96, s9, 11
	v_lshl_add_u64 v[248:249], v[184:185], 0, s[96:97]
	v_lshl_add_u64 v[250:251], v[186:187], 0, s[96:97]
	s_waitcnt vmcnt(8) lgkmcnt(3)
	v_mfma_f32_16x16x32_bf16 v[112:115], v[128:131], v[196:199], v[112:115]
	v_mfma_f32_16x16x32_bf16 v[120:123], v[132:135], v[196:199], v[120:123]
	v_mfma_f32_16x16x32_bf16 v[48:51], v[136:139], v[196:199], v[48:51]
	v_mfma_f32_16x16x32_bf16 v[56:59], v[140:143], v[196:199], v[56:59]
	ds_read_b128 v[196:199], v246 offset:20480
	s_waitcnt lgkmcnt(3)
	v_mfma_f32_16x16x32_bf16 v[116:119], v[128:131], v[200:203], v[116:119]
	v_mfma_f32_16x16x32_bf16 v[124:127], v[132:135], v[200:203], v[124:127]
	v_mfma_f32_16x16x32_bf16 v[52:55], v[136:139], v[200:203], v[52:55]
	v_mfma_f32_16x16x32_bf16 v[60:63], v[140:143], v[200:203], v[60:63]
	ds_read_b128 v[200:203], v246 offset:21504
	s_waitcnt lgkmcnt(3)
	v_mfma_f32_16x16x32_bf16 v[96:99], v[128:131], v[204:207], v[96:99]
	v_mfma_f32_16x16x32_bf16 v[104:107], v[132:135], v[204:207], v[104:107]
	v_mfma_f32_16x16x32_bf16 v[32:35], v[136:139], v[204:207], v[32:35]
	v_mfma_f32_16x16x32_bf16 v[40:43], v[140:143], v[204:207], v[40:43]
	ds_read_b128 v[204:207], v246 offset:22528
	s_waitcnt lgkmcnt(3)
	v_mfma_f32_16x16x32_bf16 v[100:103], v[128:131], v[242:245], v[100:103]
	v_mfma_f32_16x16x32_bf16 v[108:111], v[132:135], v[242:245], v[108:111]
	v_mfma_f32_16x16x32_bf16 v[36:39], v[136:139], v[242:245], v[36:39]
	v_mfma_f32_16x16x32_bf16 v[44:47], v[140:143], v[242:245], v[44:47]
	ds_read_b128 v[242:245], v246 offset:23552
	s_waitcnt lgkmcnt(3)
	v_mfma_f32_16x16x32_bf16 v[80:83], v[128:131], v[196:199], v[80:83]
	v_mfma_f32_16x16x32_bf16 v[88:91], v[132:135], v[196:199], v[88:91]
	v_mfma_f32_16x16x32_bf16 v[16:19], v[136:139], v[196:199], v[16:19]
	v_mfma_f32_16x16x32_bf16 v[24:27], v[140:143], v[196:199], v[24:27]
	s_waitcnt lgkmcnt(2)
	v_mfma_f32_16x16x32_bf16 v[84:87], v[128:131], v[200:203], v[84:87]
	v_mfma_f32_16x16x32_bf16 v[92:95], v[132:135], v[200:203], v[92:95]
	v_mfma_f32_16x16x32_bf16 v[20:23], v[136:139], v[200:203], v[20:23]
	v_mfma_f32_16x16x32_bf16 v[28:31], v[140:143], v[200:203], v[28:31]
	s_waitcnt lgkmcnt(1)
	v_mfma_f32_16x16x32_bf16 v[64:67], v[128:131], v[204:207], v[64:67]
	v_mfma_f32_16x16x32_bf16 v[72:75], v[132:135], v[204:207], v[72:75]
	v_mfma_f32_16x16x32_bf16 v[0:3], v[136:139], v[204:207], v[0:3]
	v_mfma_f32_16x16x32_bf16 v[8:11], v[140:143], v[204:207], v[8:11]
	s_waitcnt lgkmcnt(0)
	v_mfma_f32_16x16x32_bf16 v[68:71], v[128:131], v[242:245], v[68:71]
	v_mfma_f32_16x16x32_bf16 v[76:79], v[132:135], v[242:245], v[76:79]
	v_mfma_f32_16x16x32_bf16 v[4:7], v[136:139], v[242:245], v[4:7]
	v_mfma_f32_16x16x32_bf16 v[12:15], v[140:143], v[242:245], v[12:15]
	global_load_dwordx4 v[128:131], v[248:249], off
	global_load_dwordx4 v[132:135], v[248:249], off offset:256
	global_load_dwordx4 v[136:139], v[250:251], off
	global_load_dwordx4 v[140:143], v[250:251], off offset:256
	s_waitcnt vmcnt(10)
	s_barrier
	s_add_i32 s9, s3, 5
	s_lshl_b32 s96, s9, 13
	s_add_i32 m0, vcc_lo, 16384
	v_lshl_add_u64 v[160:161], v[188:189], 0, s[96:97]
	global_load_lds_dwordx4 v[160:161], off
	global_load_lds_dwordx4 v[160:161], off offset:1024
	ds_read_b128 v[196:199], v246 offset:0
	ds_read_b128 v[200:203], v246 offset:1024
	ds_read_b128 v[204:207], v246 offset:2048
	ds_read_b128 v[242:245], v246 offset:3072
	s_add_i32 s9, s3, 5
	s_lshl_b32 s96, s9, 11
	v_lshl_add_u64 v[248:249], v[184:185], 0, s[96:97]
	v_lshl_add_u64 v[250:251], v[186:187], 0, s[96:97]
	s_waitcnt vmcnt(8) lgkmcnt(3)
	v_mfma_f32_16x16x32_bf16 v[112:115], v[144:147], v[196:199], v[112:115]
	v_mfma_f32_16x16x32_bf16 v[120:123], v[148:151], v[196:199], v[120:123]
	v_mfma_f32_16x16x32_bf16 v[48:51], v[152:155], v[196:199], v[48:51]
	v_mfma_f32_16x16x32_bf16 v[56:59], v[156:159], v[196:199], v[56:59]
	ds_read_b128 v[196:199], v246 offset:4096
	s_waitcnt lgkmcnt(3)
	v_mfma_f32_16x16x32_bf16 v[116:119], v[144:147], v[200:203], v[116:119]
	v_mfma_f32_16x16x32_bf16 v[124:127], v[148:151], v[200:203], v[124:127]
	v_mfma_f32_16x16x32_bf16 v[52:55], v[152:155], v[200:203], v[52:55]
	v_mfma_f32_16x16x32_bf16 v[60:63], v[156:159], v[200:203], v[60:63]
	ds_read_b128 v[200:203], v246 offset:5120
	s_waitcnt lgkmcnt(3)
	v_mfma_f32_16x16x32_bf16 v[96:99], v[144:147], v[204:207], v[96:99]
	v_mfma_f32_16x16x32_bf16 v[104:107], v[148:151], v[204:207], v[104:107]
	v_mfma_f32_16x16x32_bf16 v[32:35], v[152:155], v[204:207], v[32:35]
	v_mfma_f32_16x16x32_bf16 v[40:43], v[156:159], v[204:207], v[40:43]
	ds_read_b128 v[204:207], v246 offset:6144
	s_waitcnt lgkmcnt(3)
	v_mfma_f32_16x16x32_bf16 v[100:103], v[144:147], v[242:245], v[100:103]
	v_mfma_f32_16x16x32_bf16 v[108:111], v[148:151], v[242:245], v[108:111]
	v_mfma_f32_16x16x32_bf16 v[36:39], v[152:155], v[242:245], v[36:39]
	v_mfma_f32_16x16x32_bf16 v[44:47], v[156:159], v[242:245], v[44:47]
	ds_read_b128 v[242:245], v246 offset:7168
	s_waitcnt lgkmcnt(3)
	v_mfma_f32_16x16x32_bf16 v[80:83], v[144:147], v[196:199], v[80:83]
	v_mfma_f32_16x16x32_bf16 v[88:91], v[148:151], v[196:199], v[88:91]
	v_mfma_f32_16x16x32_bf16 v[16:19], v[152:155], v[196:199], v[16:19]
	v_mfma_f32_16x16x32_bf16 v[24:27], v[156:159], v[196:199], v[24:27]
	s_waitcnt lgkmcnt(2)
	v_mfma_f32_16x16x32_bf16 v[84:87], v[144:147], v[200:203], v[84:87]
	v_mfma_f32_16x16x32_bf16 v[92:95], v[148:151], v[200:203], v[92:95]
	v_mfma_f32_16x16x32_bf16 v[20:23], v[152:155], v[200:203], v[20:23]
	v_mfma_f32_16x16x32_bf16 v[28:31], v[156:159], v[200:203], v[28:31]
	s_waitcnt lgkmcnt(1)
	v_mfma_f32_16x16x32_bf16 v[64:67], v[144:147], v[204:207], v[64:67]
	v_mfma_f32_16x16x32_bf16 v[72:75], v[148:151], v[204:207], v[72:75]
	v_mfma_f32_16x16x32_bf16 v[0:3], v[152:155], v[204:207], v[0:3]
	v_mfma_f32_16x16x32_bf16 v[8:11], v[156:159], v[204:207], v[8:11]
	s_waitcnt lgkmcnt(0)
	v_mfma_f32_16x16x32_bf16 v[68:71], v[144:147], v[242:245], v[68:71]
	v_mfma_f32_16x16x32_bf16 v[76:79], v[148:151], v[242:245], v[76:79]
	v_mfma_f32_16x16x32_bf16 v[4:7], v[152:155], v[242:245], v[4:7]
	v_mfma_f32_16x16x32_bf16 v[12:15], v[156:159], v[242:245], v[12:15]
	global_load_dwordx4 v[144:147], v[248:249], off
	global_load_dwordx4 v[148:151], v[248:249], off offset:256
	global_load_dwordx4 v[152:155], v[250:251], off
	global_load_dwordx4 v[156:159], v[250:251], off offset:256
	s_waitcnt vmcnt(10)
	s_barrier
	s_add_i32 s9, s3, 6
	s_lshl_b32 s96, s9, 13
	s_mov_b32 m0, vcc_lo
	v_lshl_add_u64 v[160:161], v[188:189], 0, s[96:97]
	global_load_lds_dwordx4 v[160:161], off
	global_load_lds_dwordx4 v[160:161], off offset:1024
	ds_read_b128 v[196:199], v246 offset:8192
	ds_read_b128 v[200:203], v246 offset:9216
	ds_read_b128 v[204:207], v246 offset:10240
	ds_read_b128 v[242:245], v246 offset:11264
	s_add_i32 s9, s3, 6
	s_lshl_b32 s96, s9, 11
	v_lshl_add_u64 v[248:249], v[184:185], 0, s[96:97]
	v_lshl_add_u64 v[250:251], v[186:187], 0, s[96:97]
	s_waitcnt vmcnt(8) lgkmcnt(3)
	v_mfma_f32_16x16x32_bf16 v[112:115], v[128:131], v[196:199], v[112:115]
	v_mfma_f32_16x16x32_bf16 v[120:123], v[132:135], v[196:199], v[120:123]
	v_mfma_f32_16x16x32_bf16 v[48:51], v[136:139], v[196:199], v[48:51]
	v_mfma_f32_16x16x32_bf16 v[56:59], v[140:143], v[196:199], v[56:59]
	ds_read_b128 v[196:199], v246 offset:12288
	s_waitcnt lgkmcnt(3)
	v_mfma_f32_16x16x32_bf16 v[116:119], v[128:131], v[200:203], v[116:119]
	v_mfma_f32_16x16x32_bf16 v[124:127], v[132:135], v[200:203], v[124:127]
	v_mfma_f32_16x16x32_bf16 v[52:55], v[136:139], v[200:203], v[52:55]
	v_mfma_f32_16x16x32_bf16 v[60:63], v[140:143], v[200:203], v[60:63]
	ds_read_b128 v[200:203], v246 offset:13312
	s_waitcnt lgkmcnt(3)
	v_mfma_f32_16x16x32_bf16 v[96:99], v[128:131], v[204:207], v[96:99]
	v_mfma_f32_16x16x32_bf16 v[104:107], v[132:135], v[204:207], v[104:107]
	v_mfma_f32_16x16x32_bf16 v[32:35], v[136:139], v[204:207], v[32:35]
	v_mfma_f32_16x16x32_bf16 v[40:43], v[140:143], v[204:207], v[40:43]
	ds_read_b128 v[204:207], v246 offset:14336
	s_waitcnt lgkmcnt(3)
	v_mfma_f32_16x16x32_bf16 v[100:103], v[128:131], v[242:245], v[100:103]
	v_mfma_f32_16x16x32_bf16 v[108:111], v[132:135], v[242:245], v[108:111]
	v_mfma_f32_16x16x32_bf16 v[36:39], v[136:139], v[242:245], v[36:39]
	v_mfma_f32_16x16x32_bf16 v[44:47], v[140:143], v[242:245], v[44:47]
	ds_read_b128 v[242:245], v246 offset:15360
	s_waitcnt lgkmcnt(3)
	v_mfma_f32_16x16x32_bf16 v[80:83], v[128:131], v[196:199], v[80:83]
	v_mfma_f32_16x16x32_bf16 v[88:91], v[132:135], v[196:199], v[88:91]
	v_mfma_f32_16x16x32_bf16 v[16:19], v[136:139], v[196:199], v[16:19]
	v_mfma_f32_16x16x32_bf16 v[24:27], v[140:143], v[196:199], v[24:27]
	s_waitcnt lgkmcnt(2)
	v_mfma_f32_16x16x32_bf16 v[84:87], v[128:131], v[200:203], v[84:87]
	v_mfma_f32_16x16x32_bf16 v[92:95], v[132:135], v[200:203], v[92:95]
	v_mfma_f32_16x16x32_bf16 v[20:23], v[136:139], v[200:203], v[20:23]
	v_mfma_f32_16x16x32_bf16 v[28:31], v[140:143], v[200:203], v[28:31]
	s_waitcnt lgkmcnt(1)
	v_mfma_f32_16x16x32_bf16 v[64:67], v[128:131], v[204:207], v[64:67]
	v_mfma_f32_16x16x32_bf16 v[72:75], v[132:135], v[204:207], v[72:75]
	v_mfma_f32_16x16x32_bf16 v[0:3], v[136:139], v[204:207], v[0:3]
	v_mfma_f32_16x16x32_bf16 v[8:11], v[140:143], v[204:207], v[8:11]
	s_waitcnt lgkmcnt(0)
	v_mfma_f32_16x16x32_bf16 v[68:71], v[128:131], v[242:245], v[68:71]
	v_mfma_f32_16x16x32_bf16 v[76:79], v[132:135], v[242:245], v[76:79]
	v_mfma_f32_16x16x32_bf16 v[4:7], v[136:139], v[242:245], v[4:7]
	v_mfma_f32_16x16x32_bf16 v[12:15], v[140:143], v[242:245], v[12:15]
	global_load_dwordx4 v[128:131], v[248:249], off
	global_load_dwordx4 v[132:135], v[248:249], off offset:256
	global_load_dwordx4 v[136:139], v[250:251], off
	global_load_dwordx4 v[140:143], v[250:251], off offset:256
	s_waitcnt vmcnt(10)
	s_barrier
	s_add_i32 s9, s3, 7
	s_lshl_b32 s96, s9, 13
	s_add_i32 m0, vcc_lo, 8192
	v_lshl_add_u64 v[160:161], v[188:189], 0, s[96:97]
	global_load_lds_dwordx4 v[160:161], off
	global_load_lds_dwordx4 v[160:161], off offset:1024
	ds_read_b128 v[196:199], v246 offset:16384
	ds_read_b128 v[200:203], v246 offset:17408
	ds_read_b128 v[204:207], v246 offset:18432
	ds_read_b128 v[242:245], v246 offset:19456
	s_add_i32 s9, s3, 7
	s_lshl_b32 s96, s9, 11
	v_lshl_add_u64 v[248:249], v[184:185], 0, s[96:97]
	v_lshl_add_u64 v[250:251], v[186:187], 0, s[96:97]
	s_waitcnt vmcnt(8) lgkmcnt(3)
	v_mfma_f32_16x16x32_bf16 v[112:115], v[144:147], v[196:199], v[112:115]
	v_mfma_f32_16x16x32_bf16 v[120:123], v[148:151], v[196:199], v[120:123]
	v_mfma_f32_16x16x32_bf16 v[48:51], v[152:155], v[196:199], v[48:51]
	v_mfma_f32_16x16x32_bf16 v[56:59], v[156:159], v[196:199], v[56:59]
	ds_read_b128 v[196:199], v246 offset:20480
	s_waitcnt lgkmcnt(3)
	v_mfma_f32_16x16x32_bf16 v[116:119], v[144:147], v[200:203], v[116:119]
	v_mfma_f32_16x16x32_bf16 v[124:127], v[148:151], v[200:203], v[124:127]
	v_mfma_f32_16x16x32_bf16 v[52:55], v[152:155], v[200:203], v[52:55]
	v_mfma_f32_16x16x32_bf16 v[60:63], v[156:159], v[200:203], v[60:63]
	ds_read_b128 v[200:203], v246 offset:21504
	s_waitcnt lgkmcnt(3)
	v_mfma_f32_16x16x32_bf16 v[96:99], v[144:147], v[204:207], v[96:99]
	v_mfma_f32_16x16x32_bf16 v[104:107], v[148:151], v[204:207], v[104:107]
	v_mfma_f32_16x16x32_bf16 v[32:35], v[152:155], v[204:207], v[32:35]
	v_mfma_f32_16x16x32_bf16 v[40:43], v[156:159], v[204:207], v[40:43]
	ds_read_b128 v[204:207], v246 offset:22528
	s_waitcnt lgkmcnt(3)
	v_mfma_f32_16x16x32_bf16 v[100:103], v[144:147], v[242:245], v[100:103]
	v_mfma_f32_16x16x32_bf16 v[108:111], v[148:151], v[242:245], v[108:111]
	v_mfma_f32_16x16x32_bf16 v[36:39], v[152:155], v[242:245], v[36:39]
	v_mfma_f32_16x16x32_bf16 v[44:47], v[156:159], v[242:245], v[44:47]
	ds_read_b128 v[242:245], v246 offset:23552
	s_waitcnt lgkmcnt(3)
	v_mfma_f32_16x16x32_bf16 v[80:83], v[144:147], v[196:199], v[80:83]
	v_mfma_f32_16x16x32_bf16 v[88:91], v[148:151], v[196:199], v[88:91]
	v_mfma_f32_16x16x32_bf16 v[16:19], v[152:155], v[196:199], v[16:19]
	v_mfma_f32_16x16x32_bf16 v[24:27], v[156:159], v[196:199], v[24:27]
	s_waitcnt lgkmcnt(2)
	v_mfma_f32_16x16x32_bf16 v[84:87], v[144:147], v[200:203], v[84:87]
	v_mfma_f32_16x16x32_bf16 v[92:95], v[148:151], v[200:203], v[92:95]
	v_mfma_f32_16x16x32_bf16 v[20:23], v[152:155], v[200:203], v[20:23]
	v_mfma_f32_16x16x32_bf16 v[28:31], v[156:159], v[200:203], v[28:31]
	s_waitcnt lgkmcnt(1)
	v_mfma_f32_16x16x32_bf16 v[64:67], v[144:147], v[204:207], v[64:67]
	v_mfma_f32_16x16x32_bf16 v[72:75], v[148:151], v[204:207], v[72:75]
	v_mfma_f32_16x16x32_bf16 v[0:3], v[152:155], v[204:207], v[0:3]
	v_mfma_f32_16x16x32_bf16 v[8:11], v[156:159], v[204:207], v[8:11]
	s_waitcnt lgkmcnt(0)
	v_mfma_f32_16x16x32_bf16 v[68:71], v[144:147], v[242:245], v[68:71]
	v_mfma_f32_16x16x32_bf16 v[76:79], v[148:151], v[242:245], v[76:79]
	v_mfma_f32_16x16x32_bf16 v[4:7], v[152:155], v[242:245], v[4:7]
	v_mfma_f32_16x16x32_bf16 v[12:15], v[156:159], v[242:245], v[12:15]
	global_load_dwordx4 v[144:147], v[248:249], off
	global_load_dwordx4 v[148:151], v[248:249], off offset:256
	global_load_dwordx4 v[152:155], v[250:251], off
	global_load_dwordx4 v[156:159], v[250:251], off offset:256
	s_waitcnt vmcnt(10)
	s_barrier
	s_add_i32 s3, s3, 6
	s_cmp_lt_u32 s3, 30
	s_cbranch_scc1 .Lg16_out_k
	ds_read_b128 v[196:199], v246 offset:0
	ds_read_b128 v[200:203], v246 offset:1024
	ds_read_b128 v[204:207], v246 offset:2048
	ds_read_b128 v[242:245], v246 offset:3072
	s_waitcnt vmcnt(6) lgkmcnt(3)
	v_mfma_f32_16x16x32_bf16 v[112:115], v[128:131], v[196:199], v[112:115]
	v_mfma_f32_16x16x32_bf16 v[120:123], v[132:135], v[196:199], v[120:123]
	v_mfma_f32_16x16x32_bf16 v[48:51], v[136:139], v[196:199], v[48:51]
	v_mfma_f32_16x16x32_bf16 v[56:59], v[140:143], v[196:199], v[56:59]
	ds_read_b128 v[196:199], v246 offset:4096
	s_waitcnt lgkmcnt(3)
	v_mfma_f32_16x16x32_bf16 v[116:119], v[128:131], v[200:203], v[116:119]
	v_mfma_f32_16x16x32_bf16 v[124:127], v[132:135], v[200:203], v[124:127]
	v_mfma_f32_16x16x32_bf16 v[52:55], v[136:139], v[200:203], v[52:55]
	v_mfma_f32_16x16x32_bf16 v[60:63], v[140:143], v[200:203], v[60:63]
	ds_read_b128 v[200:203], v246 offset:5120
	s_waitcnt lgkmcnt(3)
	v_mfma_f32_16x16x32_bf16 v[96:99], v[128:131], v[204:207], v[96:99]
	v_mfma_f32_16x16x32_bf16 v[104:107], v[132:135], v[204:207], v[104:107]
	v_mfma_f32_16x16x32_bf16 v[32:35], v[136:139], v[204:207], v[32:35]
	v_mfma_f32_16x16x32_bf16 v[40:43], v[140:143], v[204:207], v[40:43]
	ds_read_b128 v[204:207], v246 offset:6144
	s_waitcnt lgkmcnt(3)
	v_mfma_f32_16x16x32_bf16 v[100:103], v[128:131], v[242:245], v[100:103]
	v_mfma_f32_16x16x32_bf16 v[108:111], v[132:135], v[242:245], v[108:111]
	v_mfma_f32_16x16x32_bf16 v[36:39], v[136:139], v[242:245], v[36:39]
	v_mfma_f32_16x16x32_bf16 v[44:47], v[140:143], v[242:245], v[44:47]
	ds_read_b128 v[242:245], v246 offset:7168
	s_waitcnt lgkmcnt(3)
	v_mfma_f32_16x16x32_bf16 v[80:83], v[128:131], v[196:199], v[80:83]
	v_mfma_f32_16x16x32_bf16 v[88:91], v[132:135], v[196:199], v[88:91]
	v_mfma_f32_16x16x32_bf16 v[16:19], v[136:139], v[196:199], v[16:19]
	v_mfma_f32_16x16x32_bf16 v[24:27], v[140:143], v[196:199], v[24:27]
	s_waitcnt lgkmcnt(2)
	v_mfma_f32_16x16x32_bf16 v[84:87], v[128:131], v[200:203], v[84:87]
	v_mfma_f32_16x16x32_bf16 v[92:95], v[132:135], v[200:203], v[92:95]
	v_mfma_f32_16x16x32_bf16 v[20:23], v[136:139], v[200:203], v[20:23]
	v_mfma_f32_16x16x32_bf16 v[28:31], v[140:143], v[200:203], v[28:31]
	s_waitcnt lgkmcnt(1)
	v_mfma_f32_16x16x32_bf16 v[64:67], v[128:131], v[204:207], v[64:67]
	v_mfma_f32_16x16x32_bf16 v[72:75], v[132:135], v[204:207], v[72:75]
	v_mfma_f32_16x16x32_bf16 v[0:3], v[136:139], v[204:207], v[0:3]
	v_mfma_f32_16x16x32_bf16 v[8:11], v[140:143], v[204:207], v[8:11]
	s_waitcnt lgkmcnt(0)
	v_mfma_f32_16x16x32_bf16 v[68:71], v[128:131], v[242:245], v[68:71]
	v_mfma_f32_16x16x32_bf16 v[76:79], v[132:135], v[242:245], v[76:79]
	v_mfma_f32_16x16x32_bf16 v[4:7], v[136:139], v[242:245], v[4:7]
	v_mfma_f32_16x16x32_bf16 v[12:15], v[140:143], v[242:245], v[12:15]
	s_waitcnt vmcnt(4)
	s_barrier
	ds_read_b128 v[196:199], v246 offset:8192
	ds_read_b128 v[200:203], v246 offset:9216
	ds_read_b128 v[204:207], v246 offset:10240
	ds_read_b128 v[242:245], v246 offset:11264
	s_waitcnt vmcnt(0) lgkmcnt(3)
	v_mfma_f32_16x16x32_bf16 v[112:115], v[144:147], v[196:199], v[112:115]
	v_mfma_f32_16x16x32_bf16 v[120:123], v[148:151], v[196:199], v[120:123]
	v_mfma_f32_16x16x32_bf16 v[48:51], v[152:155], v[196:199], v[48:51]
	v_mfma_f32_16x16x32_bf16 v[56:59], v[156:159], v[196:199], v[56:59]
	ds_read_b128 v[196:199], v246 offset:12288
	s_waitcnt lgkmcnt(3)
	v_mfma_f32_16x16x32_bf16 v[116:119], v[144:147], v[200:203], v[116:119]
	v_mfma_f32_16x16x32_bf16 v[124:127], v[148:151], v[200:203], v[124:127]
	v_mfma_f32_16x16x32_bf16 v[52:55], v[152:155], v[200:203], v[52:55]
	v_mfma_f32_16x16x32_bf16 v[60:63], v[156:159], v[200:203], v[60:63]
	ds_read_b128 v[200:203], v246 offset:13312
	s_waitcnt lgkmcnt(3)
	v_mfma_f32_16x16x32_bf16 v[96:99], v[144:147], v[204:207], v[96:99]
	v_mfma_f32_16x16x32_bf16 v[104:107], v[148:151], v[204:207], v[104:107]
	v_mfma_f32_16x16x32_bf16 v[32:35], v[152:155], v[204:207], v[32:35]
	v_mfma_f32_16x16x32_bf16 v[40:43], v[156:159], v[204:207], v[40:43]
	ds_read_b128 v[204:207], v246 offset:14336
	s_waitcnt lgkmcnt(3)
	v_mfma_f32_16x16x32_bf16 v[100:103], v[144:147], v[242:245], v[100:103]
	v_mfma_f32_16x16x32_bf16 v[108:111], v[148:151], v[242:245], v[108:111]
	v_mfma_f32_16x16x32_bf16 v[36:39], v[152:155], v[242:245], v[36:39]
	v_mfma_f32_16x16x32_bf16 v[44:47], v[156:159], v[242:245], v[44:47]
	ds_read_b128 v[242:245], v246 offset:15360
	v_permlane16_swap_b32_e32 v112, v116
	v_permlane16_swap_b32_e32 v113, v117
	v_permlane16_swap_b32_e32 v114, v118
	v_permlane16_swap_b32_e32 v115, v119
	v_permlane16_swap_b32_e32 v120, v124
	v_permlane16_swap_b32_e32 v121, v125
	v_permlane16_swap_b32_e32 v122, v126
	v_permlane16_swap_b32_e32 v123, v127
	v_permlane16_swap_b32_e32 v48, v52
	v_permlane16_swap_b32_e32 v49, v53
	v_permlane16_swap_b32_e32 v50, v54
	v_permlane16_swap_b32_e32 v51, v55
	v_permlane16_swap_b32_e32 v56, v60
	v_permlane16_swap_b32_e32 v57, v61
	v_permlane16_swap_b32_e32 v58, v62
	v_permlane16_swap_b32_e32 v59, v63
	v_permlane32_swap_b32_e32 v112, v116
	v_permlane32_swap_b32_e32 v113, v117
	v_permlane32_swap_b32_e32 v114, v118
	v_permlane32_swap_b32_e32 v115, v119
	v_permlane32_swap_b32_e32 v120, v124
	v_permlane32_swap_b32_e32 v121, v125
	v_permlane32_swap_b32_e32 v122, v126
	v_permlane32_swap_b32_e32 v123, v127
	v_permlane32_swap_b32_e32 v48, v52
	v_permlane32_swap_b32_e32 v49, v53
	v_permlane32_swap_b32_e32 v50, v54
	v_permlane32_swap_b32_e32 v51, v55
	v_permlane32_swap_b32_e32 v56, v60
	v_permlane32_swap_b32_e32 v57, v61
	v_permlane32_swap_b32_e32 v58, v62
	v_permlane32_swap_b32_e32 v59, v63
	s_waitcnt lgkmcnt(3)
	v_mfma_f32_16x16x32_bf16 v[80:83], v[144:147], v[196:199], v[80:83]
	v_mfma_f32_16x16x32_bf16 v[88:91], v[148:151], v[196:199], v[88:91]
	v_mfma_f32_16x16x32_bf16 v[16:19], v[152:155], v[196:199], v[16:19]
	v_mfma_f32_16x16x32_bf16 v[24:27], v[156:159], v[196:199], v[24:27]
	s_waitcnt lgkmcnt(2)
	v_mfma_f32_16x16x32_bf16 v[84:87], v[144:147], v[200:203], v[84:87]
	v_mfma_f32_16x16x32_bf16 v[92:95], v[148:151], v[200:203], v[92:95]
	v_mfma_f32_16x16x32_bf16 v[20:23], v[152:155], v[200:203], v[20:23]
	v_mfma_f32_16x16x32_bf16 v[28:31], v[156:159], v[200:203], v[28:31]
	v_permlane16_swap_b32_e32 v96, v100
	v_permlane16_swap_b32_e32 v97, v101
	v_permlane16_swap_b32_e32 v98, v102
	v_permlane16_swap_b32_e32 v99, v103
	v_permlane16_swap_b32_e32 v104, v108
	v_permlane16_swap_b32_e32 v105, v109
	v_permlane16_swap_b32_e32 v106, v110
	v_permlane16_swap_b32_e32 v107, v111
	v_permlane16_swap_b32_e32 v32, v36
	v_permlane16_swap_b32_e32 v33, v37
	v_permlane16_swap_b32_e32 v34, v38
	v_permlane16_swap_b32_e32 v35, v39
	v_permlane16_swap_b32_e32 v40, v44
	v_permlane16_swap_b32_e32 v41, v45
	v_permlane16_swap_b32_e32 v42, v46
	v_permlane16_swap_b32_e32 v43, v47
	v_permlane32_swap_b32_e32 v96, v100
	v_permlane32_swap_b32_e32 v97, v101
	v_permlane32_swap_b32_e32 v98, v102
	v_permlane32_swap_b32_e32 v99, v103
	v_permlane32_swap_b32_e32 v104, v108
	v_permlane32_swap_b32_e32 v105, v109
	v_permlane32_swap_b32_e32 v106, v110
	v_permlane32_swap_b32_e32 v107, v111
	v_permlane32_swap_b32_e32 v32, v36
	v_permlane32_swap_b32_e32 v33, v37
	v_permlane32_swap_b32_e32 v34, v38
	v_permlane32_swap_b32_e32 v35, v39
	v_permlane32_swap_b32_e32 v40, v44
	v_permlane32_swap_b32_e32 v41, v45
	v_permlane32_swap_b32_e32 v42, v46
	v_permlane32_swap_b32_e32 v43, v47
	s_waitcnt lgkmcnt(1)
	v_mfma_f32_16x16x32_bf16 v[64:67], v[144:147], v[204:207], v[64:67]
	v_mfma_f32_16x16x32_bf16 v[72:75], v[148:151], v[204:207], v[72:75]
	v_mfma_f32_16x16x32_bf16 v[0:3], v[152:155], v[204:207], v[0:3]
	v_mfma_f32_16x16x32_bf16 v[8:11], v[156:159], v[204:207], v[8:11]
	s_waitcnt lgkmcnt(0)
	v_mfma_f32_16x16x32_bf16 v[68:71], v[144:147], v[242:245], v[68:71]
	v_mfma_f32_16x16x32_bf16 v[76:79], v[148:151], v[242:245], v[76:79]
	v_mfma_f32_16x16x32_bf16 v[4:7], v[152:155], v[242:245], v[4:7]
	v_mfma_f32_16x16x32_bf16 v[12:15], v[156:159], v[242:245], v[12:15]
	v_permlane16_swap_b32_e32 v80, v84
	v_permlane16_swap_b32_e32 v81, v85
	v_permlane16_swap_b32_e32 v82, v86
	v_permlane16_swap_b32_e32 v83, v87
	v_permlane16_swap_b32_e32 v88, v92
	v_permlane16_swap_b32_e32 v89, v93
	v_permlane16_swap_b32_e32 v90, v94
	v_permlane16_swap_b32_e32 v91, v95
	v_permlane16_swap_b32_e32 v16, v20
	v_permlane16_swap_b32_e32 v17, v21
	v_permlane16_swap_b32_e32 v18, v22
	v_permlane16_swap_b32_e32 v19, v23
	v_permlane16_swap_b32_e32 v24, v28
	v_permlane16_swap_b32_e32 v25, v29
	v_permlane16_swap_b32_e32 v26, v30
	v_permlane16_swap_b32_e32 v27, v31
	v_permlane32_swap_b32_e32 v80, v84
	v_permlane32_swap_b32_e32 v81, v85
	v_permlane32_swap_b32_e32 v82, v86
	v_permlane32_swap_b32_e32 v83, v87
	v_permlane32_swap_b32_e32 v88, v92
	v_permlane32_swap_b32_e32 v89, v93
	v_permlane32_swap_b32_e32 v90, v94
	v_permlane32_swap_b32_e32 v91, v95
	v_permlane32_swap_b32_e32 v16, v20
	v_permlane32_swap_b32_e32 v17, v21
	v_permlane32_swap_b32_e32 v18, v22
	v_permlane32_swap_b32_e32 v19, v23
	v_permlane32_swap_b32_e32 v24, v28
	v_permlane32_swap_b32_e32 v25, v29
	v_permlane32_swap_b32_e32 v26, v30
	v_permlane32_swap_b32_e32 v27, v31
	s_barrier
	s_nop 7
	v_permlane16_swap_b32_e32 v64, v68
	v_permlane16_swap_b32_e32 v65, v69
	v_permlane16_swap_b32_e32 v66, v70
	v_permlane16_swap_b32_e32 v67, v71
	v_permlane16_swap_b32_e32 v72, v76
	v_permlane16_swap_b32_e32 v73, v77
	v_permlane16_swap_b32_e32 v74, v78
	v_permlane16_swap_b32_e32 v75, v79
	v_permlane16_swap_b32_e32 v0, v4
	v_permlane16_swap_b32_e32 v1, v5
	v_permlane16_swap_b32_e32 v2, v6
	v_permlane16_swap_b32_e32 v3, v7
	v_permlane16_swap_b32_e32 v8, v12
	v_permlane16_swap_b32_e32 v9, v13
	v_permlane16_swap_b32_e32 v10, v14
	v_permlane16_swap_b32_e32 v11, v15
	v_permlane32_swap_b32_e32 v64, v68
	v_permlane32_swap_b32_e32 v65, v69
	v_permlane32_swap_b32_e32 v66, v70
	v_permlane32_swap_b32_e32 v67, v71
	v_permlane32_swap_b32_e32 v72, v76
	v_permlane32_swap_b32_e32 v73, v77
	v_permlane32_swap_b32_e32 v74, v78
	v_permlane32_swap_b32_e32 v75, v79
	v_permlane32_swap_b32_e32 v0, v4
	v_permlane32_swap_b32_e32 v1, v5
	v_permlane32_swap_b32_e32 v2, v6
	v_permlane32_swap_b32_e32 v3, v7
	v_permlane32_swap_b32_e32 v8, v12
	v_permlane32_swap_b32_e32 v9, v13
	v_permlane32_swap_b32_e32 v10, v14
	v_permlane32_swap_b32_e32 v11, v15
	s_waitcnt vmcnt(0)
	s_movk_i32 s3, 0x2400
	s_waitcnt vmcnt(6)
	v_lshlrev_b32_e32 v128, 2, v181
	s_waitcnt vmcnt(0)
	v_and_b32_e32 v133, 0xffffffc0, v181
	v_mul_lo_u32 v129, v237, s3
	v_lshlrev_b32_e32 v130, 2, v238
	v_and_b32_e32 v128, 60, v128
	v_lshl_add_u32 v176, s8, 8, v133
	v_mul_u32_u24_e32 v133, 0x110, v183
	v_or_b32_e32 v131, v129, v130
	v_lshl_or_b32 v132, v128, 2, v129
	v_lshl_or_b32 v128, s2, 7, v128
	v_lshlrev_b32_e32 v133, 2, v133
	v_lshrrev_b32_e32 v175, 4, v239
	s_movk_i32 s2, 0x110
	v_add_u32_e32 v147, v131, v133
	v_add3_u32 v148, v129, v133, v130
	v_mad_u32_u24 v146, v175, s2, v132
	v_readlane_b32 s2, v254, 39
	v_readlane_b32 s8, v253, 36
	v_add_u32_e32 v149, 0x800, v147
	v_add_u32_e32 v150, 0x800, v148
	v_add_u32_e32 v151, 0xa00, v148
	v_mov_b32_e32 v160, s2
	v_readlane_b32 s2, v254, 37
	v_readlane_b32 s9, v253, 37
	v_readlane_b32 s10, v253, 38
	v_readlane_b32 s11, v253, 39
	v_readlane_b32 s12, v253, 40
	v_readlane_b32 s13, v253, 41
	v_readlane_b32 s14, v253, 42
	v_readlane_b32 s15, v253, 43
	v_readlane_b32 s16, v253, 44
	v_readlane_b32 s17, v253, 45
	ds_write2_b32 v147, v112, v113 offset1:68
	ds_write2_b32 v148, v96, v97 offset0:32 offset1:100
	ds_write2_b32 v147, v114, v115 offset0:136 offset1:204
	ds_write2_b32 v148, v98, v99 offset0:168 offset1:236
	ds_write2_b32 v149, v116, v117 offset0:32 offset1:100
	ds_write2_b32 v150, v100, v101 offset0:64 offset1:132
	ds_write2_b32 v149, v118, v119 offset0:168 offset1:236
	ds_write2_b32 v151, v102, v103 offset0:72 offset1:140
	v_or_b32_e32 v102, v176, v175
	v_mov_b32_e32 v161, s2
	v_readlane_b32 s2, v254, 40
	v_readlane_b32 s18, v253, 46
	v_readlane_b32 s19, v253, 47
	v_readlane_b32 s20, v253, 48
	v_readlane_b32 s21, v253, 49
	v_readlane_b32 s22, v253, 50
	v_readlane_b32 s23, v253, 51
	s_mov_b64 s[8:9], s[16:17]
	v_cmp_gt_i32_e32 vcc, s39, v102
	v_add_u32_e32 v96, 0xffff8000, v102
	v_ashrrev_i32_e32 v97, 31, v102
	v_mov_b32_e32 v162, s2
	v_readlane_b32 s2, v254, 38
	s_mov_b64 s[10:11], s[18:19]
	v_cndmask_b32_e32 v97, 0, v97, vcc
	v_cndmask_b32_e32 v96, v96, v102, vcc
	v_mov_b32_e32 v163, s2
	v_mov_b32_e32 v164, s63
	v_mov_b32_e32 v165, s11
	v_mov_b32_e32 v166, s62
	v_mov_b32_e32 v167, s10
	v_min_i32_e32 v102, 0x8000, v102
	v_add_u32_e32 v152, 0x1000, v147
	v_add_u32_e32 v153, 0x1000, v148
	v_add_u32_e32 v154, 0x1200, v147
	v_add_u32_e32 v155, 0x1200, v148
	v_add_u32_e32 v156, 0x1800, v147
	v_add_u32_e32 v157, 0x1800, v148
	v_add_u32_e32 v158, 0x1a00, v147
	v_add_u32_e32 v159, 0x1c00, v148
	v_ashrrev_i32_e32 v129, 31, v128
	v_cndmask_b32_e32 v99, v160, v161, vcc
	v_cndmask_b32_e32 v98, v162, v163, vcc
	v_lshlrev_b64 v[96:97], 12, v[96:97]
	v_cndmask_b32_e32 v101, v164, v165, vcc
	v_cndmask_b32_e32 v100, v166, v167, vcc
	v_ashrrev_i32_e32 v102, 12, v102
	ds_write2_b32 v152, v120, v121 offset0:64 offset1:132
	ds_write2_b32 v153, v104, v105 offset0:96 offset1:164
	ds_write2_b32 v154, v122, v123 offset0:72 offset1:140
	ds_write2_b32 v155, v106, v107 offset0:104 offset1:172
	ds_write2_b32 v156, v124, v125 offset0:96 offset1:164
	ds_write2_b32 v157, v108, v109 offset0:128 offset1:196
	ds_write2_b32 v158, v126, v127 offset0:104 offset1:172
	ds_write2_b32 v159, v110, v111 offset0:8 offset1:76
	v_lshl_add_u64 v[98:99], v[98:99], 0, v[96:97]
	v_lshl_add_u64 v[100:101], v[100:101], 0, v[96:97]
	v_lshlrev_b64 v[96:97], 2, v[128:129]
	v_mul_hi_i32_i24_e32 v103, 0x6000, v102
	v_mul_i32_i24_e32 v102, 0x6000, v102
	s_waitcnt lgkmcnt(0)
	v_lshl_add_u64 v[98:99], v[98:99], 0, v[96:97]
	v_lshl_add_u64 v[102:103], s[0:1], 0, v[102:103]
	v_lshl_add_u64 v[102:103], v[102:103], 0, v[96:97]
	ds_read_b128 v[104:107], v146
	global_load_dwordx4 v[108:111], v[98:99], off
	global_load_dwordx4 v[112:115], v[102:103], off
	v_or_b32_e32 v168, 4, v175
	v_lshl_add_u64 v[100:101], v[100:101], 0, v[96:97]
	v_or_b32_e32 v169, 8, v175
	v_or_b32_e32 v170, 12, v175
	v_or_b32_e32 v171, 16, v175
	v_or_b32_e32 v172, 20, v175
	v_or_b32_e32 v173, 24, v175
	v_or_b32_e32 v174, 28, v175
	v_or_b32_e32 v181, v176, v174
	v_readlane_b32 s2, v254, 11
	s_add_i32 s4, s4, s2
	s_cmp_lt_i32 s4, s26
	s_mov_b64 s[12:13], s[20:21]
	s_mov_b64 s[14:15], s[22:23]
	s_waitcnt vmcnt(0) lgkmcnt(0)
	v_pk_fma_f32 v[104:105], v[104:105], v[112:113], v[108:109]
	v_pk_fma_f32 v[106:107], v[106:107], v[114:115], v[110:111]
	v_or_b32_e32 v110, v176, v168
	global_store_dwordx4 v[100:101], v[104:107], off
	v_cmp_gt_i32_e32 vcc, s39, v110
	s_nop 0
	v_ashrrev_i32_e32 v104, 31, v110
	v_add_u32_e32 v106, 0xffff8000, v110
	v_cndmask_b32_e32 v105, 0, v104, vcc
	v_cndmask_b32_e32 v104, v106, v110, vcc
	v_cndmask_b32_e32 v107, v160, v161, vcc
	v_cndmask_b32_e32 v106, v162, v163, vcc
	v_lshlrev_b64 v[104:105], 12, v[104:105]
	v_cndmask_b32_e32 v109, v164, v165, vcc
	v_cndmask_b32_e32 v108, v166, v167, vcc
	v_lshl_add_u64 v[106:107], v[106:107], 0, v[104:105]
	v_lshl_add_u64 v[104:105], v[108:109], 0, v[104:105]
	v_min_i32_e32 v108, 0x8000, v110
	v_ashrrev_i32_e32 v108, 12, v108
	v_mul_hi_i32_i24_e32 v109, 0x6000, v108
	v_mul_i32_i24_e32 v108, 0x6000, v108
	v_lshl_add_u64 v[106:107], v[106:107], 0, v[96:97]
	v_lshl_add_u64 v[108:109], s[0:1], 0, v[108:109]
	v_lshl_add_u64 v[108:109], v[108:109], 0, v[96:97]
	ds_read_b128 v[110:113], v146 offset:1088
	global_load_dwordx4 v[114:117], v[106:107], off
	global_load_dwordx4 v[118:121], v[108:109], off
	v_lshl_add_u64 v[104:105], v[104:105], 0, v[96:97]
	s_waitcnt vmcnt(0) lgkmcnt(0)
	v_pk_fma_f32 v[110:111], v[110:111], v[118:119], v[114:115]
	v_pk_fma_f32 v[112:113], v[112:113], v[120:121], v[116:117]
	v_or_b32_e32 v118, v176, v169
	global_store_dwordx4 v[104:105], v[110:113], off
	v_cmp_gt_i32_e32 vcc, s39, v118
	s_nop 0
	v_ashrrev_i32_e32 v110, 31, v118
	v_add_u32_e32 v112, 0xffff8000, v118
	v_cndmask_b32_e32 v111, 0, v110, vcc
	v_cndmask_b32_e32 v110, v112, v118, vcc
	v_cndmask_b32_e32 v113, v160, v161, vcc
	v_cndmask_b32_e32 v112, v162, v163, vcc
	v_lshlrev_b64 v[110:111], 12, v[110:111]
	v_lshl_add_u64 v[112:113], v[112:113], 0, v[110:111]
	v_cndmask_b32_e32 v115, v164, v165, vcc
	v_cndmask_b32_e32 v114, v166, v167, vcc
	v_lshl_add_u64 v[116:117], v[114:115], 0, v[110:111]
	v_lshl_add_u64 v[110:111], v[112:113], 0, v[96:97]
	v_min_i32_e32 v112, 0x8000, v118
	v_ashrrev_i32_e32 v112, 12, v112
	v_mul_hi_i32_i24_e32 v113, 0x6000, v112
	v_mul_i32_i24_e32 v112, 0x6000, v112
	v_lshl_add_u64 v[112:113], s[0:1], 0, v[112:113]
	v_lshl_add_u64 v[114:115], v[112:113], 0, v[96:97]
	v_lshl_add_u64 v[112:113], v[116:117], 0, v[96:97]
	ds_read_b128 v[116:119], v146 offset:2176
	global_load_dwordx4 v[120:123], v[110:111], off
	global_load_dwordx4 v[124:127], v[114:115], off
	s_waitcnt vmcnt(0) lgkmcnt(0)
	v_pk_fma_f32 v[116:117], v[116:117], v[124:125], v[120:121]
	v_pk_fma_f32 v[118:119], v[118:119], v[126:127], v[122:123]
	v_or_b32_e32 v124, v176, v170
	global_store_dwordx4 v[112:113], v[116:119], off
	v_cmp_gt_i32_e32 vcc, s39, v124
	s_nop 0
	v_ashrrev_i32_e32 v116, 31, v124
	v_add_u32_e32 v118, 0xffff8000, v124
	v_cndmask_b32_e32 v117, 0, v116, vcc
	v_cndmask_b32_e32 v116, v118, v124, vcc
	v_cndmask_b32_e32 v119, v160, v161, vcc
	v_cndmask_b32_e32 v118, v162, v163, vcc
	v_lshlrev_b64 v[116:117], 12, v[116:117]
	v_lshl_add_u64 v[118:119], v[118:119], 0, v[116:117]
	v_cndmask_b32_e32 v121, v164, v165, vcc
	v_cndmask_b32_e32 v120, v166, v167, vcc
	v_lshl_add_u64 v[122:123], v[120:121], 0, v[116:117]
	v_lshl_add_u64 v[116:117], v[118:119], 0, v[96:97]
	v_min_i32_e32 v118, 0x8000, v124
	v_ashrrev_i32_e32 v118, 12, v118
	v_mul_hi_i32_i24_e32 v119, 0x6000, v118
	v_mul_i32_i24_e32 v118, 0x6000, v118
	v_lshl_add_u64 v[118:119], s[0:1], 0, v[118:119]
	v_lshl_add_u64 v[120:121], v[118:119], 0, v[96:97]
	v_lshl_add_u64 v[118:119], v[122:123], 0, v[96:97]
	ds_read_b128 v[122:125], v146 offset:3264
	global_load_dwordx4 v[126:129], v[116:117], off
	global_load_dwordx4 v[130:133], v[120:121], off
	s_waitcnt vmcnt(0) lgkmcnt(0)
	v_pk_fma_f32 v[122:123], v[122:123], v[130:131], v[126:127]
	v_pk_fma_f32 v[124:125], v[124:125], v[132:133], v[128:129]
	v_or_b32_e32 v130, v176, v171
	global_store_dwordx4 v[118:119], v[122:125], off
	v_cmp_gt_i32_e32 vcc, s39, v130
	s_nop 0
	v_ashrrev_i32_e32 v122, 31, v130
	v_add_u32_e32 v124, 0xffff8000, v130
	v_cndmask_b32_e32 v123, 0, v122, vcc
	v_cndmask_b32_e32 v122, v124, v130, vcc
	v_cndmask_b32_e32 v125, v160, v161, vcc
	v_cndmask_b32_e32 v124, v162, v163, vcc
	v_lshlrev_b64 v[122:123], 12, v[122:123]
	v_lshl_add_u64 v[124:125], v[124:125], 0, v[122:123]
	v_cndmask_b32_e32 v127, v164, v165, vcc
	v_cndmask_b32_e32 v126, v166, v167, vcc
	v_lshl_add_u64 v[128:129], v[126:127], 0, v[122:123]
	v_lshl_add_u64 v[122:123], v[124:125], 0, v[96:97]
	v_min_i32_e32 v124, 0x8000, v130
	v_ashrrev_i32_e32 v124, 12, v124
	v_mul_hi_i32_i24_e32 v125, 0x6000, v124
	v_mul_i32_i24_e32 v124, 0x6000, v124
	v_lshl_add_u64 v[124:125], s[0:1], 0, v[124:125]
	v_lshl_add_u64 v[126:127], v[124:125], 0, v[96:97]
	v_lshl_add_u64 v[124:125], v[128:129], 0, v[96:97]
	ds_read_b128 v[128:131], v146 offset:4352
	global_load_dwordx4 v[132:135], v[122:123], off
	global_load_dwordx4 v[136:139], v[126:127], off
	s_waitcnt vmcnt(0) lgkmcnt(0)
	v_pk_fma_f32 v[128:129], v[128:129], v[136:137], v[132:133]
	v_pk_fma_f32 v[130:131], v[130:131], v[138:139], v[134:135]
	v_or_b32_e32 v136, v176, v172
	global_store_dwordx4 v[124:125], v[128:131], off
	v_cmp_gt_i32_e32 vcc, s39, v136
	s_nop 0
	v_ashrrev_i32_e32 v128, 31, v136
	v_add_u32_e32 v130, 0xffff8000, v136
	v_cndmask_b32_e32 v129, 0, v128, vcc
	v_cndmask_b32_e32 v128, v130, v136, vcc
	v_cndmask_b32_e32 v131, v160, v161, vcc
	v_cndmask_b32_e32 v130, v162, v163, vcc
	v_lshlrev_b64 v[128:129], 12, v[128:129]
	v_lshl_add_u64 v[130:131], v[130:131], 0, v[128:129]
	v_cndmask_b32_e32 v133, v164, v165, vcc
	v_cndmask_b32_e32 v132, v166, v167, vcc
	v_lshl_add_u64 v[134:135], v[132:133], 0, v[128:129]
	v_lshl_add_u64 v[128:129], v[130:131], 0, v[96:97]
	v_min_i32_e32 v130, 0x8000, v136
	v_ashrrev_i32_e32 v130, 12, v130
	v_mul_hi_i32_i24_e32 v131, 0x6000, v130
	v_mul_i32_i24_e32 v130, 0x6000, v130
	v_lshl_add_u64 v[130:131], s[0:1], 0, v[130:131]
	v_lshl_add_u64 v[132:133], v[130:131], 0, v[96:97]
	v_lshl_add_u64 v[130:131], v[134:135], 0, v[96:97]
	ds_read_b128 v[134:137], v146 offset:5440
	global_load_dwordx4 v[138:141], v[128:129], off
	global_load_dwordx4 v[142:145], v[132:133], off
	s_waitcnt vmcnt(0) lgkmcnt(0)
	v_pk_fma_f32 v[134:135], v[134:135], v[142:143], v[138:139]
	v_pk_fma_f32 v[136:137], v[136:137], v[144:145], v[140:141]
	v_or_b32_e32 v142, v176, v173
	global_store_dwordx4 v[130:131], v[134:137], off
	v_cmp_gt_i32_e32 vcc, s39, v142
	s_nop 0
	v_ashrrev_i32_e32 v134, 31, v142
	v_add_u32_e32 v136, 0xffff8000, v142
	v_cndmask_b32_e32 v135, 0, v134, vcc
	v_cndmask_b32_e32 v134, v136, v142, vcc
	v_cndmask_b32_e32 v137, v160, v161, vcc
	v_cndmask_b32_e32 v136, v162, v163, vcc
	v_lshlrev_b64 v[134:135], 12, v[134:135]
	v_lshl_add_u64 v[136:137], v[136:137], 0, v[134:135]
	v_cndmask_b32_e32 v139, v164, v165, vcc
	v_cndmask_b32_e32 v138, v166, v167, vcc
	v_lshl_add_u64 v[140:141], v[138:139], 0, v[134:135]
	v_lshl_add_u64 v[134:135], v[136:137], 0, v[96:97]
	v_min_i32_e32 v136, 0x8000, v142
	v_ashrrev_i32_e32 v136, 12, v136
	v_mul_hi_i32_i24_e32 v137, 0x6000, v136
	v_mul_i32_i24_e32 v136, 0x6000, v136
	v_lshl_add_u64 v[136:137], s[0:1], 0, v[136:137]
	v_lshl_add_u64 v[138:139], v[136:137], 0, v[96:97]
	v_lshl_add_u64 v[136:137], v[140:141], 0, v[96:97]
	ds_read_b128 v[140:143], v146 offset:6528
	global_load_dwordx4 v[184:187], v[134:135], off
	global_load_dwordx4 v[196:199], v[138:139], off
	v_cmp_gt_i32_e32 vcc, s39, v181
	s_waitcnt vmcnt(0) lgkmcnt(0)
	v_pk_fma_f32 v[140:141], v[140:141], v[196:197], v[184:185]
	v_pk_fma_f32 v[142:143], v[142:143], v[198:199], v[186:187]
	global_store_dwordx4 v[136:137], v[140:143], off
	v_cndmask_b32_e32 v145, v164, v165, vcc
	v_cndmask_b32_e32 v144, v166, v167, vcc
	v_ashrrev_i32_e32 v140, 31, v181
	v_add_u32_e32 v142, 0xffff8000, v181
	v_cndmask_b32_e32 v141, 0, v140, vcc
	v_cndmask_b32_e32 v140, v142, v181, vcc
	v_cndmask_b32_e32 v143, v160, v161, vcc
	v_cndmask_b32_e32 v142, v162, v163, vcc
	v_lshlrev_b64 v[140:141], 12, v[140:141]
	v_lshl_add_u64 v[142:143], v[142:143], 0, v[140:141]
	v_lshl_add_u64 v[184:185], v[144:145], 0, v[140:141]
	v_lshl_add_u64 v[140:141], v[142:143], 0, v[96:97]
	v_min_i32_e32 v142, 0x8000, v181
	v_ashrrev_i32_e32 v142, 12, v142
	v_mul_hi_i32_i24_e32 v143, 0x6000, v142
	v_mul_i32_i24_e32 v142, 0x6000, v142
	v_lshl_add_u64 v[142:143], s[0:1], 0, v[142:143]
	v_lshl_add_u64 v[144:145], v[142:143], 0, v[96:97]
	v_lshl_add_u64 v[142:143], v[184:185], 0, v[96:97]
	ds_read_b128 v[184:187], v146 offset:7616
	global_load_dwordx4 v[196:199], v[140:141], off
	global_load_dwordx4 v[200:203], v[144:145], off
	s_waitcnt vmcnt(0) lgkmcnt(0)
	v_pk_fma_f32 v[184:185], v[184:185], v[200:201], v[196:197]
	v_pk_fma_f32 v[186:187], v[186:187], v[202:203], v[198:199]
	global_store_dwordx4 v[142:143], v[184:187], off
	s_waitcnt lgkmcnt(0)
	ds_write2_b32 v147, v80, v81 offset1:68
	ds_write2_b32 v148, v64, v65 offset0:32 offset1:100
	ds_write2_b32 v147, v82, v83 offset0:136 offset1:204
	ds_write2_b32 v148, v66, v67 offset0:168 offset1:236
	ds_write2_b32 v149, v84, v85 offset0:32 offset1:100
	ds_write2_b32 v150, v68, v69 offset0:64 offset1:132
	ds_write2_b32 v149, v86, v87 offset0:168 offset1:236
	ds_write2_b32 v151, v70, v71 offset0:72 offset1:140
	ds_write2_b32 v152, v88, v89 offset0:64 offset1:132
	ds_write2_b32 v153, v72, v73 offset0:96 offset1:164
	ds_write2_b32 v154, v90, v91 offset0:72 offset1:140
	ds_write2_b32 v155, v74, v75 offset0:104 offset1:172
	ds_write2_b32 v156, v92, v93 offset0:96 offset1:164
	ds_write2_b32 v157, v76, v77 offset0:128 offset1:196
	ds_write2_b32 v158, v94, v95 offset0:104 offset1:172
	ds_write2_b32 v159, v78, v79 offset0:8 offset1:76
	s_waitcnt lgkmcnt(0)
	ds_read_b128 v[64:67], v146
	global_load_dwordx4 v[68:71], v[98:99], off offset:256
	global_load_dwordx4 v[72:75], v[102:103], off offset:256
	s_waitcnt vmcnt(0) lgkmcnt(0)
	v_pk_fma_f32 v[64:65], v[64:65], v[72:73], v[68:69]
	v_pk_fma_f32 v[66:67], v[66:67], v[74:75], v[70:71]
	global_store_dwordx4 v[100:101], v[64:67], off offset:256
	ds_read_b128 v[64:67], v146 offset:1088
	global_load_dwordx4 v[68:71], v[106:107], off offset:256
	global_load_dwordx4 v[72:75], v[108:109], off offset:256
	s_waitcnt vmcnt(0) lgkmcnt(0)
	v_pk_fma_f32 v[64:65], v[64:65], v[72:73], v[68:69]
	v_pk_fma_f32 v[66:67], v[66:67], v[74:75], v[70:71]
	global_store_dwordx4 v[104:105], v[64:67], off offset:256
	ds_read_b128 v[64:67], v146 offset:2176
	global_load_dwordx4 v[68:71], v[110:111], off offset:256
	global_load_dwordx4 v[72:75], v[114:115], off offset:256
	s_waitcnt vmcnt(0) lgkmcnt(0)
	v_pk_fma_f32 v[64:65], v[64:65], v[72:73], v[68:69]
	v_pk_fma_f32 v[66:67], v[66:67], v[74:75], v[70:71]
	global_store_dwordx4 v[112:113], v[64:67], off offset:256
	ds_read_b128 v[64:67], v146 offset:3264
	global_load_dwordx4 v[68:71], v[116:117], off offset:256
	global_load_dwordx4 v[72:75], v[120:121], off offset:256
	s_waitcnt vmcnt(0) lgkmcnt(0)
	v_pk_fma_f32 v[64:65], v[64:65], v[72:73], v[68:69]
	v_pk_fma_f32 v[66:67], v[66:67], v[74:75], v[70:71]
	global_store_dwordx4 v[118:119], v[64:67], off offset:256
	ds_read_b128 v[64:67], v146 offset:4352
	global_load_dwordx4 v[68:71], v[122:123], off offset:256
	global_load_dwordx4 v[72:75], v[126:127], off offset:256
	s_waitcnt vmcnt(0) lgkmcnt(0)
	v_pk_fma_f32 v[64:65], v[64:65], v[72:73], v[68:69]
	v_pk_fma_f32 v[66:67], v[66:67], v[74:75], v[70:71]
	global_store_dwordx4 v[124:125], v[64:67], off offset:256
	ds_read_b128 v[64:67], v146 offset:5440
	global_load_dwordx4 v[68:71], v[128:129], off offset:256
	global_load_dwordx4 v[72:75], v[132:133], off offset:256
	s_waitcnt vmcnt(0) lgkmcnt(0)
	v_pk_fma_f32 v[64:65], v[64:65], v[72:73], v[68:69]
	v_pk_fma_f32 v[66:67], v[66:67], v[74:75], v[70:71]
	global_store_dwordx4 v[130:131], v[64:67], off offset:256
	ds_read_b128 v[64:67], v146 offset:6528
	global_load_dwordx4 v[68:71], v[134:135], off offset:256
	global_load_dwordx4 v[72:75], v[138:139], off offset:256
	s_waitcnt vmcnt(0) lgkmcnt(0)
	v_pk_fma_f32 v[64:65], v[64:65], v[72:73], v[68:69]
	v_pk_fma_f32 v[66:67], v[66:67], v[74:75], v[70:71]
	global_store_dwordx4 v[136:137], v[64:67], off offset:256
	ds_read_b128 v[64:67], v146 offset:7616
	global_load_dwordx4 v[68:71], v[140:141], off offset:256
	global_load_dwordx4 v[72:75], v[144:145], off offset:256
	s_waitcnt vmcnt(0) lgkmcnt(0)
	v_pk_fma_f32 v[64:65], v[64:65], v[72:73], v[68:69]
	v_pk_fma_f32 v[66:67], v[66:67], v[74:75], v[70:71]
	global_store_dwordx4 v[142:143], v[64:67], off offset:256
	v_or_b32_e32 v74, 32, v176
	s_waitcnt lgkmcnt(0)
	ds_write2_b32 v147, v48, v49 offset1:68
	ds_write2_b32 v148, v32, v33 offset0:32 offset1:100
	ds_write2_b32 v147, v50, v51 offset0:136 offset1:204
	ds_write2_b32 v148, v34, v35 offset0:168 offset1:236
	ds_write2_b32 v149, v52, v53 offset0:32 offset1:100
	ds_write2_b32 v150, v36, v37 offset0:64 offset1:132
	ds_write2_b32 v149, v54, v55 offset0:168 offset1:236
	ds_write2_b32 v151, v38, v39 offset0:72 offset1:140
	ds_write2_b32 v152, v56, v57 offset0:64 offset1:132
	ds_write2_b32 v153, v40, v41 offset0:96 offset1:164
	ds_write2_b32 v154, v58, v59 offset0:72 offset1:140
	ds_write2_b32 v155, v42, v43 offset0:104 offset1:172
	ds_write2_b32 v156, v60, v61 offset0:96 offset1:164
	ds_write2_b32 v157, v44, v45 offset0:128 offset1:196
	ds_write2_b32 v158, v62, v63 offset0:104 offset1:172
	ds_write2_b32 v159, v46, v47 offset0:8 offset1:76
	v_or_b32_e32 v40, v74, v175
	v_cmp_gt_i32_e32 vcc, s39, v40
	v_ashrrev_i32_e32 v32, 31, v40
	v_add_u32_e32 v34, 0xffff8000, v40
	v_cndmask_b32_e32 v33, 0, v32, vcc
	v_cndmask_b32_e32 v32, v34, v40, vcc
	v_cndmask_b32_e32 v35, v160, v161, vcc
	v_cndmask_b32_e32 v34, v162, v163, vcc
	v_lshlrev_b64 v[32:33], 12, v[32:33]
	v_lshl_add_u64 v[34:35], v[34:35], 0, v[32:33]
	v_cndmask_b32_e32 v37, v164, v165, vcc
	v_cndmask_b32_e32 v36, v166, v167, vcc
	v_lshl_add_u64 v[38:39], v[36:37], 0, v[32:33]
	v_lshl_add_u64 v[32:33], v[34:35], 0, v[96:97]
	v_min_i32_e32 v34, 0x8000, v40
	v_ashrrev_i32_e32 v34, 12, v34
	v_mul_hi_i32_i24_e32 v35, 0x6000, v34
	v_mul_i32_i24_e32 v34, 0x6000, v34
	s_waitcnt lgkmcnt(0)
	v_lshl_add_u64 v[34:35], s[0:1], 0, v[34:35]
	v_lshl_add_u64 v[36:37], v[34:35], 0, v[96:97]
	v_lshl_add_u64 v[34:35], v[38:39], 0, v[96:97]
	ds_read_b128 v[38:41], v146
	global_load_dwordx4 v[42:45], v[32:33], off
	global_load_dwordx4 v[46:49], v[36:37], off
	v_or_b32_e32 v75, v74, v173
	s_waitcnt vmcnt(0) lgkmcnt(0)
	v_pk_fma_f32 v[38:39], v[38:39], v[46:47], v[42:43]
	v_pk_fma_f32 v[40:41], v[40:41], v[48:49], v[44:45]
	v_or_b32_e32 v46, v74, v168
	global_store_dwordx4 v[34:35], v[38:41], off
	v_cmp_gt_i32_e32 vcc, s39, v46
	s_nop 0
	v_ashrrev_i32_e32 v38, 31, v46
	v_add_u32_e32 v40, 0xffff8000, v46
	v_cndmask_b32_e32 v39, 0, v38, vcc
	v_cndmask_b32_e32 v38, v40, v46, vcc
	v_cndmask_b32_e32 v41, v160, v161, vcc
	v_cndmask_b32_e32 v40, v162, v163, vcc
	v_lshlrev_b64 v[38:39], 12, v[38:39]
	v_lshl_add_u64 v[40:41], v[40:41], 0, v[38:39]
	v_cndmask_b32_e32 v43, v164, v165, vcc
	v_cndmask_b32_e32 v42, v166, v167, vcc
	v_lshl_add_u64 v[44:45], v[42:43], 0, v[38:39]
	v_lshl_add_u64 v[38:39], v[40:41], 0, v[96:97]
	v_min_i32_e32 v40, 0x8000, v46
	v_ashrrev_i32_e32 v40, 12, v40
	v_mul_hi_i32_i24_e32 v41, 0x6000, v40
	v_mul_i32_i24_e32 v40, 0x6000, v40
	v_lshl_add_u64 v[40:41], s[0:1], 0, v[40:41]
	v_lshl_add_u64 v[42:43], v[40:41], 0, v[96:97]
	v_lshl_add_u64 v[40:41], v[44:45], 0, v[96:97]
	ds_read_b128 v[44:47], v146 offset:1088
	global_load_dwordx4 v[48:51], v[38:39], off
	global_load_dwordx4 v[52:55], v[42:43], off
	s_waitcnt vmcnt(0) lgkmcnt(0)
	v_pk_fma_f32 v[44:45], v[44:45], v[52:53], v[48:49]
	v_pk_fma_f32 v[46:47], v[46:47], v[54:55], v[50:51]
	v_or_b32_e32 v52, v74, v169
	global_store_dwordx4 v[40:41], v[44:47], off
	v_cmp_gt_i32_e32 vcc, s39, v52
	s_nop 0
	v_ashrrev_i32_e32 v44, 31, v52
	v_add_u32_e32 v46, 0xffff8000, v52
	v_cndmask_b32_e32 v45, 0, v44, vcc
	v_cndmask_b32_e32 v44, v46, v52, vcc
	v_cndmask_b32_e32 v47, v160, v161, vcc
	v_cndmask_b32_e32 v46, v162, v163, vcc
	v_lshlrev_b64 v[44:45], 12, v[44:45]
	v_lshl_add_u64 v[46:47], v[46:47], 0, v[44:45]
	v_cndmask_b32_e32 v49, v164, v165, vcc
	v_cndmask_b32_e32 v48, v166, v167, vcc
	v_lshl_add_u64 v[50:51], v[48:49], 0, v[44:45]
	v_lshl_add_u64 v[44:45], v[46:47], 0, v[96:97]
	v_min_i32_e32 v46, 0x8000, v52
	v_ashrrev_i32_e32 v46, 12, v46
	v_mul_hi_i32_i24_e32 v47, 0x6000, v46
	v_mul_i32_i24_e32 v46, 0x6000, v46
	v_lshl_add_u64 v[46:47], s[0:1], 0, v[46:47]
	v_lshl_add_u64 v[48:49], v[46:47], 0, v[96:97]
	v_lshl_add_u64 v[46:47], v[50:51], 0, v[96:97]
	ds_read_b128 v[50:53], v146 offset:2176
	global_load_dwordx4 v[54:57], v[44:45], off
	global_load_dwordx4 v[58:61], v[48:49], off
	s_waitcnt vmcnt(0) lgkmcnt(0)
	v_pk_fma_f32 v[50:51], v[50:51], v[58:59], v[54:55]
	v_pk_fma_f32 v[52:53], v[52:53], v[60:61], v[56:57]
	v_or_b32_e32 v58, v74, v170
	global_store_dwordx4 v[46:47], v[50:53], off
	v_cmp_gt_i32_e32 vcc, s39, v58
	s_nop 0
	v_ashrrev_i32_e32 v50, 31, v58
	v_add_u32_e32 v52, 0xffff8000, v58
	v_cndmask_b32_e32 v51, 0, v50, vcc
	v_cndmask_b32_e32 v50, v52, v58, vcc
	v_cndmask_b32_e32 v53, v160, v161, vcc
	v_cndmask_b32_e32 v52, v162, v163, vcc
	v_lshlrev_b64 v[50:51], 12, v[50:51]
	v_lshl_add_u64 v[52:53], v[52:53], 0, v[50:51]
	v_cndmask_b32_e32 v55, v164, v165, vcc
	v_cndmask_b32_e32 v54, v166, v167, vcc
	v_lshl_add_u64 v[56:57], v[54:55], 0, v[50:51]
	v_lshl_add_u64 v[50:51], v[52:53], 0, v[96:97]
	v_min_i32_e32 v52, 0x8000, v58
	v_ashrrev_i32_e32 v52, 12, v52
	v_mul_hi_i32_i24_e32 v53, 0x6000, v52
	v_mul_i32_i24_e32 v52, 0x6000, v52
	v_lshl_add_u64 v[52:53], s[0:1], 0, v[52:53]
	v_lshl_add_u64 v[54:55], v[52:53], 0, v[96:97]
	v_lshl_add_u64 v[52:53], v[56:57], 0, v[96:97]
	ds_read_b128 v[56:59], v146 offset:3264
	global_load_dwordx4 v[60:63], v[50:51], off
	global_load_dwordx4 v[64:67], v[54:55], off
	s_waitcnt vmcnt(0) lgkmcnt(0)
	v_pk_fma_f32 v[56:57], v[56:57], v[64:65], v[60:61]
	v_pk_fma_f32 v[58:59], v[58:59], v[66:67], v[62:63]
	v_or_b32_e32 v64, v74, v171
	global_store_dwordx4 v[52:53], v[56:59], off
	v_cmp_gt_i32_e32 vcc, s39, v64
	s_nop 0
	v_ashrrev_i32_e32 v56, 31, v64
	v_add_u32_e32 v58, 0xffff8000, v64
	v_cndmask_b32_e32 v57, 0, v56, vcc
	v_cndmask_b32_e32 v56, v58, v64, vcc
	v_cndmask_b32_e32 v59, v160, v161, vcc
	v_cndmask_b32_e32 v58, v162, v163, vcc
	v_lshlrev_b64 v[56:57], 12, v[56:57]
	v_lshl_add_u64 v[58:59], v[58:59], 0, v[56:57]
	v_cndmask_b32_e32 v61, v164, v165, vcc
	v_cndmask_b32_e32 v60, v166, v167, vcc
	v_lshl_add_u64 v[62:63], v[60:61], 0, v[56:57]
	v_lshl_add_u64 v[56:57], v[58:59], 0, v[96:97]
	v_min_i32_e32 v58, 0x8000, v64
	v_ashrrev_i32_e32 v58, 12, v58
	v_mul_hi_i32_i24_e32 v59, 0x6000, v58
	v_mul_i32_i24_e32 v58, 0x6000, v58
	v_lshl_add_u64 v[58:59], s[0:1], 0, v[58:59]
	v_lshl_add_u64 v[60:61], v[58:59], 0, v[96:97]
	v_lshl_add_u64 v[58:59], v[62:63], 0, v[96:97]
	ds_read_b128 v[62:65], v146 offset:4352
	global_load_dwordx4 v[66:69], v[56:57], off
	global_load_dwordx4 v[70:73], v[60:61], off
	s_waitcnt vmcnt(0) lgkmcnt(0)
	v_pk_fma_f32 v[62:63], v[62:63], v[70:71], v[66:67]
	v_pk_fma_f32 v[64:65], v[64:65], v[72:73], v[68:69]
	v_or_b32_e32 v70, v74, v172
	global_store_dwordx4 v[58:59], v[62:65], off
	v_cmp_gt_i32_e32 vcc, s39, v70
	s_nop 0
	v_ashrrev_i32_e32 v62, 31, v70
	v_add_u32_e32 v64, 0xffff8000, v70
	v_cndmask_b32_e32 v63, 0, v62, vcc
	v_cndmask_b32_e32 v62, v64, v70, vcc
	v_cndmask_b32_e32 v65, v160, v161, vcc
	v_cndmask_b32_e32 v64, v162, v163, vcc
	v_lshlrev_b64 v[62:63], 12, v[62:63]
	v_lshl_add_u64 v[64:65], v[64:65], 0, v[62:63]
	v_cndmask_b32_e32 v67, v164, v165, vcc
	v_cndmask_b32_e32 v66, v166, v167, vcc
	v_lshl_add_u64 v[68:69], v[66:67], 0, v[62:63]
	v_lshl_add_u64 v[62:63], v[64:65], 0, v[96:97]
	v_min_i32_e32 v64, 0x8000, v70
	v_ashrrev_i32_e32 v64, 12, v64
	v_mul_hi_i32_i24_e32 v65, 0x6000, v64
	v_mul_i32_i24_e32 v64, 0x6000, v64
	v_lshl_add_u64 v[64:65], s[0:1], 0, v[64:65]
	v_lshl_add_u64 v[66:67], v[64:65], 0, v[96:97]
	v_lshl_add_u64 v[64:65], v[68:69], 0, v[96:97]
	ds_read_b128 v[68:71], v146 offset:5440
	global_load_dwordx4 v[76:79], v[62:63], off
	global_load_dwordx4 v[80:83], v[66:67], off
	v_cmp_gt_i32_e32 vcc, s39, v75
	s_waitcnt vmcnt(0) lgkmcnt(0)
	v_pk_fma_f32 v[68:69], v[68:69], v[80:81], v[76:77]
	v_pk_fma_f32 v[70:71], v[70:71], v[82:83], v[78:79]
	global_store_dwordx4 v[64:65], v[68:71], off
	v_cndmask_b32_e32 v73, v164, v165, vcc
	v_cndmask_b32_e32 v72, v166, v167, vcc
	v_ashrrev_i32_e32 v68, 31, v75
	v_add_u32_e32 v70, 0xffff8000, v75
	v_cndmask_b32_e32 v69, 0, v68, vcc
	v_cndmask_b32_e32 v68, v70, v75, vcc
	v_cndmask_b32_e32 v71, v160, v161, vcc
	v_cndmask_b32_e32 v70, v162, v163, vcc
	v_lshlrev_b64 v[68:69], 12, v[68:69]
	v_lshl_add_u64 v[70:71], v[70:71], 0, v[68:69]
	v_lshl_add_u64 v[76:77], v[72:73], 0, v[68:69]
	v_lshl_add_u64 v[68:69], v[70:71], 0, v[96:97]
	v_min_i32_e32 v70, 0x8000, v75
	v_ashrrev_i32_e32 v70, 12, v70
	v_mul_hi_i32_i24_e32 v71, 0x6000, v70
	v_mul_i32_i24_e32 v70, 0x6000, v70
	v_lshl_add_u64 v[70:71], s[0:1], 0, v[70:71]
	v_lshl_add_u64 v[72:73], v[70:71], 0, v[96:97]
	v_lshl_add_u64 v[70:71], v[76:77], 0, v[96:97]
	ds_read_b128 v[76:79], v146 offset:6528
	global_load_dwordx4 v[80:83], v[68:69], off
	global_load_dwordx4 v[84:87], v[72:73], off
	s_waitcnt vmcnt(0) lgkmcnt(0)
	v_pk_fma_f32 v[76:77], v[76:77], v[84:85], v[80:81]
	v_pk_fma_f32 v[78:79], v[78:79], v[86:87], v[82:83]
	v_or_b32_e32 v82, v74, v174
	global_store_dwordx4 v[70:71], v[76:79], off
	v_cmp_gt_i32_e32 vcc, s39, v82
	v_ashrrev_i32_e32 v74, 31, v82
	v_add_u32_e32 v76, 0xffff8000, v82
	v_cndmask_b32_e32 v75, 0, v74, vcc
	v_cndmask_b32_e32 v74, v76, v82, vcc
	v_cndmask_b32_e32 v77, v160, v161, vcc
	v_cndmask_b32_e32 v76, v162, v163, vcc
	v_lshlrev_b64 v[74:75], 12, v[74:75]
	v_lshl_add_u64 v[76:77], v[76:77], 0, v[74:75]
	v_cndmask_b32_e32 v79, v164, v165, vcc
	v_cndmask_b32_e32 v78, v166, v167, vcc
	v_lshl_add_u64 v[80:81], v[78:79], 0, v[74:75]
	v_lshl_add_u64 v[74:75], v[76:77], 0, v[96:97]
	v_min_i32_e32 v76, 0x8000, v82
	v_ashrrev_i32_e32 v76, 12, v76
	v_mul_hi_i32_i24_e32 v77, 0x6000, v76
	v_mul_i32_i24_e32 v76, 0x6000, v76
	v_lshl_add_u64 v[76:77], s[0:1], 0, v[76:77]
	v_lshl_add_u64 v[78:79], v[76:77], 0, v[96:97]
	v_lshl_add_u64 v[76:77], v[80:81], 0, v[96:97]
	ds_read_b128 v[80:83], v146 offset:7616
	global_load_dwordx4 v[84:87], v[74:75], off
	global_load_dwordx4 v[88:91], v[78:79], off
	s_waitcnt vmcnt(0) lgkmcnt(0)
	v_pk_fma_f32 v[80:81], v[80:81], v[88:89], v[84:85]
	v_pk_fma_f32 v[82:83], v[82:83], v[90:91], v[86:87]
	global_store_dwordx4 v[76:77], v[80:83], off
	s_waitcnt lgkmcnt(0)
	ds_write2_b32 v147, v16, v17 offset1:68
	ds_write2_b32 v148, v0, v1 offset0:32 offset1:100
	ds_write2_b32 v147, v18, v19 offset0:136 offset1:204
	ds_write2_b32 v148, v2, v3 offset0:168 offset1:236
	ds_write2_b32 v149, v20, v21 offset0:32 offset1:100
	ds_write2_b32 v150, v4, v5 offset0:64 offset1:132
	ds_write2_b32 v149, v22, v23 offset0:168 offset1:236
	ds_write2_b32 v151, v6, v7 offset0:72 offset1:140
	ds_write2_b32 v152, v24, v25 offset0:64 offset1:132
	ds_write2_b32 v153, v8, v9 offset0:96 offset1:164
	ds_write2_b32 v154, v26, v27 offset0:72 offset1:140
	ds_write2_b32 v155, v10, v11 offset0:104 offset1:172
	ds_write2_b32 v156, v28, v29 offset0:96 offset1:164
	ds_write2_b32 v157, v12, v13 offset0:128 offset1:196
	ds_write2_b32 v158, v30, v31 offset0:104 offset1:172
	ds_write2_b32 v159, v14, v15 offset0:8 offset1:76
	s_waitcnt lgkmcnt(0)
	ds_read_b128 v[0:3], v146
	global_load_dwordx4 v[4:7], v[32:33], off offset:256
	global_load_dwordx4 v[8:11], v[36:37], off offset:256
	s_waitcnt vmcnt(0) lgkmcnt(0)
	v_pk_fma_f32 v[0:1], v[0:1], v[8:9], v[4:5]
	v_pk_fma_f32 v[2:3], v[2:3], v[10:11], v[6:7]
	global_store_dwordx4 v[34:35], v[0:3], off offset:256
	ds_read_b128 v[0:3], v146 offset:1088
	global_load_dwordx4 v[4:7], v[38:39], off offset:256
	global_load_dwordx4 v[8:11], v[42:43], off offset:256
	s_waitcnt vmcnt(0) lgkmcnt(0)
	v_pk_fma_f32 v[0:1], v[0:1], v[8:9], v[4:5]
	v_pk_fma_f32 v[2:3], v[2:3], v[10:11], v[6:7]
	global_store_dwordx4 v[40:41], v[0:3], off offset:256
	ds_read_b128 v[0:3], v146 offset:2176
	global_load_dwordx4 v[4:7], v[44:45], off offset:256
	global_load_dwordx4 v[8:11], v[48:49], off offset:256
	s_waitcnt vmcnt(0) lgkmcnt(0)
	v_pk_fma_f32 v[0:1], v[0:1], v[8:9], v[4:5]
	v_pk_fma_f32 v[2:3], v[2:3], v[10:11], v[6:7]
	global_store_dwordx4 v[46:47], v[0:3], off offset:256
	ds_read_b128 v[0:3], v146 offset:3264
	global_load_dwordx4 v[4:7], v[50:51], off offset:256
	global_load_dwordx4 v[8:11], v[54:55], off offset:256
	s_waitcnt vmcnt(0) lgkmcnt(0)
	v_pk_fma_f32 v[0:1], v[0:1], v[8:9], v[4:5]
	v_pk_fma_f32 v[2:3], v[2:3], v[10:11], v[6:7]
	global_store_dwordx4 v[52:53], v[0:3], off offset:256
	ds_read_b128 v[0:3], v146 offset:4352
	global_load_dwordx4 v[4:7], v[56:57], off offset:256
	global_load_dwordx4 v[8:11], v[60:61], off offset:256
	s_waitcnt vmcnt(0) lgkmcnt(0)
	v_pk_fma_f32 v[0:1], v[0:1], v[8:9], v[4:5]
	v_pk_fma_f32 v[2:3], v[2:3], v[10:11], v[6:7]
	global_store_dwordx4 v[58:59], v[0:3], off offset:256
	ds_read_b128 v[0:3], v146 offset:5440
	global_load_dwordx4 v[4:7], v[62:63], off offset:256
	global_load_dwordx4 v[8:11], v[66:67], off offset:256
	s_waitcnt vmcnt(0) lgkmcnt(0)
	v_pk_fma_f32 v[0:1], v[0:1], v[8:9], v[4:5]
	v_pk_fma_f32 v[2:3], v[2:3], v[10:11], v[6:7]
	global_store_dwordx4 v[64:65], v[0:3], off offset:256
	ds_read_b128 v[0:3], v146 offset:6528
	global_load_dwordx4 v[4:7], v[68:69], off offset:256
	global_load_dwordx4 v[8:11], v[72:73], off offset:256
	s_waitcnt vmcnt(0) lgkmcnt(0)
	v_pk_fma_f32 v[0:1], v[0:1], v[8:9], v[4:5]
	v_pk_fma_f32 v[2:3], v[2:3], v[10:11], v[6:7]
	global_store_dwordx4 v[70:71], v[0:3], off offset:256
	ds_read_b128 v[0:3], v146 offset:7616
	global_load_dwordx4 v[4:7], v[74:75], off offset:256
	global_load_dwordx4 v[8:11], v[78:79], off offset:256
	s_waitcnt vmcnt(0) lgkmcnt(0)
	v_pk_fma_f32 v[0:1], v[0:1], v[8:9], v[4:5]
	v_pk_fma_f32 v[2:3], v[2:3], v[10:11], v[6:7]
	global_store_dwordx4 v[76:77], v[0:3], off offset:256
	s_waitcnt lgkmcnt(0)
	s_barrier
	s_cbranch_scc1 .LBB0_923

.Lg16_gu_k:
	s_add_i32 s8, s1, 2
	s_lshl_b32 s96, s8, 13
	s_add_i32 m0, vcc_lo, 16384
	v_lshl_add_u64 v[160:161], v[188:189], 0, s[96:97]
	global_load_lds_dwordx4 v[160:161], off
	global_load_lds_dwordx4 v[160:161], off offset:1024
	ds_read_b128 v[196:199], v246 offset:0
	ds_read_b128 v[200:203], v246 offset:1024
	ds_read_b128 v[204:207], v246 offset:2048
	ds_read_b128 v[242:245], v246 offset:3072
	s_add_i32 s8, s1, 2
	s_lshl_b32 s96, s8, 11
	v_lshl_add_u64 v[248:249], v[184:185], 0, s[96:97]
	v_lshl_add_u64 v[250:251], v[186:187], 0, s[96:97]
	s_waitcnt vmcnt(8) lgkmcnt(3)
	v_mfma_f32_16x16x32_bf16 v[112:115], v[128:131], v[196:199], v[112:115]
	v_mfma_f32_16x16x32_bf16 v[120:123], v[132:135], v[196:199], v[120:123]
	v_mfma_f32_16x16x32_bf16 v[80:83], v[136:139], v[196:199], v[80:83]
	v_mfma_f32_16x16x32_bf16 v[88:91], v[140:143], v[196:199], v[88:91]
	ds_read_b128 v[196:199], v246 offset:4096
	s_waitcnt lgkmcnt(3)
	v_mfma_f32_16x16x32_bf16 v[116:119], v[128:131], v[200:203], v[116:119]
	v_mfma_f32_16x16x32_bf16 v[124:127], v[132:135], v[200:203], v[124:127]
	v_mfma_f32_16x16x32_bf16 v[84:87], v[136:139], v[200:203], v[84:87]
	v_mfma_f32_16x16x32_bf16 v[92:95], v[140:143], v[200:203], v[92:95]
	ds_read_b128 v[200:203], v246 offset:5120
	s_waitcnt lgkmcnt(3)
	v_mfma_f32_16x16x32_bf16 v[96:99], v[128:131], v[204:207], v[96:99]
	v_mfma_f32_16x16x32_bf16 v[104:107], v[132:135], v[204:207], v[104:107]
	v_mfma_f32_16x16x32_bf16 v[64:67], v[136:139], v[204:207], v[64:67]
	v_mfma_f32_16x16x32_bf16 v[72:75], v[140:143], v[204:207], v[72:75]
	ds_read_b128 v[204:207], v246 offset:6144
	s_waitcnt lgkmcnt(3)
	v_mfma_f32_16x16x32_bf16 v[100:103], v[128:131], v[242:245], v[100:103]
	v_mfma_f32_16x16x32_bf16 v[108:111], v[132:135], v[242:245], v[108:111]
	v_mfma_f32_16x16x32_bf16 v[68:71], v[136:139], v[242:245], v[68:71]
	v_mfma_f32_16x16x32_bf16 v[76:79], v[140:143], v[242:245], v[76:79]
	ds_read_b128 v[242:245], v246 offset:7168
	s_waitcnt lgkmcnt(3)
	v_mfma_f32_16x16x32_bf16 v[48:51], v[128:131], v[196:199], v[48:51]
	v_mfma_f32_16x16x32_bf16 v[56:59], v[132:135], v[196:199], v[56:59]
	v_mfma_f32_16x16x32_bf16 v[16:19], v[136:139], v[196:199], v[16:19]
	v_mfma_f32_16x16x32_bf16 v[24:27], v[140:143], v[196:199], v[24:27]
	s_waitcnt lgkmcnt(2)
	v_mfma_f32_16x16x32_bf16 v[52:55], v[128:131], v[200:203], v[52:55]
	v_mfma_f32_16x16x32_bf16 v[60:63], v[132:135], v[200:203], v[60:63]
	v_mfma_f32_16x16x32_bf16 v[20:23], v[136:139], v[200:203], v[20:23]
	v_mfma_f32_16x16x32_bf16 v[28:31], v[140:143], v[200:203], v[28:31]
	s_waitcnt lgkmcnt(1)
	v_mfma_f32_16x16x32_bf16 v[32:35], v[128:131], v[204:207], v[32:35]
	v_mfma_f32_16x16x32_bf16 v[40:43], v[132:135], v[204:207], v[40:43]
	v_mfma_f32_16x16x32_bf16 v[0:3], v[136:139], v[204:207], v[0:3]
	v_mfma_f32_16x16x32_bf16 v[8:11], v[140:143], v[204:207], v[8:11]
	s_waitcnt lgkmcnt(0)
	v_mfma_f32_16x16x32_bf16 v[36:39], v[128:131], v[242:245], v[36:39]
	v_mfma_f32_16x16x32_bf16 v[44:47], v[132:135], v[242:245], v[44:47]
	v_mfma_f32_16x16x32_bf16 v[4:7], v[136:139], v[242:245], v[4:7]
	v_mfma_f32_16x16x32_bf16 v[12:15], v[140:143], v[242:245], v[12:15]
	global_load_dwordx4 v[128:131], v[248:249], off
	global_load_dwordx4 v[132:135], v[248:249], off offset:256
	global_load_dwordx4 v[136:139], v[250:251], off
	global_load_dwordx4 v[140:143], v[250:251], off offset:256
	s_waitcnt vmcnt(10)
	s_barrier
	s_add_i32 s8, s1, 3
	s_lshl_b32 s96, s8, 13
	s_mov_b32 m0, vcc_lo
	v_lshl_add_u64 v[160:161], v[188:189], 0, s[96:97]
	global_load_lds_dwordx4 v[160:161], off
	global_load_lds_dwordx4 v[160:161], off offset:1024
	ds_read_b128 v[196:199], v246 offset:8192
	ds_read_b128 v[200:203], v246 offset:9216
	ds_read_b128 v[204:207], v246 offset:10240
	ds_read_b128 v[242:245], v246 offset:11264
	s_add_i32 s8, s1, 3
	s_lshl_b32 s96, s8, 11
	v_lshl_add_u64 v[248:249], v[184:185], 0, s[96:97]
	v_lshl_add_u64 v[250:251], v[186:187], 0, s[96:97]
	s_waitcnt vmcnt(8) lgkmcnt(3)
	v_mfma_f32_16x16x32_bf16 v[112:115], v[144:147], v[196:199], v[112:115]
	v_mfma_f32_16x16x32_bf16 v[120:123], v[148:151], v[196:199], v[120:123]
	v_mfma_f32_16x16x32_bf16 v[80:83], v[152:155], v[196:199], v[80:83]
	v_mfma_f32_16x16x32_bf16 v[88:91], v[156:159], v[196:199], v[88:91]
	ds_read_b128 v[196:199], v246 offset:12288
	s_waitcnt lgkmcnt(3)
	v_mfma_f32_16x16x32_bf16 v[116:119], v[144:147], v[200:203], v[116:119]
	v_mfma_f32_16x16x32_bf16 v[124:127], v[148:151], v[200:203], v[124:127]
	v_mfma_f32_16x16x32_bf16 v[84:87], v[152:155], v[200:203], v[84:87]
	v_mfma_f32_16x16x32_bf16 v[92:95], v[156:159], v[200:203], v[92:95]
	ds_read_b128 v[200:203], v246 offset:13312
	s_waitcnt lgkmcnt(3)
	v_mfma_f32_16x16x32_bf16 v[96:99], v[144:147], v[204:207], v[96:99]
	v_mfma_f32_16x16x32_bf16 v[104:107], v[148:151], v[204:207], v[104:107]
	v_mfma_f32_16x16x32_bf16 v[64:67], v[152:155], v[204:207], v[64:67]
	v_mfma_f32_16x16x32_bf16 v[72:75], v[156:159], v[204:207], v[72:75]
	ds_read_b128 v[204:207], v246 offset:14336
	s_waitcnt lgkmcnt(3)
	v_mfma_f32_16x16x32_bf16 v[100:103], v[144:147], v[242:245], v[100:103]
	v_mfma_f32_16x16x32_bf16 v[108:111], v[148:151], v[242:245], v[108:111]
	v_mfma_f32_16x16x32_bf16 v[68:71], v[152:155], v[242:245], v[68:71]
	v_mfma_f32_16x16x32_bf16 v[76:79], v[156:159], v[242:245], v[76:79]
	ds_read_b128 v[242:245], v246 offset:15360
	s_waitcnt lgkmcnt(3)
	v_mfma_f32_16x16x32_bf16 v[48:51], v[144:147], v[196:199], v[48:51]
	v_mfma_f32_16x16x32_bf16 v[56:59], v[148:151], v[196:199], v[56:59]
	v_mfma_f32_16x16x32_bf16 v[16:19], v[152:155], v[196:199], v[16:19]
	v_mfma_f32_16x16x32_bf16 v[24:27], v[156:159], v[196:199], v[24:27]
	s_waitcnt lgkmcnt(2)
	v_mfma_f32_16x16x32_bf16 v[52:55], v[144:147], v[200:203], v[52:55]
	v_mfma_f32_16x16x32_bf16 v[60:63], v[148:151], v[200:203], v[60:63]
	v_mfma_f32_16x16x32_bf16 v[20:23], v[152:155], v[200:203], v[20:23]
	v_mfma_f32_16x16x32_bf16 v[28:31], v[156:159], v[200:203], v[28:31]
	s_waitcnt lgkmcnt(1)
	v_mfma_f32_16x16x32_bf16 v[32:35], v[144:147], v[204:207], v[32:35]
	v_mfma_f32_16x16x32_bf16 v[40:43], v[148:151], v[204:207], v[40:43]
	v_mfma_f32_16x16x32_bf16 v[0:3], v[152:155], v[204:207], v[0:3]
	v_mfma_f32_16x16x32_bf16 v[8:11], v[156:159], v[204:207], v[8:11]
	s_waitcnt lgkmcnt(0)
	v_mfma_f32_16x16x32_bf16 v[36:39], v[144:147], v[242:245], v[36:39]
	v_mfma_f32_16x16x32_bf16 v[44:47], v[148:151], v[242:245], v[44:47]
	v_mfma_f32_16x16x32_bf16 v[4:7], v[152:155], v[242:245], v[4:7]
	v_mfma_f32_16x16x32_bf16 v[12:15], v[156:159], v[242:245], v[12:15]
	global_load_dwordx4 v[144:147], v[248:249], off
	global_load_dwordx4 v[148:151], v[248:249], off offset:256
	global_load_dwordx4 v[152:155], v[250:251], off
	global_load_dwordx4 v[156:159], v[250:251], off offset:256
	s_waitcnt vmcnt(10)
	s_barrier
	s_add_i32 s8, s1, 4
	s_lshl_b32 s96, s8, 13
	s_add_i32 m0, vcc_lo, 8192
	v_lshl_add_u64 v[160:161], v[188:189], 0, s[96:97]
	global_load_lds_dwordx4 v[160:161], off
	global_load_lds_dwordx4 v[160:161], off offset:1024
	ds_read_b128 v[196:199], v246 offset:16384
	ds_read_b128 v[200:203], v246 offset:17408
	ds_read_b128 v[204:207], v246 offset:18432
	ds_read_b128 v[242:245], v246 offset:19456
	s_add_i32 s8, s1, 4
	s_lshl_b32 s96, s8, 11
	v_lshl_add_u64 v[248:249], v[184:185], 0, s[96:97]
	v_lshl_add_u64 v[250:251], v[186:187], 0, s[96:97]
	s_waitcnt vmcnt(8) lgkmcnt(3)
	v_mfma_f32_16x16x32_bf16 v[112:115], v[128:131], v[196:199], v[112:115]
	v_mfma_f32_16x16x32_bf16 v[120:123], v[132:135], v[196:199], v[120:123]
	v_mfma_f32_16x16x32_bf16 v[80:83], v[136:139], v[196:199], v[80:83]
	v_mfma_f32_16x16x32_bf16 v[88:91], v[140:143], v[196:199], v[88:91]
	ds_read_b128 v[196:199], v246 offset:20480
	s_waitcnt lgkmcnt(3)
	v_mfma_f32_16x16x32_bf16 v[116:119], v[128:131], v[200:203], v[116:119]
	v_mfma_f32_16x16x32_bf16 v[124:127], v[132:135], v[200:203], v[124:127]
	v_mfma_f32_16x16x32_bf16 v[84:87], v[136:139], v[200:203], v[84:87]
	v_mfma_f32_16x16x32_bf16 v[92:95], v[140:143], v[200:203], v[92:95]
	ds_read_b128 v[200:203], v246 offset:21504
	s_waitcnt lgkmcnt(3)
	v_mfma_f32_16x16x32_bf16 v[96:99], v[128:131], v[204:207], v[96:99]
	v_mfma_f32_16x16x32_bf16 v[104:107], v[132:135], v[204:207], v[104:107]
	v_mfma_f32_16x16x32_bf16 v[64:67], v[136:139], v[204:207], v[64:67]
	v_mfma_f32_16x16x32_bf16 v[72:75], v[140:143], v[204:207], v[72:75]
	ds_read_b128 v[204:207], v246 offset:22528
	s_waitcnt lgkmcnt(3)
	v_mfma_f32_16x16x32_bf16 v[100:103], v[128:131], v[242:245], v[100:103]
	v_mfma_f32_16x16x32_bf16 v[108:111], v[132:135], v[242:245], v[108:111]
	v_mfma_f32_16x16x32_bf16 v[68:71], v[136:139], v[242:245], v[68:71]
	v_mfma_f32_16x16x32_bf16 v[76:79], v[140:143], v[242:245], v[76:79]
	ds_read_b128 v[242:245], v246 offset:23552
	s_waitcnt lgkmcnt(3)
	v_mfma_f32_16x16x32_bf16 v[48:51], v[128:131], v[196:199], v[48:51]
	v_mfma_f32_16x16x32_bf16 v[56:59], v[132:135], v[196:199], v[56:59]
	v_mfma_f32_16x16x32_bf16 v[16:19], v[136:139], v[196:199], v[16:19]
	v_mfma_f32_16x16x32_bf16 v[24:27], v[140:143], v[196:199], v[24:27]
	s_waitcnt lgkmcnt(2)
	v_mfma_f32_16x16x32_bf16 v[52:55], v[128:131], v[200:203], v[52:55]
	v_mfma_f32_16x16x32_bf16 v[60:63], v[132:135], v[200:203], v[60:63]
	v_mfma_f32_16x16x32_bf16 v[20:23], v[136:139], v[200:203], v[20:23]
	v_mfma_f32_16x16x32_bf16 v[28:31], v[140:143], v[200:203], v[28:31]
	s_waitcnt lgkmcnt(1)
	v_mfma_f32_16x16x32_bf16 v[32:35], v[128:131], v[204:207], v[32:35]
	v_mfma_f32_16x16x32_bf16 v[40:43], v[132:135], v[204:207], v[40:43]
	v_mfma_f32_16x16x32_bf16 v[0:3], v[136:139], v[204:207], v[0:3]
	v_mfma_f32_16x16x32_bf16 v[8:11], v[140:143], v[204:207], v[8:11]
	s_waitcnt lgkmcnt(0)
	v_mfma_f32_16x16x32_bf16 v[36:39], v[128:131], v[242:245], v[36:39]
	v_mfma_f32_16x16x32_bf16 v[44:47], v[132:135], v[242:245], v[44:47]
	v_mfma_f32_16x16x32_bf16 v[4:7], v[136:139], v[242:245], v[4:7]
	v_mfma_f32_16x16x32_bf16 v[12:15], v[140:143], v[242:245], v[12:15]
	global_load_dwordx4 v[128:131], v[248:249], off
	global_load_dwordx4 v[132:135], v[248:249], off offset:256
	global_load_dwordx4 v[136:139], v[250:251], off
	global_load_dwordx4 v[140:143], v[250:251], off offset:256
	s_waitcnt vmcnt(10)
	s_barrier
	s_add_i32 s8, s1, 5
	s_lshl_b32 s96, s8, 13
	s_add_i32 m0, vcc_lo, 16384
	v_lshl_add_u64 v[160:161], v[188:189], 0, s[96:97]
	global_load_lds_dwordx4 v[160:161], off
	global_load_lds_dwordx4 v[160:161], off offset:1024
	ds_read_b128 v[196:199], v246 offset:0
	ds_read_b128 v[200:203], v246 offset:1024
	ds_read_b128 v[204:207], v246 offset:2048
	ds_read_b128 v[242:245], v246 offset:3072
	s_add_i32 s8, s1, 5
	s_lshl_b32 s96, s8, 11
	v_lshl_add_u64 v[248:249], v[184:185], 0, s[96:97]
	v_lshl_add_u64 v[250:251], v[186:187], 0, s[96:97]
	s_waitcnt vmcnt(8) lgkmcnt(3)
	v_mfma_f32_16x16x32_bf16 v[112:115], v[144:147], v[196:199], v[112:115]
	v_mfma_f32_16x16x32_bf16 v[120:123], v[148:151], v[196:199], v[120:123]
	v_mfma_f32_16x16x32_bf16 v[80:83], v[152:155], v[196:199], v[80:83]
	v_mfma_f32_16x16x32_bf16 v[88:91], v[156:159], v[196:199], v[88:91]
	ds_read_b128 v[196:199], v246 offset:4096
	s_waitcnt lgkmcnt(3)
	v_mfma_f32_16x16x32_bf16 v[116:119], v[144:147], v[200:203], v[116:119]
	v_mfma_f32_16x16x32_bf16 v[124:127], v[148:151], v[200:203], v[124:127]
	v_mfma_f32_16x16x32_bf16 v[84:87], v[152:155], v[200:203], v[84:87]
	v_mfma_f32_16x16x32_bf16 v[92:95], v[156:159], v[200:203], v[92:95]
	ds_read_b128 v[200:203], v246 offset:5120
	s_waitcnt lgkmcnt(3)
	v_mfma_f32_16x16x32_bf16 v[96:99], v[144:147], v[204:207], v[96:99]
	v_mfma_f32_16x16x32_bf16 v[104:107], v[148:151], v[204:207], v[104:107]
	v_mfma_f32_16x16x32_bf16 v[64:67], v[152:155], v[204:207], v[64:67]
	v_mfma_f32_16x16x32_bf16 v[72:75], v[156:159], v[204:207], v[72:75]
	ds_read_b128 v[204:207], v246 offset:6144
	s_waitcnt lgkmcnt(3)
	v_mfma_f32_16x16x32_bf16 v[100:103], v[144:147], v[242:245], v[100:103]
	v_mfma_f32_16x16x32_bf16 v[108:111], v[148:151], v[242:245], v[108:111]
	v_mfma_f32_16x16x32_bf16 v[68:71], v[152:155], v[242:245], v[68:71]
	v_mfma_f32_16x16x32_bf16 v[76:79], v[156:159], v[242:245], v[76:79]
	ds_read_b128 v[242:245], v246 offset:7168
	s_waitcnt lgkmcnt(3)
	v_mfma_f32_16x16x32_bf16 v[48:51], v[144:147], v[196:199], v[48:51]
	v_mfma_f32_16x16x32_bf16 v[56:59], v[148:151], v[196:199], v[56:59]
	v_mfma_f32_16x16x32_bf16 v[16:19], v[152:155], v[196:199], v[16:19]
	v_mfma_f32_16x16x32_bf16 v[24:27], v[156:159], v[196:199], v[24:27]
	s_waitcnt lgkmcnt(2)
	v_mfma_f32_16x16x32_bf16 v[52:55], v[144:147], v[200:203], v[52:55]
	v_mfma_f32_16x16x32_bf16 v[60:63], v[148:151], v[200:203], v[60:63]
	v_mfma_f32_16x16x32_bf16 v[20:23], v[152:155], v[200:203], v[20:23]
	v_mfma_f32_16x16x32_bf16 v[28:31], v[156:159], v[200:203], v[28:31]
	s_waitcnt lgkmcnt(1)
	v_mfma_f32_16x16x32_bf16 v[32:35], v[144:147], v[204:207], v[32:35]
	v_mfma_f32_16x16x32_bf16 v[40:43], v[148:151], v[204:207], v[40:43]
	v_mfma_f32_16x16x32_bf16 v[0:3], v[152:155], v[204:207], v[0:3]
	v_mfma_f32_16x16x32_bf16 v[8:11], v[156:159], v[204:207], v[8:11]
	s_waitcnt lgkmcnt(0)
	v_mfma_f32_16x16x32_bf16 v[36:39], v[144:147], v[242:245], v[36:39]
	v_mfma_f32_16x16x32_bf16 v[44:47], v[148:151], v[242:245], v[44:47]
	v_mfma_f32_16x16x32_bf16 v[4:7], v[152:155], v[242:245], v[4:7]
	v_mfma_f32_16x16x32_bf16 v[12:15], v[156:159], v[242:245], v[12:15]
	global_load_dwordx4 v[144:147], v[248:249], off
	global_load_dwordx4 v[148:151], v[248:249], off offset:256
	global_load_dwordx4 v[152:155], v[250:251], off
	global_load_dwordx4 v[156:159], v[250:251], off offset:256
	s_waitcnt vmcnt(10)
	s_barrier
	s_add_i32 s8, s1, 6
	s_lshl_b32 s96, s8, 13
	s_mov_b32 m0, vcc_lo
	v_lshl_add_u64 v[160:161], v[188:189], 0, s[96:97]
	global_load_lds_dwordx4 v[160:161], off
	global_load_lds_dwordx4 v[160:161], off offset:1024
	ds_read_b128 v[196:199], v246 offset:8192
	ds_read_b128 v[200:203], v246 offset:9216
	ds_read_b128 v[204:207], v246 offset:10240
	ds_read_b128 v[242:245], v246 offset:11264
	s_add_i32 s8, s1, 6
	s_lshl_b32 s96, s8, 11
	v_lshl_add_u64 v[248:249], v[184:185], 0, s[96:97]
	v_lshl_add_u64 v[250:251], v[186:187], 0, s[96:97]
	s_waitcnt vmcnt(8) lgkmcnt(3)
	v_mfma_f32_16x16x32_bf16 v[112:115], v[128:131], v[196:199], v[112:115]
	v_mfma_f32_16x16x32_bf16 v[120:123], v[132:135], v[196:199], v[120:123]
	v_mfma_f32_16x16x32_bf16 v[80:83], v[136:139], v[196:199], v[80:83]
	v_mfma_f32_16x16x32_bf16 v[88:91], v[140:143], v[196:199], v[88:91]
	ds_read_b128 v[196:199], v246 offset:12288
	s_waitcnt lgkmcnt(3)
	v_mfma_f32_16x16x32_bf16 v[116:119], v[128:131], v[200:203], v[116:119]
	v_mfma_f32_16x16x32_bf16 v[124:127], v[132:135], v[200:203], v[124:127]
	v_mfma_f32_16x16x32_bf16 v[84:87], v[136:139], v[200:203], v[84:87]
	v_mfma_f32_16x16x32_bf16 v[92:95], v[140:143], v[200:203], v[92:95]
	ds_read_b128 v[200:203], v246 offset:13312
	s_waitcnt lgkmcnt(3)
	v_mfma_f32_16x16x32_bf16 v[96:99], v[128:131], v[204:207], v[96:99]
	v_mfma_f32_16x16x32_bf16 v[104:107], v[132:135], v[204:207], v[104:107]
	v_mfma_f32_16x16x32_bf16 v[64:67], v[136:139], v[204:207], v[64:67]
	v_mfma_f32_16x16x32_bf16 v[72:75], v[140:143], v[204:207], v[72:75]
	ds_read_b128 v[204:207], v246 offset:14336
	s_waitcnt lgkmcnt(3)
	v_mfma_f32_16x16x32_bf16 v[100:103], v[128:131], v[242:245], v[100:103]
	v_mfma_f32_16x16x32_bf16 v[108:111], v[132:135], v[242:245], v[108:111]
	v_mfma_f32_16x16x32_bf16 v[68:71], v[136:139], v[242:245], v[68:71]
	v_mfma_f32_16x16x32_bf16 v[76:79], v[140:143], v[242:245], v[76:79]
	ds_read_b128 v[242:245], v246 offset:15360
	s_waitcnt lgkmcnt(3)
	v_mfma_f32_16x16x32_bf16 v[48:51], v[128:131], v[196:199], v[48:51]
	v_mfma_f32_16x16x32_bf16 v[56:59], v[132:135], v[196:199], v[56:59]
	v_mfma_f32_16x16x32_bf16 v[16:19], v[136:139], v[196:199], v[16:19]
	v_mfma_f32_16x16x32_bf16 v[24:27], v[140:143], v[196:199], v[24:27]
	s_waitcnt lgkmcnt(2)
	v_mfma_f32_16x16x32_bf16 v[52:55], v[128:131], v[200:203], v[52:55]
	v_mfma_f32_16x16x32_bf16 v[60:63], v[132:135], v[200:203], v[60:63]
	v_mfma_f32_16x16x32_bf16 v[20:23], v[136:139], v[200:203], v[20:23]
	v_mfma_f32_16x16x32_bf16 v[28:31], v[140:143], v[200:203], v[28:31]
	s_waitcnt lgkmcnt(1)
	v_mfma_f32_16x16x32_bf16 v[32:35], v[128:131], v[204:207], v[32:35]
	v_mfma_f32_16x16x32_bf16 v[40:43], v[132:135], v[204:207], v[40:43]
	v_mfma_f32_16x16x32_bf16 v[0:3], v[136:139], v[204:207], v[0:3]
	v_mfma_f32_16x16x32_bf16 v[8:11], v[140:143], v[204:207], v[8:11]
	s_waitcnt lgkmcnt(0)
	v_mfma_f32_16x16x32_bf16 v[36:39], v[128:131], v[242:245], v[36:39]
	v_mfma_f32_16x16x32_bf16 v[44:47], v[132:135], v[242:245], v[44:47]
	v_mfma_f32_16x16x32_bf16 v[4:7], v[136:139], v[242:245], v[4:7]
	v_mfma_f32_16x16x32_bf16 v[12:15], v[140:143], v[242:245], v[12:15]
	global_load_dwordx4 v[128:131], v[248:249], off
	global_load_dwordx4 v[132:135], v[248:249], off offset:256
	global_load_dwordx4 v[136:139], v[250:251], off
	global_load_dwordx4 v[140:143], v[250:251], off offset:256
	s_waitcnt vmcnt(10)
	s_barrier
	s_add_i32 s8, s1, 7
	s_lshl_b32 s96, s8, 13
	s_add_i32 m0, vcc_lo, 8192
	v_lshl_add_u64 v[160:161], v[188:189], 0, s[96:97]
	global_load_lds_dwordx4 v[160:161], off
	global_load_lds_dwordx4 v[160:161], off offset:1024
	ds_read_b128 v[196:199], v246 offset:16384
	ds_read_b128 v[200:203], v246 offset:17408
	ds_read_b128 v[204:207], v246 offset:18432
	ds_read_b128 v[242:245], v246 offset:19456
	s_add_i32 s8, s1, 7
	s_lshl_b32 s96, s8, 11
	v_lshl_add_u64 v[248:249], v[184:185], 0, s[96:97]
	v_lshl_add_u64 v[250:251], v[186:187], 0, s[96:97]
	s_waitcnt vmcnt(8) lgkmcnt(3)
	v_mfma_f32_16x16x32_bf16 v[112:115], v[144:147], v[196:199], v[112:115]
	v_mfma_f32_16x16x32_bf16 v[120:123], v[148:151], v[196:199], v[120:123]
	v_mfma_f32_16x16x32_bf16 v[80:83], v[152:155], v[196:199], v[80:83]
	v_mfma_f32_16x16x32_bf16 v[88:91], v[156:159], v[196:199], v[88:91]
	ds_read_b128 v[196:199], v246 offset:20480
	s_waitcnt lgkmcnt(3)
	v_mfma_f32_16x16x32_bf16 v[116:119], v[144:147], v[200:203], v[116:119]
	v_mfma_f32_16x16x32_bf16 v[124:127], v[148:151], v[200:203], v[124:127]
	v_mfma_f32_16x16x32_bf16 v[84:87], v[152:155], v[200:203], v[84:87]
	v_mfma_f32_16x16x32_bf16 v[92:95], v[156:159], v[200:203], v[92:95]
	ds_read_b128 v[200:203], v246 offset:21504
	s_waitcnt lgkmcnt(3)
	v_mfma_f32_16x16x32_bf16 v[96:99], v[144:147], v[204:207], v[96:99]
	v_mfma_f32_16x16x32_bf16 v[104:107], v[148:151], v[204:207], v[104:107]
	v_mfma_f32_16x16x32_bf16 v[64:67], v[152:155], v[204:207], v[64:67]
	v_mfma_f32_16x16x32_bf16 v[72:75], v[156:159], v[204:207], v[72:75]
	ds_read_b128 v[204:207], v246 offset:22528
	s_waitcnt lgkmcnt(3)
	v_mfma_f32_16x16x32_bf16 v[100:103], v[144:147], v[242:245], v[100:103]
	v_mfma_f32_16x16x32_bf16 v[108:111], v[148:151], v[242:245], v[108:111]
	v_mfma_f32_16x16x32_bf16 v[68:71], v[152:155], v[242:245], v[68:71]
	v_mfma_f32_16x16x32_bf16 v[76:79], v[156:159], v[242:245], v[76:79]
	ds_read_b128 v[242:245], v246 offset:23552
	s_waitcnt lgkmcnt(3)
	v_mfma_f32_16x16x32_bf16 v[48:51], v[144:147], v[196:199], v[48:51]
	v_mfma_f32_16x16x32_bf16 v[56:59], v[148:151], v[196:199], v[56:59]
	v_mfma_f32_16x16x32_bf16 v[16:19], v[152:155], v[196:199], v[16:19]
	v_mfma_f32_16x16x32_bf16 v[24:27], v[156:159], v[196:199], v[24:27]
	s_waitcnt lgkmcnt(2)
	v_mfma_f32_16x16x32_bf16 v[52:55], v[144:147], v[200:203], v[52:55]
	v_mfma_f32_16x16x32_bf16 v[60:63], v[148:151], v[200:203], v[60:63]
	v_mfma_f32_16x16x32_bf16 v[20:23], v[152:155], v[200:203], v[20:23]
	v_mfma_f32_16x16x32_bf16 v[28:31], v[156:159], v[200:203], v[28:31]
	s_waitcnt lgkmcnt(1)
	v_mfma_f32_16x16x32_bf16 v[32:35], v[144:147], v[204:207], v[32:35]
	v_mfma_f32_16x16x32_bf16 v[40:43], v[148:151], v[204:207], v[40:43]
	v_mfma_f32_16x16x32_bf16 v[0:3], v[152:155], v[204:207], v[0:3]
	v_mfma_f32_16x16x32_bf16 v[8:11], v[156:159], v[204:207], v[8:11]
	s_waitcnt lgkmcnt(0)
	v_mfma_f32_16x16x32_bf16 v[36:39], v[144:147], v[242:245], v[36:39]
	v_mfma_f32_16x16x32_bf16 v[44:47], v[148:151], v[242:245], v[44:47]
	v_mfma_f32_16x16x32_bf16 v[4:7], v[152:155], v[242:245], v[4:7]
	v_mfma_f32_16x16x32_bf16 v[12:15], v[156:159], v[242:245], v[12:15]
	global_load_dwordx4 v[144:147], v[248:249], off
	global_load_dwordx4 v[148:151], v[248:249], off offset:256
	global_load_dwordx4 v[152:155], v[250:251], off
	global_load_dwordx4 v[156:159], v[250:251], off offset:256
	s_waitcnt vmcnt(10)
	s_barrier
	s_add_i32 s1, s1, 6
	s_cmp_lt_u32 s1, 30
	s_cbranch_scc1 .Lg16_gu_k
	ds_read_b128 v[196:199], v246 offset:0
	ds_read_b128 v[200:203], v246 offset:1024
	ds_read_b128 v[204:207], v246 offset:2048
	ds_read_b128 v[242:245], v246 offset:3072
	s_waitcnt vmcnt(6) lgkmcnt(3)
	v_mfma_f32_16x16x32_bf16 v[112:115], v[128:131], v[196:199], v[112:115]
	v_mfma_f32_16x16x32_bf16 v[120:123], v[132:135], v[196:199], v[120:123]
	v_mfma_f32_16x16x32_bf16 v[80:83], v[136:139], v[196:199], v[80:83]
	v_mfma_f32_16x16x32_bf16 v[88:91], v[140:143], v[196:199], v[88:91]
	ds_read_b128 v[196:199], v246 offset:4096
	s_waitcnt lgkmcnt(3)
	v_mfma_f32_16x16x32_bf16 v[116:119], v[128:131], v[200:203], v[116:119]
	v_mfma_f32_16x16x32_bf16 v[124:127], v[132:135], v[200:203], v[124:127]
	v_mfma_f32_16x16x32_bf16 v[84:87], v[136:139], v[200:203], v[84:87]
	v_mfma_f32_16x16x32_bf16 v[92:95], v[140:143], v[200:203], v[92:95]
	ds_read_b128 v[200:203], v246 offset:5120
	s_waitcnt lgkmcnt(3)
	v_mfma_f32_16x16x32_bf16 v[96:99], v[128:131], v[204:207], v[96:99]
	v_mfma_f32_16x16x32_bf16 v[104:107], v[132:135], v[204:207], v[104:107]
	v_mfma_f32_16x16x32_bf16 v[64:67], v[136:139], v[204:207], v[64:67]
	v_mfma_f32_16x16x32_bf16 v[72:75], v[140:143], v[204:207], v[72:75]
	ds_read_b128 v[204:207], v246 offset:6144
	s_waitcnt lgkmcnt(3)
	v_mfma_f32_16x16x32_bf16 v[100:103], v[128:131], v[242:245], v[100:103]
	v_mfma_f32_16x16x32_bf16 v[108:111], v[132:135], v[242:245], v[108:111]
	v_mfma_f32_16x16x32_bf16 v[68:71], v[136:139], v[242:245], v[68:71]
	v_mfma_f32_16x16x32_bf16 v[76:79], v[140:143], v[242:245], v[76:79]
	ds_read_b128 v[242:245], v246 offset:7168
	s_waitcnt lgkmcnt(3)
	v_mfma_f32_16x16x32_bf16 v[48:51], v[128:131], v[196:199], v[48:51]
	v_mfma_f32_16x16x32_bf16 v[56:59], v[132:135], v[196:199], v[56:59]
	v_mfma_f32_16x16x32_bf16 v[16:19], v[136:139], v[196:199], v[16:19]
	v_mfma_f32_16x16x32_bf16 v[24:27], v[140:143], v[196:199], v[24:27]
	s_waitcnt lgkmcnt(2)
	v_mfma_f32_16x16x32_bf16 v[52:55], v[128:131], v[200:203], v[52:55]
	v_mfma_f32_16x16x32_bf16 v[60:63], v[132:135], v[200:203], v[60:63]
	v_mfma_f32_16x16x32_bf16 v[20:23], v[136:139], v[200:203], v[20:23]
	v_mfma_f32_16x16x32_bf16 v[28:31], v[140:143], v[200:203], v[28:31]
	s_waitcnt lgkmcnt(1)
	v_mfma_f32_16x16x32_bf16 v[32:35], v[128:131], v[204:207], v[32:35]
	v_mfma_f32_16x16x32_bf16 v[40:43], v[132:135], v[204:207], v[40:43]
	v_mfma_f32_16x16x32_bf16 v[0:3], v[136:139], v[204:207], v[0:3]
	v_mfma_f32_16x16x32_bf16 v[8:11], v[140:143], v[204:207], v[8:11]
	s_waitcnt lgkmcnt(0)
	v_mfma_f32_16x16x32_bf16 v[36:39], v[128:131], v[242:245], v[36:39]
	v_mfma_f32_16x16x32_bf16 v[44:47], v[132:135], v[242:245], v[44:47]
	v_mfma_f32_16x16x32_bf16 v[4:7], v[136:139], v[242:245], v[4:7]
	v_mfma_f32_16x16x32_bf16 v[12:15], v[140:143], v[242:245], v[12:15]
	s_waitcnt vmcnt(4)
	s_barrier
	ds_read_b128 v[196:199], v246 offset:8192
	ds_read_b128 v[200:203], v246 offset:9216
	ds_read_b128 v[204:207], v246 offset:10240
	ds_read_b128 v[242:245], v246 offset:11264
	s_waitcnt vmcnt(0) lgkmcnt(3)
	v_mfma_f32_16x16x32_bf16 v[112:115], v[144:147], v[196:199], v[112:115]
	v_mfma_f32_16x16x32_bf16 v[120:123], v[148:151], v[196:199], v[120:123]
	v_mfma_f32_16x16x32_bf16 v[80:83], v[152:155], v[196:199], v[80:83]
	v_mfma_f32_16x16x32_bf16 v[88:91], v[156:159], v[196:199], v[88:91]
	ds_read_b128 v[196:199], v246 offset:12288
	s_waitcnt lgkmcnt(3)
	v_mfma_f32_16x16x32_bf16 v[116:119], v[144:147], v[200:203], v[116:119]
	v_mfma_f32_16x16x32_bf16 v[124:127], v[148:151], v[200:203], v[124:127]
	v_mfma_f32_16x16x32_bf16 v[84:87], v[152:155], v[200:203], v[84:87]
	v_mfma_f32_16x16x32_bf16 v[92:95], v[156:159], v[200:203], v[92:95]
	ds_read_b128 v[200:203], v246 offset:13312
	s_waitcnt lgkmcnt(3)
	v_mfma_f32_16x16x32_bf16 v[96:99], v[144:147], v[204:207], v[96:99]
	v_mfma_f32_16x16x32_bf16 v[104:107], v[148:151], v[204:207], v[104:107]
	v_mfma_f32_16x16x32_bf16 v[64:67], v[152:155], v[204:207], v[64:67]
	v_mfma_f32_16x16x32_bf16 v[72:75], v[156:159], v[204:207], v[72:75]
	ds_read_b128 v[204:207], v246 offset:14336
	s_waitcnt lgkmcnt(3)
	v_mfma_f32_16x16x32_bf16 v[100:103], v[144:147], v[242:245], v[100:103]
	v_mfma_f32_16x16x32_bf16 v[108:111], v[148:151], v[242:245], v[108:111]
	v_mfma_f32_16x16x32_bf16 v[68:71], v[152:155], v[242:245], v[68:71]
	v_mfma_f32_16x16x32_bf16 v[76:79], v[156:159], v[242:245], v[76:79]
	ds_read_b128 v[242:245], v246 offset:15360
	v_permlane16_swap_b32_e32 v112, v116
	v_permlane16_swap_b32_e32 v113, v117
	v_permlane16_swap_b32_e32 v114, v118
	v_permlane16_swap_b32_e32 v115, v119
	v_permlane16_swap_b32_e32 v120, v124
	v_permlane16_swap_b32_e32 v121, v125
	v_permlane16_swap_b32_e32 v122, v126
	v_permlane16_swap_b32_e32 v123, v127
	v_permlane16_swap_b32_e32 v80, v84
	v_permlane16_swap_b32_e32 v81, v85
	v_permlane16_swap_b32_e32 v82, v86
	v_permlane16_swap_b32_e32 v83, v87
	v_permlane16_swap_b32_e32 v88, v92
	v_permlane16_swap_b32_e32 v89, v93
	v_permlane16_swap_b32_e32 v90, v94
	v_permlane16_swap_b32_e32 v91, v95
	v_permlane32_swap_b32_e32 v112, v116
	v_permlane32_swap_b32_e32 v113, v117
	v_permlane32_swap_b32_e32 v114, v118
	v_permlane32_swap_b32_e32 v115, v119
	v_permlane32_swap_b32_e32 v120, v124
	v_permlane32_swap_b32_e32 v121, v125
	v_permlane32_swap_b32_e32 v122, v126
	v_permlane32_swap_b32_e32 v123, v127
	v_permlane32_swap_b32_e32 v80, v84
	v_permlane32_swap_b32_e32 v81, v85
	v_permlane32_swap_b32_e32 v82, v86
	v_permlane32_swap_b32_e32 v83, v87
	v_permlane32_swap_b32_e32 v88, v92
	v_permlane32_swap_b32_e32 v89, v93
	v_permlane32_swap_b32_e32 v90, v94
	v_permlane32_swap_b32_e32 v91, v95
	s_waitcnt lgkmcnt(3)
	v_mfma_f32_16x16x32_bf16 v[48:51], v[144:147], v[196:199], v[48:51]
	v_mfma_f32_16x16x32_bf16 v[56:59], v[148:151], v[196:199], v[56:59]
	v_mfma_f32_16x16x32_bf16 v[16:19], v[152:155], v[196:199], v[16:19]
	v_mfma_f32_16x16x32_bf16 v[24:27], v[156:159], v[196:199], v[24:27]
	s_waitcnt lgkmcnt(2)
	v_mfma_f32_16x16x32_bf16 v[52:55], v[144:147], v[200:203], v[52:55]
	v_mfma_f32_16x16x32_bf16 v[60:63], v[148:151], v[200:203], v[60:63]
	v_mfma_f32_16x16x32_bf16 v[20:23], v[152:155], v[200:203], v[20:23]
	v_mfma_f32_16x16x32_bf16 v[28:31], v[156:159], v[200:203], v[28:31]
	v_permlane16_swap_b32_e32 v96, v100
	v_permlane16_swap_b32_e32 v97, v101
	v_permlane16_swap_b32_e32 v98, v102
	v_permlane16_swap_b32_e32 v99, v103
	v_permlane16_swap_b32_e32 v104, v108
	v_permlane16_swap_b32_e32 v105, v109
	v_permlane16_swap_b32_e32 v106, v110
	v_permlane16_swap_b32_e32 v107, v111
	v_permlane16_swap_b32_e32 v64, v68
	v_permlane16_swap_b32_e32 v65, v69
	v_permlane16_swap_b32_e32 v66, v70
	v_permlane16_swap_b32_e32 v67, v71
	v_permlane16_swap_b32_e32 v72, v76
	v_permlane16_swap_b32_e32 v73, v77
	v_permlane16_swap_b32_e32 v74, v78
	v_permlane16_swap_b32_e32 v75, v79
	v_permlane32_swap_b32_e32 v96, v100
	v_permlane32_swap_b32_e32 v97, v101
	v_permlane32_swap_b32_e32 v98, v102
	v_permlane32_swap_b32_e32 v99, v103
	v_permlane32_swap_b32_e32 v104, v108
	v_permlane32_swap_b32_e32 v105, v109
	v_permlane32_swap_b32_e32 v106, v110
	v_permlane32_swap_b32_e32 v107, v111
	v_permlane32_swap_b32_e32 v64, v68
	v_permlane32_swap_b32_e32 v65, v69
	v_permlane32_swap_b32_e32 v66, v70
	v_permlane32_swap_b32_e32 v67, v71
	v_permlane32_swap_b32_e32 v72, v76
	v_permlane32_swap_b32_e32 v73, v77
	v_permlane32_swap_b32_e32 v74, v78
	v_permlane32_swap_b32_e32 v75, v79
	s_waitcnt lgkmcnt(1)
	v_mfma_f32_16x16x32_bf16 v[32:35], v[144:147], v[204:207], v[32:35]
	v_mfma_f32_16x16x32_bf16 v[40:43], v[148:151], v[204:207], v[40:43]
	v_mfma_f32_16x16x32_bf16 v[0:3], v[152:155], v[204:207], v[0:3]
	v_mfma_f32_16x16x32_bf16 v[8:11], v[156:159], v[204:207], v[8:11]
	s_waitcnt lgkmcnt(0)
	v_mfma_f32_16x16x32_bf16 v[36:39], v[144:147], v[242:245], v[36:39]
	v_mfma_f32_16x16x32_bf16 v[44:47], v[148:151], v[242:245], v[44:47]
	v_mfma_f32_16x16x32_bf16 v[4:7], v[152:155], v[242:245], v[4:7]
	v_mfma_f32_16x16x32_bf16 v[12:15], v[156:159], v[242:245], v[12:15]
	v_permlane16_swap_b32_e32 v48, v52
	v_permlane16_swap_b32_e32 v49, v53
	v_permlane16_swap_b32_e32 v50, v54
	v_permlane16_swap_b32_e32 v51, v55
	v_permlane16_swap_b32_e32 v56, v60
	v_permlane16_swap_b32_e32 v57, v61
	v_permlane16_swap_b32_e32 v58, v62
	v_permlane16_swap_b32_e32 v59, v63
	v_permlane16_swap_b32_e32 v16, v20
	v_permlane16_swap_b32_e32 v17, v21
	v_permlane16_swap_b32_e32 v18, v22
	v_permlane16_swap_b32_e32 v19, v23
	v_permlane16_swap_b32_e32 v24, v28
	v_permlane16_swap_b32_e32 v25, v29
	v_permlane16_swap_b32_e32 v26, v30
	v_permlane16_swap_b32_e32 v27, v31
	v_permlane32_swap_b32_e32 v48, v52
	v_permlane32_swap_b32_e32 v49, v53
	v_permlane32_swap_b32_e32 v50, v54
	v_permlane32_swap_b32_e32 v51, v55
	v_permlane32_swap_b32_e32 v56, v60
	v_permlane32_swap_b32_e32 v57, v61
	v_permlane32_swap_b32_e32 v58, v62
	v_permlane32_swap_b32_e32 v59, v63
	v_permlane32_swap_b32_e32 v16, v20
	v_permlane32_swap_b32_e32 v17, v21
	v_permlane32_swap_b32_e32 v18, v22
	v_permlane32_swap_b32_e32 v19, v23
	v_permlane32_swap_b32_e32 v24, v28
	v_permlane32_swap_b32_e32 v25, v29
	v_permlane32_swap_b32_e32 v26, v30
	v_permlane32_swap_b32_e32 v27, v31
	s_barrier
	s_nop 7
	v_permlane16_swap_b32_e32 v32, v36
	v_permlane16_swap_b32_e32 v33, v37
	v_permlane16_swap_b32_e32 v34, v38
	v_permlane16_swap_b32_e32 v35, v39
	v_permlane16_swap_b32_e32 v40, v44
	v_permlane16_swap_b32_e32 v41, v45
	v_permlane16_swap_b32_e32 v42, v46
	v_permlane16_swap_b32_e32 v43, v47
	v_permlane16_swap_b32_e32 v0, v4
	v_permlane16_swap_b32_e32 v1, v5
	v_permlane16_swap_b32_e32 v2, v6
	v_permlane16_swap_b32_e32 v3, v7
	v_permlane16_swap_b32_e32 v8, v12
	v_permlane16_swap_b32_e32 v9, v13
	v_permlane16_swap_b32_e32 v10, v14
	v_permlane16_swap_b32_e32 v11, v15
	v_permlane32_swap_b32_e32 v32, v36
	v_permlane32_swap_b32_e32 v33, v37
	v_permlane32_swap_b32_e32 v34, v38
	v_permlane32_swap_b32_e32 v35, v39
	v_permlane32_swap_b32_e32 v40, v44
	v_permlane32_swap_b32_e32 v41, v45
	v_permlane32_swap_b32_e32 v42, v46
	v_permlane32_swap_b32_e32 v43, v47
	v_permlane32_swap_b32_e32 v0, v4
	v_permlane32_swap_b32_e32 v1, v5
	v_permlane32_swap_b32_e32 v2, v6
	v_permlane32_swap_b32_e32 v3, v7
	v_permlane32_swap_b32_e32 v8, v12
	v_permlane32_swap_b32_e32 v9, v13
	v_permlane32_swap_b32_e32 v10, v14
	v_permlane32_swap_b32_e32 v11, v15
	s_waitcnt vmcnt(0)
	s_waitcnt vmcnt(0)
	v_mul_f32_e32 v133, 0xbfb8aa3b, v112
	v_exp_f32_e32 v133, v133
	s_movk_i32 s1, 0x2400
	v_mul_lo_u32 v128, v238, s1
	v_lshl_or_b32 v131, s0, 6, v181
	v_add_f32_e32 v133, 1.0, v133
	v_lshl_or_b32 v132, v239, 1, v128
	v_and_b32_e32 v129, 0xffffffc0, v237
	v_lshl_or_b32 v128, v181, 1, v128
	v_rcp_f32_e32 v135, v133
	s_nop 0
	v_mul_f32_e32 v112, v112, v135
	v_mul_f32_e32 v96, v96, v112
	v_cvt_pk_bf16_f32 v112, v96, s0
	s_movk_i32 s0, 0x240
	v_mad_u32_u24 v96, v183, s0, v132
	ds_write_b16 v96, v112
	v_mul_f32_e32 v112, 0xbfb8aa3b, v113
	v_exp_f32_e32 v112, v112
	v_lshl_add_u32 v130, s7, 8, v129
	v_lshrrev_b32_e32 v129, 2, v240
	v_mad_u32_u24 v128, v129, s42, v128
	v_add_f32_e32 v112, 1.0, v112
	v_rcp_f32_e32 v133, v112
	s_nop 0
	v_mul_f32_e32 v112, v113, v133
	v_mul_f32_e32 v97, v97, v112
	v_cvt_pk_bf16_f32 v97, v97, s0
	ds_write_b16 v96, v97 offset:144
	v_mul_f32_e32 v97, 0xbfb8aa3b, v114
	v_exp_f32_e32 v97, v97
	s_nop 0
	v_add_f32_e32 v97, 1.0, v97
	v_rcp_f32_e32 v113, v97
	s_nop 0
	v_mul_f32_e32 v97, v114, v113
	v_mul_f32_e32 v97, v98, v97
	v_cvt_pk_bf16_f32 v97, v97, s0
	ds_write_b16 v96, v97 offset:288
	v_mul_f32_e32 v97, 0xbfb8aa3b, v115
	v_exp_f32_e32 v97, v97
	s_nop 0
	v_add_f32_e32 v97, 1.0, v97
	v_rcp_f32_e32 v112, v97
	s_nop 0
	v_mul_f32_e32 v97, v115, v112
	v_mul_f32_e32 v97, v99, v97
	v_cvt_pk_bf16_f32 v97, v97, s0
	ds_write_b16 v96, v97 offset:432
	v_mul_f32_e32 v97, 0xbfb8aa3b, v116
	v_exp_f32_e32 v97, v97
	s_nop 0
	v_add_f32_e32 v97, 1.0, v97
	v_rcp_f32_e32 v99, v97
	s_nop 0
	v_mul_f32_e32 v97, v116, v99
	v_mul_f32_e32 v97, v100, v97
	v_cvt_pk_bf16_f32 v97, v97, s0
	ds_write_b16 v96, v97 offset:1152
	v_mul_f32_e32 v97, 0xbfb8aa3b, v117
	v_exp_f32_e32 v97, v97
	s_nop 0
	v_add_f32_e32 v97, 1.0, v97
	v_rcp_f32_e32 v99, v97
	s_nop 0
	v_mul_f32_e32 v97, v117, v99
	v_mul_f32_e32 v97, v101, v97
	v_cvt_pk_bf16_f32 v97, v97, s0
	ds_write_b16 v96, v97 offset:1296
	v_mul_f32_e32 v97, 0xbfb8aa3b, v118
	v_exp_f32_e32 v97, v97
	s_nop 0
	v_add_f32_e32 v97, 1.0, v97
	v_rcp_f32_e32 v99, v97
	s_nop 0
	v_mul_f32_e32 v97, v118, v99
	v_mul_f32_e32 v97, v102, v97
	v_cvt_pk_bf16_f32 v97, v97, s0
	ds_write_b16 v96, v97 offset:1440
	v_mul_f32_e32 v97, 0xbfb8aa3b, v119
	v_exp_f32_e32 v97, v97
	s_nop 0
	v_add_f32_e32 v97, 1.0, v97
	v_rcp_f32_e32 v99, v97
	s_nop 0
	v_mul_f32_e32 v97, v119, v99
	v_mul_f32_e32 v97, v103, v97
	v_cvt_pk_bf16_f32 v97, v97, s0
	ds_write_b16 v96, v97 offset:1584
	v_mul_f32_e32 v97, 0xbfb8aa3b, v120
	v_exp_f32_e32 v97, v97
	s_nop 0
	v_add_f32_e32 v97, 1.0, v97
	v_rcp_f32_e32 v99, v97
	s_nop 0
	v_mul_f32_e32 v97, v120, v99
	v_mul_f32_e32 v97, v104, v97
	v_cvt_pk_bf16_f32 v97, v97, s0
	ds_write_b16 v96, v97 offset:2304
	v_mul_f32_e32 v97, 0xbfb8aa3b, v121
	v_exp_f32_e32 v97, v97
	s_nop 0
	v_add_f32_e32 v97, 1.0, v97
	v_rcp_f32_e32 v99, v97
	s_nop 0
	v_mul_f32_e32 v97, v121, v99
	v_mul_f32_e32 v97, v105, v97
	v_cvt_pk_bf16_f32 v97, v97, s0
	ds_write_b16 v96, v97 offset:2448
	v_mul_f32_e32 v97, 0xbfb8aa3b, v122
	v_exp_f32_e32 v97, v97
	s_nop 0
	v_add_f32_e32 v97, 1.0, v97
	v_rcp_f32_e32 v99, v97
	s_nop 0
	v_mul_f32_e32 v97, v122, v99
	v_mul_f32_e32 v97, v106, v97
	v_cvt_pk_bf16_f32 v97, v97, s0
	ds_write_b16 v96, v97 offset:2592
	v_mul_f32_e32 v97, 0xbfb8aa3b, v123
	v_exp_f32_e32 v97, v97
	s_nop 0
	v_add_f32_e32 v97, 1.0, v97
	v_rcp_f32_e32 v99, v97
	s_nop 0
	v_mul_f32_e32 v97, v123, v99
	v_mul_f32_e32 v97, v107, v97
	v_cvt_pk_bf16_f32 v97, v97, s0
	ds_write_b16 v96, v97 offset:2736
	v_mul_f32_e32 v97, 0xbfb8aa3b, v124
	v_exp_f32_e32 v97, v97
	s_nop 0
	v_add_f32_e32 v97, 1.0, v97
	v_rcp_f32_e32 v99, v97
	s_nop 0
	v_mul_f32_e32 v97, v124, v99
	v_mul_f32_e32 v97, v108, v97
	v_cvt_pk_bf16_f32 v97, v97, s0
	ds_write_b16 v96, v97 offset:3456
	v_mul_f32_e32 v97, 0xbfb8aa3b, v125
	v_exp_f32_e32 v97, v97
	s_nop 0
	v_add_f32_e32 v97, 1.0, v97
	v_rcp_f32_e32 v99, v97
	s_nop 0
	v_mul_f32_e32 v97, v125, v99
	v_mul_f32_e32 v97, v109, v97
	v_cvt_pk_bf16_f32 v97, v97, s0
	ds_write_b16 v96, v97 offset:3600
	v_mul_f32_e32 v97, 0xbfb8aa3b, v126
	v_exp_f32_e32 v97, v97
	s_nop 0
	v_add_f32_e32 v97, 1.0, v97
	v_rcp_f32_e32 v99, v97
	s_nop 0
	v_mul_f32_e32 v97, v126, v99
	v_mul_f32_e32 v97, v110, v97
	v_cvt_pk_bf16_f32 v97, v97, s0
	ds_write_b16 v96, v97 offset:3744
	v_mul_f32_e32 v97, 0xbfb8aa3b, v127
	v_exp_f32_e32 v97, v97
	s_nop 0
	v_add_f32_e32 v97, 1.0, v97
	v_rcp_f32_e32 v99, v97
	s_nop 0
	v_mul_f32_e32 v97, v127, v99
	v_mul_f32_e32 v97, v111, v97
	v_cvt_pk_bf16_f32 v97, v97, s0
	ds_write_b16 v96, v97 offset:3888
	v_mul_f32_e32 v97, 0xbfb8aa3b, v80
	v_exp_f32_e32 v97, v97
	s_nop 0
	v_add_f32_e32 v97, 1.0, v97
	v_rcp_f32_e32 v99, v97
	s_nop 0
	v_mul_f32_e32 v80, v80, v99
	v_mul_f32_e32 v64, v64, v80
	v_cvt_pk_bf16_f32 v64, v64, s0
	ds_write_b16 v96, v64 offset:4608
	v_mul_f32_e32 v64, 0xbfb8aa3b, v81
	v_exp_f32_e32 v64, v64
	s_nop 0
	v_add_f32_e32 v64, 1.0, v64
	v_rcp_f32_e32 v97, v64
	s_nop 0
	v_mul_f32_e32 v64, v81, v97
	v_mul_f32_e32 v64, v65, v64
	v_cvt_pk_bf16_f32 v64, v64, s0
	ds_write_b16 v96, v64 offset:4752
	v_mul_f32_e32 v64, 0xbfb8aa3b, v82
	v_exp_f32_e32 v64, v64
	s_nop 0
	v_add_f32_e32 v64, 1.0, v64
	v_rcp_f32_e32 v80, v64
	s_nop 0
	v_mul_f32_e32 v64, v82, v80
	v_mul_f32_e32 v64, v66, v64
	v_cvt_pk_bf16_f32 v64, v64, s0
	ds_write_b16 v96, v64 offset:4896
	v_mul_f32_e32 v64, 0xbfb8aa3b, v83
	v_exp_f32_e32 v64, v64
	s_nop 0
	v_add_f32_e32 v64, 1.0, v64
	v_rcp_f32_e32 v66, v64
	s_nop 0
	v_mul_f32_e32 v64, v83, v66
	v_mul_f32_e32 v64, v67, v64
	v_cvt_pk_bf16_f32 v64, v64, s0
	ds_write_b16 v96, v64 offset:5040
	v_mul_f32_e32 v64, 0xbfb8aa3b, v84
	v_exp_f32_e32 v64, v64
	s_nop 0
	v_add_f32_e32 v64, 1.0, v64
	v_rcp_f32_e32 v66, v64
	s_nop 0
	v_mul_f32_e32 v64, v84, v66
	v_mul_f32_e32 v64, v68, v64
	v_cvt_pk_bf16_f32 v64, v64, s0
	ds_write_b16 v96, v64 offset:5760
	v_mul_f32_e32 v64, 0xbfb8aa3b, v85
	v_exp_f32_e32 v64, v64
	s_nop 0
	v_add_f32_e32 v64, 1.0, v64
	v_rcp_f32_e32 v66, v64
	s_nop 0
	v_mul_f32_e32 v64, v85, v66
	v_mul_f32_e32 v64, v69, v64
	v_cvt_pk_bf16_f32 v64, v64, s0
	ds_write_b16 v96, v64 offset:5904
	v_mul_f32_e32 v64, 0xbfb8aa3b, v86
	v_exp_f32_e32 v64, v64
	s_nop 0
	v_add_f32_e32 v64, 1.0, v64
	v_rcp_f32_e32 v66, v64
	s_nop 0
	v_mul_f32_e32 v64, v86, v66
	v_mul_f32_e32 v64, v70, v64
	v_cvt_pk_bf16_f32 v64, v64, s0
	ds_write_b16 v96, v64 offset:6048
	v_mul_f32_e32 v64, 0xbfb8aa3b, v87
	v_exp_f32_e32 v64, v64
	s_nop 0
	v_add_f32_e32 v64, 1.0, v64
	v_rcp_f32_e32 v66, v64
	s_nop 0
	v_mul_f32_e32 v64, v87, v66
	v_mul_f32_e32 v64, v71, v64
	v_cvt_pk_bf16_f32 v64, v64, s0
	ds_write_b16 v96, v64 offset:6192
	v_mul_f32_e32 v64, 0xbfb8aa3b, v88
	v_exp_f32_e32 v64, v64
	v_ashrrev_i32_e32 v71, 5, v130
	v_or_b32_e32 v70, 1, v71
	v_add_f32_e32 v64, 1.0, v64
	v_rcp_f32_e32 v66, v64
	s_nop 0
	v_mul_f32_e32 v64, v88, v66
	v_mul_f32_e32 v64, v72, v64
	v_cvt_pk_bf16_f32 v64, v64, s0
	ds_write_b16 v96, v64 offset:6912
	v_mul_f32_e32 v64, 0xbfb8aa3b, v89
	v_exp_f32_e32 v64, v64
	s_nop 0
	v_add_f32_e32 v64, 1.0, v64
	v_rcp_f32_e32 v66, v64
	s_nop 0
	v_mul_f32_e32 v64, v89, v66
	v_mul_f32_e32 v64, v73, v64
	v_cvt_pk_bf16_f32 v64, v64, s0
	ds_write_b16 v96, v64 offset:7056
	v_mul_f32_e32 v64, 0xbfb8aa3b, v90
	v_exp_f32_e32 v64, v64
	s_nop 0
	v_add_f32_e32 v64, 1.0, v64
	v_rcp_f32_e32 v66, v64
	s_nop 0
	v_mul_f32_e32 v64, v90, v66
	v_mul_f32_e32 v64, v74, v64
	v_cvt_pk_bf16_f32 v64, v64, s0
	ds_write_b16 v96, v64 offset:7200
	v_mul_f32_e32 v64, 0xbfb8aa3b, v91
	v_exp_f32_e32 v64, v64
	s_nop 0
	v_add_f32_e32 v64, 1.0, v64
	v_rcp_f32_e32 v66, v64
	s_nop 0
	v_mul_f32_e32 v64, v91, v66
	v_mul_f32_e32 v64, v75, v64
	v_cvt_pk_bf16_f32 v64, v64, s0
	ds_write_b16 v96, v64 offset:7344
	v_mul_f32_e32 v64, 0xbfb8aa3b, v92
	v_exp_f32_e32 v64, v64
	s_nop 0
	v_add_f32_e32 v64, 1.0, v64
	v_rcp_f32_e32 v66, v64
	s_nop 0
	v_mul_f32_e32 v64, v92, v66
	v_mul_f32_e32 v64, v76, v64
	v_cvt_pk_bf16_f32 v64, v64, s0
	ds_write_b16 v96, v64 offset:8064
	v_mul_f32_e32 v64, 0xbfb8aa3b, v93
	v_exp_f32_e32 v64, v64
	s_nop 0
	v_add_f32_e32 v64, 1.0, v64
	v_rcp_f32_e32 v66, v64
	s_nop 0
	v_mul_f32_e32 v64, v93, v66
	v_mul_f32_e32 v64, v77, v64
	v_cvt_pk_bf16_f32 v64, v64, s0
	ds_write_b16 v96, v64 offset:8208
	v_mul_f32_e32 v64, 0xbfb8aa3b, v94
	v_exp_f32_e32 v64, v64
	s_nop 0
	v_add_f32_e32 v64, 1.0, v64
	v_rcp_f32_e32 v66, v64
	s_nop 0
	v_mul_f32_e32 v64, v94, v66
	v_mul_f32_e32 v64, v78, v64
	v_cvt_pk_bf16_f32 v64, v64, s0
	ds_write_b16 v96, v64 offset:8352
	v_mul_f32_e32 v64, 0xbfb8aa3b, v95
	v_exp_f32_e32 v64, v64
	s_nop 0
	v_add_f32_e32 v64, 1.0, v64
	v_rcp_f32_e32 v66, v64
	s_nop 0
	v_mul_f32_e32 v64, v95, v66
	v_mul_f32_e32 v64, v79, v64
	v_cvt_pk_bf16_f32 v64, v64, s0
	ds_write_b16 v96, v64 offset:8496
	v_ashrrev_i32_e32 v68, 4, v131
	s_waitcnt lgkmcnt(0)
	v_ashrrev_i32_e32 v69, 31, v68
	ds_read_b128 v[72:75], v128
	v_mad_i64_i32 v[64:65], s[0:1], v71, s23, v[68:69]
	v_lshlrev_b64 v[64:65], 10, v[64:65]
	v_lshlrev_b32_e32 v66, 6, v181
	v_lshl_add_u64 v[64:65], s[66:67], 0, v[64:65]
	v_and_b32_e32 v176, 0x200, v66
	v_lshl_add_u64 v[76:77], v[64:65], 0, v[176:177]
	v_lshlrev_b32_e32 v66, 4, v129
	v_mov_b32_e32 v67, v177
	v_lshl_add_u64 v[64:65], v[76:77], 0, v[66:67]
	s_waitcnt lgkmcnt(0)
	global_store_dwordx4 v[64:65], v[72:75], off
	ds_read_b128 v[72:75], v128 offset:2304
	v_or_b32_e32 v64, 0x100, v66
	v_mov_b32_e32 v65, v177
	v_lshl_add_u64 v[76:77], v[76:77], 0, v[64:65]
	s_waitcnt lgkmcnt(0)
	global_store_dwordx4 v[76:77], v[72:75], off
	ds_read_b128 v[72:75], v128 offset:4608
	v_mad_i64_i32 v[76:77], s[0:1], v70, s23, v[68:69]
	v_lshlrev_b64 v[76:77], 10, v[76:77]
	v_lshl_add_u64 v[76:77], s[66:67], 0, v[76:77]
	v_lshl_add_u64 v[76:77], v[76:77], 0, v[176:177]
	v_lshl_add_u64 v[78:79], v[76:77], 0, v[66:67]
	v_mul_f32_e32 v69, 0xbfb8aa3b, v48
	s_waitcnt lgkmcnt(0)
	global_store_dwordx4 v[78:79], v[72:75], off
	ds_read_b128 v[72:75], v128 offset:6912
	v_exp_f32_e32 v69, v69
	v_lshl_add_u64 v[76:77], v[76:77], 0, v[64:65]
	v_add_f32_e32 v69, 1.0, v69
	s_waitcnt lgkmcnt(0)
	global_store_dwordx4 v[76:77], v[72:75], off
	s_waitcnt lgkmcnt(0)
	s_nop 1
	v_rcp_f32_e32 v73, v69
	s_nop 0
	v_mul_f32_e32 v48, v48, v73
	v_mul_f32_e32 v32, v32, v48
	v_cvt_pk_bf16_f32 v32, v32, s0
	ds_write_b16 v96, v32
	v_mul_f32_e32 v32, 0xbfb8aa3b, v49
	v_exp_f32_e32 v32, v32
	s_nop 0
	v_add_f32_e32 v32, 1.0, v32
	v_rcp_f32_e32 v69, v32
	s_nop 0
	v_mul_f32_e32 v32, v49, v69
	v_mul_f32_e32 v32, v33, v32
	v_cvt_pk_bf16_f32 v32, v32, s0
	ds_write_b16 v96, v32 offset:144
	v_mul_f32_e32 v32, 0xbfb8aa3b, v50
	v_exp_f32_e32 v32, v32
	s_nop 0
	v_add_f32_e32 v32, 1.0, v32
	v_rcp_f32_e32 v48, v32
	s_nop 0
	v_mul_f32_e32 v32, v50, v48
	v_mul_f32_e32 v32, v34, v32
	v_cvt_pk_bf16_f32 v32, v32, s0
	ds_write_b16 v96, v32 offset:288
	v_mul_f32_e32 v32, 0xbfb8aa3b, v51
	v_exp_f32_e32 v32, v32
	s_nop 0
	v_add_f32_e32 v32, 1.0, v32
	v_rcp_f32_e32 v34, v32
	s_nop 0
	v_mul_f32_e32 v32, v51, v34
	v_mul_f32_e32 v32, v35, v32
	v_cvt_pk_bf16_f32 v32, v32, s0
	ds_write_b16 v96, v32 offset:432
	v_mul_f32_e32 v32, 0xbfb8aa3b, v52
	v_exp_f32_e32 v32, v32
	s_nop 0
	v_add_f32_e32 v32, 1.0, v32
	v_rcp_f32_e32 v34, v32
	s_nop 0
	v_mul_f32_e32 v32, v52, v34
	v_mul_f32_e32 v32, v36, v32
	v_cvt_pk_bf16_f32 v32, v32, s0
	ds_write_b16 v96, v32 offset:1152
	v_mul_f32_e32 v32, 0xbfb8aa3b, v53
	v_exp_f32_e32 v32, v32
	s_nop 0
	v_add_f32_e32 v32, 1.0, v32
	v_rcp_f32_e32 v34, v32
	s_nop 0
	v_mul_f32_e32 v32, v53, v34
	v_mul_f32_e32 v32, v37, v32
	v_cvt_pk_bf16_f32 v32, v32, s0
	ds_write_b16 v96, v32 offset:1296
	v_mul_f32_e32 v32, 0xbfb8aa3b, v54
	v_exp_f32_e32 v32, v32
	s_nop 0
	v_add_f32_e32 v32, 1.0, v32
	v_rcp_f32_e32 v34, v32
	s_nop 0
	v_mul_f32_e32 v32, v54, v34
	v_mul_f32_e32 v32, v38, v32
	v_cvt_pk_bf16_f32 v32, v32, s0
	ds_write_b16 v96, v32 offset:1440
	v_mul_f32_e32 v32, 0xbfb8aa3b, v55
	v_exp_f32_e32 v32, v32
	s_nop 0
	v_add_f32_e32 v32, 1.0, v32
	v_rcp_f32_e32 v34, v32
	s_nop 0
	v_mul_f32_e32 v32, v55, v34
	v_mul_f32_e32 v32, v39, v32
	v_cvt_pk_bf16_f32 v32, v32, s0
	ds_write_b16 v96, v32 offset:1584
	v_mul_f32_e32 v32, 0xbfb8aa3b, v56
	v_exp_f32_e32 v32, v32
	s_nop 0
	v_add_f32_e32 v32, 1.0, v32
	v_rcp_f32_e32 v34, v32
	s_nop 0
	v_mul_f32_e32 v32, v56, v34
	v_mul_f32_e32 v32, v40, v32
	v_cvt_pk_bf16_f32 v32, v32, s0
	ds_write_b16 v96, v32 offset:2304
	v_mul_f32_e32 v32, 0xbfb8aa3b, v57
	v_exp_f32_e32 v32, v32
	s_nop 0
	v_add_f32_e32 v32, 1.0, v32
	v_rcp_f32_e32 v34, v32
	s_nop 0
	v_mul_f32_e32 v32, v57, v34
	v_mul_f32_e32 v32, v41, v32
	v_cvt_pk_bf16_f32 v32, v32, s0
	ds_write_b16 v96, v32 offset:2448
	v_mul_f32_e32 v32, 0xbfb8aa3b, v58
	v_exp_f32_e32 v32, v32
	s_nop 0
	v_add_f32_e32 v32, 1.0, v32
	v_rcp_f32_e32 v34, v32
	s_nop 0
	v_mul_f32_e32 v32, v58, v34
	v_mul_f32_e32 v32, v42, v32
	v_cvt_pk_bf16_f32 v32, v32, s0
	ds_write_b16 v96, v32 offset:2592
	v_mul_f32_e32 v32, 0xbfb8aa3b, v59
	v_exp_f32_e32 v32, v32
	s_nop 0
	v_add_f32_e32 v32, 1.0, v32
	v_rcp_f32_e32 v34, v32
	s_nop 0
	v_mul_f32_e32 v32, v59, v34
	v_mul_f32_e32 v32, v43, v32
	v_cvt_pk_bf16_f32 v32, v32, s0
	ds_write_b16 v96, v32 offset:2736
	v_mul_f32_e32 v32, 0xbfb8aa3b, v60
	v_exp_f32_e32 v32, v32
	s_nop 0
	v_add_f32_e32 v32, 1.0, v32
	v_rcp_f32_e32 v34, v32
	s_nop 0
	v_mul_f32_e32 v32, v60, v34
	v_mul_f32_e32 v32, v44, v32
	v_cvt_pk_bf16_f32 v32, v32, s0
	ds_write_b16 v96, v32 offset:3456
	v_mul_f32_e32 v32, 0xbfb8aa3b, v61
	v_exp_f32_e32 v32, v32
	s_nop 0
	v_add_f32_e32 v32, 1.0, v32
	v_rcp_f32_e32 v34, v32
	s_nop 0
	v_mul_f32_e32 v32, v61, v34
	v_mul_f32_e32 v32, v45, v32
	v_cvt_pk_bf16_f32 v32, v32, s0
	ds_write_b16 v96, v32 offset:3600
	v_mul_f32_e32 v32, 0xbfb8aa3b, v62
	v_exp_f32_e32 v32, v32
	s_nop 0
	v_add_f32_e32 v32, 1.0, v32
	v_rcp_f32_e32 v34, v32
	s_nop 0
	v_mul_f32_e32 v32, v62, v34
	v_mul_f32_e32 v32, v46, v32
	v_cvt_pk_bf16_f32 v32, v32, s0
	ds_write_b16 v96, v32 offset:3744
	v_mul_f32_e32 v32, 0xbfb8aa3b, v63
	v_exp_f32_e32 v32, v32
	s_nop 0
	v_add_f32_e32 v32, 1.0, v32
	v_rcp_f32_e32 v34, v32
	s_nop 0
	v_mul_f32_e32 v32, v63, v34
	v_mul_f32_e32 v32, v47, v32
	v_cvt_pk_bf16_f32 v32, v32, s0
	ds_write_b16 v96, v32 offset:3888
	v_mul_f32_e32 v32, 0xbfb8aa3b, v16
	v_exp_f32_e32 v32, v32
	s_nop 0
	v_add_f32_e32 v32, 1.0, v32
	v_rcp_f32_e32 v34, v32
	s_nop 0
	v_mul_f32_e32 v16, v16, v34
	v_mul_f32_e32 v0, v0, v16
	v_cvt_pk_bf16_f32 v0, v0, s0
	ds_write_b16 v96, v0 offset:4608
	v_mul_f32_e32 v0, 0xbfb8aa3b, v17
	v_exp_f32_e32 v0, v0
	s_nop 0
	v_add_f32_e32 v0, 1.0, v0
	v_rcp_f32_e32 v32, v0
	s_nop 0
	v_mul_f32_e32 v0, v17, v32
	v_mul_f32_e32 v0, v1, v0
	v_cvt_pk_bf16_f32 v0, v0, s0
	ds_write_b16 v96, v0 offset:4752
	v_mul_f32_e32 v0, 0xbfb8aa3b, v18
	v_exp_f32_e32 v0, v0
	s_nop 0
	v_add_f32_e32 v0, 1.0, v0
	v_rcp_f32_e32 v16, v0
	s_nop 0
	v_mul_f32_e32 v0, v18, v16
	v_mul_f32_e32 v0, v2, v0
	v_cvt_pk_bf16_f32 v0, v0, s0
	ds_write_b16 v96, v0 offset:4896
	v_mul_f32_e32 v0, 0xbfb8aa3b, v19
	v_exp_f32_e32 v0, v0
	s_nop 0
	v_add_f32_e32 v0, 1.0, v0
	v_rcp_f32_e32 v2, v0
	s_nop 0
	v_mul_f32_e32 v0, v19, v2
	v_mul_f32_e32 v0, v3, v0
	v_cvt_pk_bf16_f32 v0, v0, s0
	ds_write_b16 v96, v0 offset:5040
	v_mul_f32_e32 v0, 0xbfb8aa3b, v20
	v_exp_f32_e32 v0, v0
	s_nop 0
	v_add_f32_e32 v0, 1.0, v0
	v_rcp_f32_e32 v2, v0
	s_nop 0
	v_mul_f32_e32 v0, v20, v2
	v_mul_f32_e32 v0, v4, v0
	v_cvt_pk_bf16_f32 v0, v0, s0
	ds_write_b16 v96, v0 offset:5760
	v_mul_f32_e32 v0, 0xbfb8aa3b, v21
	v_exp_f32_e32 v0, v0
	s_nop 0
	v_add_f32_e32 v0, 1.0, v0
	v_rcp_f32_e32 v2, v0
	s_nop 0
	v_mul_f32_e32 v0, v21, v2
	v_mul_f32_e32 v0, v5, v0
	v_cvt_pk_bf16_f32 v0, v0, s0
	ds_write_b16 v96, v0 offset:5904
	v_mul_f32_e32 v0, 0xbfb8aa3b, v22
	v_exp_f32_e32 v0, v0
	s_nop 0
	v_add_f32_e32 v0, 1.0, v0
	v_rcp_f32_e32 v2, v0
	s_nop 0
	v_mul_f32_e32 v0, v22, v2
	v_mul_f32_e32 v0, v6, v0
	v_cvt_pk_bf16_f32 v0, v0, s0
	ds_write_b16 v96, v0 offset:6048
	v_mul_f32_e32 v0, 0xbfb8aa3b, v23
	v_exp_f32_e32 v0, v0
	s_nop 0
	v_add_f32_e32 v0, 1.0, v0
	v_rcp_f32_e32 v2, v0
	s_nop 0
	v_mul_f32_e32 v0, v23, v2
	v_mul_f32_e32 v0, v7, v0
	v_cvt_pk_bf16_f32 v0, v0, s0
	ds_write_b16 v96, v0 offset:6192
	v_mul_f32_e32 v0, 0xbfb8aa3b, v24
	v_exp_f32_e32 v0, v0
	s_nop 0
	v_add_f32_e32 v0, 1.0, v0
	v_rcp_f32_e32 v2, v0
	s_nop 0
	v_mul_f32_e32 v0, v24, v2
	v_mul_f32_e32 v0, v8, v0
	v_cvt_pk_bf16_f32 v0, v0, s0
	ds_write_b16 v96, v0 offset:6912
	v_mul_f32_e32 v0, 0xbfb8aa3b, v25
	v_exp_f32_e32 v0, v0
	s_nop 0
	v_add_f32_e32 v0, 1.0, v0
	v_rcp_f32_e32 v2, v0
	s_nop 0
	v_mul_f32_e32 v0, v25, v2
	v_mul_f32_e32 v0, v9, v0
	v_cvt_pk_bf16_f32 v0, v0, s0
	ds_write_b16 v96, v0 offset:7056
	v_mul_f32_e32 v0, 0xbfb8aa3b, v26
	v_exp_f32_e32 v0, v0
	s_nop 0
	v_add_f32_e32 v0, 1.0, v0
	v_rcp_f32_e32 v2, v0
	s_nop 0
	v_mul_f32_e32 v0, v26, v2
	v_mul_f32_e32 v0, v10, v0
	v_cvt_pk_bf16_f32 v0, v0, s0
	ds_write_b16 v96, v0 offset:7200
	v_mul_f32_e32 v0, 0xbfb8aa3b, v27
	v_exp_f32_e32 v0, v0
	s_nop 0
	v_add_f32_e32 v0, 1.0, v0
	v_rcp_f32_e32 v2, v0
	s_nop 0
	v_mul_f32_e32 v0, v27, v2
	v_mul_f32_e32 v0, v11, v0
	v_cvt_pk_bf16_f32 v0, v0, s0
	ds_write_b16 v96, v0 offset:7344
	v_mul_f32_e32 v0, 0xbfb8aa3b, v28
	v_exp_f32_e32 v0, v0
	s_nop 0
	v_add_f32_e32 v0, 1.0, v0
	v_rcp_f32_e32 v2, v0
	s_nop 0
	v_mul_f32_e32 v0, v28, v2
	v_mul_f32_e32 v0, v12, v0
	v_cvt_pk_bf16_f32 v0, v0, s0
	ds_write_b16 v96, v0 offset:8064
	v_mul_f32_e32 v0, 0xbfb8aa3b, v29
	v_exp_f32_e32 v0, v0
	s_nop 0
	v_add_f32_e32 v0, 1.0, v0
	v_rcp_f32_e32 v2, v0
	s_nop 0
	v_mul_f32_e32 v0, v29, v2
	v_mul_f32_e32 v0, v13, v0
	v_cvt_pk_bf16_f32 v0, v0, s0
	ds_write_b16 v96, v0 offset:8208
	v_mul_f32_e32 v0, 0xbfb8aa3b, v30
	v_exp_f32_e32 v0, v0
	s_nop 0
	v_add_f32_e32 v0, 1.0, v0
	v_rcp_f32_e32 v2, v0
	s_nop 0
	v_mul_f32_e32 v0, v30, v2
	v_mul_f32_e32 v0, v14, v0
	v_cvt_pk_bf16_f32 v0, v0, s0
	ds_write_b16 v96, v0 offset:8352
	v_mul_f32_e32 v0, 0xbfb8aa3b, v31
	v_exp_f32_e32 v0, v0
	s_nop 0
	v_add_f32_e32 v0, 1.0, v0
	v_rcp_f32_e32 v2, v0
	s_nop 0
	v_mul_f32_e32 v0, v31, v2
	v_mul_f32_e32 v0, v15, v0
	v_cvt_pk_bf16_f32 v0, v0, s0
	ds_write_b16 v96, v0 offset:8496
	v_or_b32_e32 v4, 2, v68
	s_waitcnt lgkmcnt(0)
	v_ashrrev_i32_e32 v5, 31, v4
	ds_read_b128 v[0:3], v128
	v_mad_i64_i32 v[6:7], s[0:1], v71, s23, v[4:5]
	v_lshlrev_b64 v[6:7], 10, v[6:7]
	v_lshl_add_u64 v[6:7], s[66:67], 0, v[6:7]
	v_lshl_add_u64 v[6:7], v[6:7], 0, v[176:177]
	v_lshl_add_u64 v[8:9], v[6:7], 0, v[66:67]
	s_waitcnt lgkmcnt(0)
	global_store_dwordx4 v[8:9], v[0:3], off
	ds_read_b128 v[0:3], v128 offset:2304
	v_lshl_add_u64 v[6:7], v[6:7], 0, v[64:65]
	v_mad_i64_i32 v[4:5], s[0:1], v70, s23, v[4:5]
	v_lshlrev_b64 v[4:5], 10, v[4:5]
	s_waitcnt lgkmcnt(0)
	global_store_dwordx4 v[6:7], v[0:3], off
	ds_read_b128 v[0:3], v128 offset:4608
	v_lshl_add_u64 v[4:5], s[66:67], 0, v[4:5]
	v_lshl_add_u64 v[4:5], v[4:5], 0, v[176:177]
	v_lshl_add_u64 v[6:7], v[4:5], 0, v[66:67]
	v_lshl_add_u64 v[4:5], v[4:5], 0, v[64:65]
	s_waitcnt lgkmcnt(0)
	global_store_dwordx4 v[6:7], v[0:3], off
	ds_read_b128 v[0:3], v128 offset:6912
	v_readlane_b32 s0, v254, 11
	s_add_i32 s2, s2, s0
	s_cmp_lt_i32 s2, s3
	s_waitcnt lgkmcnt(0)
	global_store_dwordx4 v[4:5], v[0:3], off
	s_waitcnt lgkmcnt(0)
	s_barrier
	s_cbranch_scc1 .LBB0_1031

.Lg16_down_k:
	s_add_i32 s9, s8, 2
	s_lshl_b32 s96, s9, 13
	s_add_i32 m0, vcc_lo, 16384
	v_lshl_add_u64 v[160:161], v[188:189], 0, s[96:97]
	global_load_lds_dwordx4 v[160:161], off
	global_load_lds_dwordx4 v[160:161], off offset:1024
	ds_read_b128 v[196:199], v246 offset:0
	ds_read_b128 v[200:203], v246 offset:1024
	ds_read_b128 v[204:207], v246 offset:2048
	ds_read_b128 v[242:245], v246 offset:3072
	s_add_i32 s9, s8, 2
	s_lshl_b32 s96, s9, 11
	v_lshl_add_u64 v[248:249], v[184:185], 0, s[96:97]
	v_lshl_add_u64 v[250:251], v[186:187], 0, s[96:97]
	s_waitcnt vmcnt(8) lgkmcnt(3)
	v_mfma_f32_16x16x32_bf16 v[112:115], v[128:131], v[196:199], v[112:115]
	v_mfma_f32_16x16x32_bf16 v[120:123], v[132:135], v[196:199], v[120:123]
	v_mfma_f32_16x16x32_bf16 v[48:51], v[136:139], v[196:199], v[48:51]
	v_mfma_f32_16x16x32_bf16 v[56:59], v[140:143], v[196:199], v[56:59]
	ds_read_b128 v[196:199], v246 offset:4096
	s_waitcnt lgkmcnt(3)
	v_mfma_f32_16x16x32_bf16 v[116:119], v[128:131], v[200:203], v[116:119]
	v_mfma_f32_16x16x32_bf16 v[124:127], v[132:135], v[200:203], v[124:127]
	v_mfma_f32_16x16x32_bf16 v[52:55], v[136:139], v[200:203], v[52:55]
	v_mfma_f32_16x16x32_bf16 v[60:63], v[140:143], v[200:203], v[60:63]
	ds_read_b128 v[200:203], v246 offset:5120
	s_waitcnt lgkmcnt(3)
	v_mfma_f32_16x16x32_bf16 v[96:99], v[128:131], v[204:207], v[96:99]
	v_mfma_f32_16x16x32_bf16 v[104:107], v[132:135], v[204:207], v[104:107]
	v_mfma_f32_16x16x32_bf16 v[32:35], v[136:139], v[204:207], v[32:35]
	v_mfma_f32_16x16x32_bf16 v[40:43], v[140:143], v[204:207], v[40:43]
	ds_read_b128 v[204:207], v246 offset:6144
	s_waitcnt lgkmcnt(3)
	v_mfma_f32_16x16x32_bf16 v[100:103], v[128:131], v[242:245], v[100:103]
	v_mfma_f32_16x16x32_bf16 v[108:111], v[132:135], v[242:245], v[108:111]
	v_mfma_f32_16x16x32_bf16 v[36:39], v[136:139], v[242:245], v[36:39]
	v_mfma_f32_16x16x32_bf16 v[44:47], v[140:143], v[242:245], v[44:47]
	ds_read_b128 v[242:245], v246 offset:7168
	s_waitcnt lgkmcnt(3)
	v_mfma_f32_16x16x32_bf16 v[80:83], v[128:131], v[196:199], v[80:83]
	v_mfma_f32_16x16x32_bf16 v[88:91], v[132:135], v[196:199], v[88:91]
	v_mfma_f32_16x16x32_bf16 v[16:19], v[136:139], v[196:199], v[16:19]
	v_mfma_f32_16x16x32_bf16 v[24:27], v[140:143], v[196:199], v[24:27]
	s_waitcnt lgkmcnt(2)
	v_mfma_f32_16x16x32_bf16 v[84:87], v[128:131], v[200:203], v[84:87]
	v_mfma_f32_16x16x32_bf16 v[92:95], v[132:135], v[200:203], v[92:95]
	v_mfma_f32_16x16x32_bf16 v[20:23], v[136:139], v[200:203], v[20:23]
	v_mfma_f32_16x16x32_bf16 v[28:31], v[140:143], v[200:203], v[28:31]
	s_waitcnt lgkmcnt(1)
	v_mfma_f32_16x16x32_bf16 v[64:67], v[128:131], v[204:207], v[64:67]
	v_mfma_f32_16x16x32_bf16 v[72:75], v[132:135], v[204:207], v[72:75]
	v_mfma_f32_16x16x32_bf16 v[0:3], v[136:139], v[204:207], v[0:3]
	v_mfma_f32_16x16x32_bf16 v[8:11], v[140:143], v[204:207], v[8:11]
	s_waitcnt lgkmcnt(0)
	v_mfma_f32_16x16x32_bf16 v[68:71], v[128:131], v[242:245], v[68:71]
	v_mfma_f32_16x16x32_bf16 v[76:79], v[132:135], v[242:245], v[76:79]
	v_mfma_f32_16x16x32_bf16 v[4:7], v[136:139], v[242:245], v[4:7]
	v_mfma_f32_16x16x32_bf16 v[12:15], v[140:143], v[242:245], v[12:15]
	global_load_dwordx4 v[128:131], v[248:249], off
	global_load_dwordx4 v[132:135], v[248:249], off offset:256
	global_load_dwordx4 v[136:139], v[250:251], off
	global_load_dwordx4 v[140:143], v[250:251], off offset:256
	s_waitcnt vmcnt(10)
	s_barrier
	s_add_i32 s9, s8, 3
	s_lshl_b32 s96, s9, 13
	s_mov_b32 m0, vcc_lo
	v_lshl_add_u64 v[160:161], v[188:189], 0, s[96:97]
	global_load_lds_dwordx4 v[160:161], off
	global_load_lds_dwordx4 v[160:161], off offset:1024
	ds_read_b128 v[196:199], v246 offset:8192
	ds_read_b128 v[200:203], v246 offset:9216
	ds_read_b128 v[204:207], v246 offset:10240
	ds_read_b128 v[242:245], v246 offset:11264
	s_add_i32 s9, s8, 3
	s_lshl_b32 s96, s9, 11
	v_lshl_add_u64 v[248:249], v[184:185], 0, s[96:97]
	v_lshl_add_u64 v[250:251], v[186:187], 0, s[96:97]
	s_waitcnt vmcnt(8) lgkmcnt(3)
	v_mfma_f32_16x16x32_bf16 v[112:115], v[144:147], v[196:199], v[112:115]
	v_mfma_f32_16x16x32_bf16 v[120:123], v[148:151], v[196:199], v[120:123]
	v_mfma_f32_16x16x32_bf16 v[48:51], v[152:155], v[196:199], v[48:51]
	v_mfma_f32_16x16x32_bf16 v[56:59], v[156:159], v[196:199], v[56:59]
	ds_read_b128 v[196:199], v246 offset:12288
	s_waitcnt lgkmcnt(3)
	v_mfma_f32_16x16x32_bf16 v[116:119], v[144:147], v[200:203], v[116:119]
	v_mfma_f32_16x16x32_bf16 v[124:127], v[148:151], v[200:203], v[124:127]
	v_mfma_f32_16x16x32_bf16 v[52:55], v[152:155], v[200:203], v[52:55]
	v_mfma_f32_16x16x32_bf16 v[60:63], v[156:159], v[200:203], v[60:63]
	ds_read_b128 v[200:203], v246 offset:13312
	s_waitcnt lgkmcnt(3)
	v_mfma_f32_16x16x32_bf16 v[96:99], v[144:147], v[204:207], v[96:99]
	v_mfma_f32_16x16x32_bf16 v[104:107], v[148:151], v[204:207], v[104:107]
	v_mfma_f32_16x16x32_bf16 v[32:35], v[152:155], v[204:207], v[32:35]
	v_mfma_f32_16x16x32_bf16 v[40:43], v[156:159], v[204:207], v[40:43]
	ds_read_b128 v[204:207], v246 offset:14336
	s_waitcnt lgkmcnt(3)
	v_mfma_f32_16x16x32_bf16 v[100:103], v[144:147], v[242:245], v[100:103]
	v_mfma_f32_16x16x32_bf16 v[108:111], v[148:151], v[242:245], v[108:111]
	v_mfma_f32_16x16x32_bf16 v[36:39], v[152:155], v[242:245], v[36:39]
	v_mfma_f32_16x16x32_bf16 v[44:47], v[156:159], v[242:245], v[44:47]
	ds_read_b128 v[242:245], v246 offset:15360
	s_waitcnt lgkmcnt(3)
	v_mfma_f32_16x16x32_bf16 v[80:83], v[144:147], v[196:199], v[80:83]
	v_mfma_f32_16x16x32_bf16 v[88:91], v[148:151], v[196:199], v[88:91]
	v_mfma_f32_16x16x32_bf16 v[16:19], v[152:155], v[196:199], v[16:19]
	v_mfma_f32_16x16x32_bf16 v[24:27], v[156:159], v[196:199], v[24:27]
	s_waitcnt lgkmcnt(2)
	v_mfma_f32_16x16x32_bf16 v[84:87], v[144:147], v[200:203], v[84:87]
	v_mfma_f32_16x16x32_bf16 v[92:95], v[148:151], v[200:203], v[92:95]
	v_mfma_f32_16x16x32_bf16 v[20:23], v[152:155], v[200:203], v[20:23]
	v_mfma_f32_16x16x32_bf16 v[28:31], v[156:159], v[200:203], v[28:31]
	s_waitcnt lgkmcnt(1)
	v_mfma_f32_16x16x32_bf16 v[64:67], v[144:147], v[204:207], v[64:67]
	v_mfma_f32_16x16x32_bf16 v[72:75], v[148:151], v[204:207], v[72:75]
	v_mfma_f32_16x16x32_bf16 v[0:3], v[152:155], v[204:207], v[0:3]
	v_mfma_f32_16x16x32_bf16 v[8:11], v[156:159], v[204:207], v[8:11]
	s_waitcnt lgkmcnt(0)
	v_mfma_f32_16x16x32_bf16 v[68:71], v[144:147], v[242:245], v[68:71]
	v_mfma_f32_16x16x32_bf16 v[76:79], v[148:151], v[242:245], v[76:79]
	v_mfma_f32_16x16x32_bf16 v[4:7], v[152:155], v[242:245], v[4:7]
	v_mfma_f32_16x16x32_bf16 v[12:15], v[156:159], v[242:245], v[12:15]
	global_load_dwordx4 v[144:147], v[248:249], off
	global_load_dwordx4 v[148:151], v[248:249], off offset:256
	global_load_dwordx4 v[152:155], v[250:251], off
	global_load_dwordx4 v[156:159], v[250:251], off offset:256
	s_waitcnt vmcnt(10)
	s_barrier
	s_add_i32 s9, s8, 4
	s_lshl_b32 s96, s9, 13
	s_add_i32 m0, vcc_lo, 8192
	v_lshl_add_u64 v[160:161], v[188:189], 0, s[96:97]
	global_load_lds_dwordx4 v[160:161], off
	global_load_lds_dwordx4 v[160:161], off offset:1024
	ds_read_b128 v[196:199], v246 offset:16384
	ds_read_b128 v[200:203], v246 offset:17408
	ds_read_b128 v[204:207], v246 offset:18432
	ds_read_b128 v[242:245], v246 offset:19456
	s_add_i32 s9, s8, 4
	s_lshl_b32 s96, s9, 11
	v_lshl_add_u64 v[248:249], v[184:185], 0, s[96:97]
	v_lshl_add_u64 v[250:251], v[186:187], 0, s[96:97]
	s_waitcnt vmcnt(8) lgkmcnt(3)
	v_mfma_f32_16x16x32_bf16 v[112:115], v[128:131], v[196:199], v[112:115]
	v_mfma_f32_16x16x32_bf16 v[120:123], v[132:135], v[196:199], v[120:123]
	v_mfma_f32_16x16x32_bf16 v[48:51], v[136:139], v[196:199], v[48:51]
	v_mfma_f32_16x16x32_bf16 v[56:59], v[140:143], v[196:199], v[56:59]
	ds_read_b128 v[196:199], v246 offset:20480
	s_waitcnt lgkmcnt(3)
	v_mfma_f32_16x16x32_bf16 v[116:119], v[128:131], v[200:203], v[116:119]
	v_mfma_f32_16x16x32_bf16 v[124:127], v[132:135], v[200:203], v[124:127]
	v_mfma_f32_16x16x32_bf16 v[52:55], v[136:139], v[200:203], v[52:55]
	v_mfma_f32_16x16x32_bf16 v[60:63], v[140:143], v[200:203], v[60:63]
	ds_read_b128 v[200:203], v246 offset:21504
	s_waitcnt lgkmcnt(3)
	v_mfma_f32_16x16x32_bf16 v[96:99], v[128:131], v[204:207], v[96:99]
	v_mfma_f32_16x16x32_bf16 v[104:107], v[132:135], v[204:207], v[104:107]
	v_mfma_f32_16x16x32_bf16 v[32:35], v[136:139], v[204:207], v[32:35]
	v_mfma_f32_16x16x32_bf16 v[40:43], v[140:143], v[204:207], v[40:43]
	ds_read_b128 v[204:207], v246 offset:22528
	s_waitcnt lgkmcnt(3)
	v_mfma_f32_16x16x32_bf16 v[100:103], v[128:131], v[242:245], v[100:103]
	v_mfma_f32_16x16x32_bf16 v[108:111], v[132:135], v[242:245], v[108:111]
	v_mfma_f32_16x16x32_bf16 v[36:39], v[136:139], v[242:245], v[36:39]
	v_mfma_f32_16x16x32_bf16 v[44:47], v[140:143], v[242:245], v[44:47]
	ds_read_b128 v[242:245], v246 offset:23552
	s_waitcnt lgkmcnt(3)
	v_mfma_f32_16x16x32_bf16 v[80:83], v[128:131], v[196:199], v[80:83]
	v_mfma_f32_16x16x32_bf16 v[88:91], v[132:135], v[196:199], v[88:91]
	v_mfma_f32_16x16x32_bf16 v[16:19], v[136:139], v[196:199], v[16:19]
	v_mfma_f32_16x16x32_bf16 v[24:27], v[140:143], v[196:199], v[24:27]
	s_waitcnt lgkmcnt(2)
	v_mfma_f32_16x16x32_bf16 v[84:87], v[128:131], v[200:203], v[84:87]
	v_mfma_f32_16x16x32_bf16 v[92:95], v[132:135], v[200:203], v[92:95]
	v_mfma_f32_16x16x32_bf16 v[20:23], v[136:139], v[200:203], v[20:23]
	v_mfma_f32_16x16x32_bf16 v[28:31], v[140:143], v[200:203], v[28:31]
	s_waitcnt lgkmcnt(1)
	v_mfma_f32_16x16x32_bf16 v[64:67], v[128:131], v[204:207], v[64:67]
	v_mfma_f32_16x16x32_bf16 v[72:75], v[132:135], v[204:207], v[72:75]
	v_mfma_f32_16x16x32_bf16 v[0:3], v[136:139], v[204:207], v[0:3]
	v_mfma_f32_16x16x32_bf16 v[8:11], v[140:143], v[204:207], v[8:11]
	s_waitcnt lgkmcnt(0)
	v_mfma_f32_16x16x32_bf16 v[68:71], v[128:131], v[242:245], v[68:71]
	v_mfma_f32_16x16x32_bf16 v[76:79], v[132:135], v[242:245], v[76:79]
	v_mfma_f32_16x16x32_bf16 v[4:7], v[136:139], v[242:245], v[4:7]
	v_mfma_f32_16x16x32_bf16 v[12:15], v[140:143], v[242:245], v[12:15]
	global_load_dwordx4 v[128:131], v[248:249], off
	global_load_dwordx4 v[132:135], v[248:249], off offset:256
	global_load_dwordx4 v[136:139], v[250:251], off
	global_load_dwordx4 v[140:143], v[250:251], off offset:256
	s_waitcnt vmcnt(10)
	s_barrier
	s_add_i32 s9, s8, 5
	s_lshl_b32 s96, s9, 13
	s_add_i32 m0, vcc_lo, 16384
	v_lshl_add_u64 v[160:161], v[188:189], 0, s[96:97]
	global_load_lds_dwordx4 v[160:161], off
	global_load_lds_dwordx4 v[160:161], off offset:1024
	ds_read_b128 v[196:199], v246 offset:0
	ds_read_b128 v[200:203], v246 offset:1024
	ds_read_b128 v[204:207], v246 offset:2048
	ds_read_b128 v[242:245], v246 offset:3072
	s_add_i32 s9, s8, 5
	s_lshl_b32 s96, s9, 11
	v_lshl_add_u64 v[248:249], v[184:185], 0, s[96:97]
	v_lshl_add_u64 v[250:251], v[186:187], 0, s[96:97]
	s_waitcnt vmcnt(8) lgkmcnt(3)
	v_mfma_f32_16x16x32_bf16 v[112:115], v[144:147], v[196:199], v[112:115]
	v_mfma_f32_16x16x32_bf16 v[120:123], v[148:151], v[196:199], v[120:123]
	v_mfma_f32_16x16x32_bf16 v[48:51], v[152:155], v[196:199], v[48:51]
	v_mfma_f32_16x16x32_bf16 v[56:59], v[156:159], v[196:199], v[56:59]
	ds_read_b128 v[196:199], v246 offset:4096
	s_waitcnt lgkmcnt(3)
	v_mfma_f32_16x16x32_bf16 v[116:119], v[144:147], v[200:203], v[116:119]
	v_mfma_f32_16x16x32_bf16 v[124:127], v[148:151], v[200:203], v[124:127]
	v_mfma_f32_16x16x32_bf16 v[52:55], v[152:155], v[200:203], v[52:55]
	v_mfma_f32_16x16x32_bf16 v[60:63], v[156:159], v[200:203], v[60:63]
	ds_read_b128 v[200:203], v246 offset:5120
	s_waitcnt lgkmcnt(3)
	v_mfma_f32_16x16x32_bf16 v[96:99], v[144:147], v[204:207], v[96:99]
	v_mfma_f32_16x16x32_bf16 v[104:107], v[148:151], v[204:207], v[104:107]
	v_mfma_f32_16x16x32_bf16 v[32:35], v[152:155], v[204:207], v[32:35]
	v_mfma_f32_16x16x32_bf16 v[40:43], v[156:159], v[204:207], v[40:43]
	ds_read_b128 v[204:207], v246 offset:6144
	s_waitcnt lgkmcnt(3)
	v_mfma_f32_16x16x32_bf16 v[100:103], v[144:147], v[242:245], v[100:103]
	v_mfma_f32_16x16x32_bf16 v[108:111], v[148:151], v[242:245], v[108:111]
	v_mfma_f32_16x16x32_bf16 v[36:39], v[152:155], v[242:245], v[36:39]
	v_mfma_f32_16x16x32_bf16 v[44:47], v[156:159], v[242:245], v[44:47]
	ds_read_b128 v[242:245], v246 offset:7168
	s_waitcnt lgkmcnt(3)
	v_mfma_f32_16x16x32_bf16 v[80:83], v[144:147], v[196:199], v[80:83]
	v_mfma_f32_16x16x32_bf16 v[88:91], v[148:151], v[196:199], v[88:91]
	v_mfma_f32_16x16x32_bf16 v[16:19], v[152:155], v[196:199], v[16:19]
	v_mfma_f32_16x16x32_bf16 v[24:27], v[156:159], v[196:199], v[24:27]
	s_waitcnt lgkmcnt(2)
	v_mfma_f32_16x16x32_bf16 v[84:87], v[144:147], v[200:203], v[84:87]
	v_mfma_f32_16x16x32_bf16 v[92:95], v[148:151], v[200:203], v[92:95]
	v_mfma_f32_16x16x32_bf16 v[20:23], v[152:155], v[200:203], v[20:23]
	v_mfma_f32_16x16x32_bf16 v[28:31], v[156:159], v[200:203], v[28:31]
	s_waitcnt lgkmcnt(1)
	v_mfma_f32_16x16x32_bf16 v[64:67], v[144:147], v[204:207], v[64:67]
	v_mfma_f32_16x16x32_bf16 v[72:75], v[148:151], v[204:207], v[72:75]
	v_mfma_f32_16x16x32_bf16 v[0:3], v[152:155], v[204:207], v[0:3]
	v_mfma_f32_16x16x32_bf16 v[8:11], v[156:159], v[204:207], v[8:11]
	s_waitcnt lgkmcnt(0)
	v_mfma_f32_16x16x32_bf16 v[68:71], v[144:147], v[242:245], v[68:71]
	v_mfma_f32_16x16x32_bf16 v[76:79], v[148:151], v[242:245], v[76:79]
	v_mfma_f32_16x16x32_bf16 v[4:7], v[152:155], v[242:245], v[4:7]
	v_mfma_f32_16x16x32_bf16 v[12:15], v[156:159], v[242:245], v[12:15]
	global_load_dwordx4 v[144:147], v[248:249], off
	global_load_dwordx4 v[148:151], v[248:249], off offset:256
	global_load_dwordx4 v[152:155], v[250:251], off
	global_load_dwordx4 v[156:159], v[250:251], off offset:256
	s_waitcnt vmcnt(10)
	s_barrier
	s_add_i32 s9, s8, 6
	s_lshl_b32 s96, s9, 13
	s_mov_b32 m0, vcc_lo
	v_lshl_add_u64 v[160:161], v[188:189], 0, s[96:97]
	global_load_lds_dwordx4 v[160:161], off
	global_load_lds_dwordx4 v[160:161], off offset:1024
	ds_read_b128 v[196:199], v246 offset:8192
	ds_read_b128 v[200:203], v246 offset:9216
	ds_read_b128 v[204:207], v246 offset:10240
	ds_read_b128 v[242:245], v246 offset:11264
	s_add_i32 s9, s8, 6
	s_lshl_b32 s96, s9, 11
	v_lshl_add_u64 v[248:249], v[184:185], 0, s[96:97]
	v_lshl_add_u64 v[250:251], v[186:187], 0, s[96:97]
	s_waitcnt vmcnt(8) lgkmcnt(3)
	v_mfma_f32_16x16x32_bf16 v[112:115], v[128:131], v[196:199], v[112:115]
	v_mfma_f32_16x16x32_bf16 v[120:123], v[132:135], v[196:199], v[120:123]
	v_mfma_f32_16x16x32_bf16 v[48:51], v[136:139], v[196:199], v[48:51]
	v_mfma_f32_16x16x32_bf16 v[56:59], v[140:143], v[196:199], v[56:59]
	ds_read_b128 v[196:199], v246 offset:12288
	s_waitcnt lgkmcnt(3)
	v_mfma_f32_16x16x32_bf16 v[116:119], v[128:131], v[200:203], v[116:119]
	v_mfma_f32_16x16x32_bf16 v[124:127], v[132:135], v[200:203], v[124:127]
	v_mfma_f32_16x16x32_bf16 v[52:55], v[136:139], v[200:203], v[52:55]
	v_mfma_f32_16x16x32_bf16 v[60:63], v[140:143], v[200:203], v[60:63]
	ds_read_b128 v[200:203], v246 offset:13312
	s_waitcnt lgkmcnt(3)
	v_mfma_f32_16x16x32_bf16 v[96:99], v[128:131], v[204:207], v[96:99]
	v_mfma_f32_16x16x32_bf16 v[104:107], v[132:135], v[204:207], v[104:107]
	v_mfma_f32_16x16x32_bf16 v[32:35], v[136:139], v[204:207], v[32:35]
	v_mfma_f32_16x16x32_bf16 v[40:43], v[140:143], v[204:207], v[40:43]
	ds_read_b128 v[204:207], v246 offset:14336
	s_waitcnt lgkmcnt(3)
	v_mfma_f32_16x16x32_bf16 v[100:103], v[128:131], v[242:245], v[100:103]
	v_mfma_f32_16x16x32_bf16 v[108:111], v[132:135], v[242:245], v[108:111]
	v_mfma_f32_16x16x32_bf16 v[36:39], v[136:139], v[242:245], v[36:39]
	v_mfma_f32_16x16x32_bf16 v[44:47], v[140:143], v[242:245], v[44:47]
	ds_read_b128 v[242:245], v246 offset:15360
	s_waitcnt lgkmcnt(3)
	v_mfma_f32_16x16x32_bf16 v[80:83], v[128:131], v[196:199], v[80:83]
	v_mfma_f32_16x16x32_bf16 v[88:91], v[132:135], v[196:199], v[88:91]
	v_mfma_f32_16x16x32_bf16 v[16:19], v[136:139], v[196:199], v[16:19]
	v_mfma_f32_16x16x32_bf16 v[24:27], v[140:143], v[196:199], v[24:27]
	s_waitcnt lgkmcnt(2)
	v_mfma_f32_16x16x32_bf16 v[84:87], v[128:131], v[200:203], v[84:87]
	v_mfma_f32_16x16x32_bf16 v[92:95], v[132:135], v[200:203], v[92:95]
	v_mfma_f32_16x16x32_bf16 v[20:23], v[136:139], v[200:203], v[20:23]
	v_mfma_f32_16x16x32_bf16 v[28:31], v[140:143], v[200:203], v[28:31]
	s_waitcnt lgkmcnt(1)
	v_mfma_f32_16x16x32_bf16 v[64:67], v[128:131], v[204:207], v[64:67]
	v_mfma_f32_16x16x32_bf16 v[72:75], v[132:135], v[204:207], v[72:75]
	v_mfma_f32_16x16x32_bf16 v[0:3], v[136:139], v[204:207], v[0:3]
	v_mfma_f32_16x16x32_bf16 v[8:11], v[140:143], v[204:207], v[8:11]
	s_waitcnt lgkmcnt(0)
	v_mfma_f32_16x16x32_bf16 v[68:71], v[128:131], v[242:245], v[68:71]
	v_mfma_f32_16x16x32_bf16 v[76:79], v[132:135], v[242:245], v[76:79]
	v_mfma_f32_16x16x32_bf16 v[4:7], v[136:139], v[242:245], v[4:7]
	v_mfma_f32_16x16x32_bf16 v[12:15], v[140:143], v[242:245], v[12:15]
	global_load_dwordx4 v[128:131], v[248:249], off
	global_load_dwordx4 v[132:135], v[248:249], off offset:256
	global_load_dwordx4 v[136:139], v[250:251], off
	global_load_dwordx4 v[140:143], v[250:251], off offset:256
	s_waitcnt vmcnt(10)
	s_barrier
	s_add_i32 s9, s8, 7
	s_lshl_b32 s96, s9, 13
	s_add_i32 m0, vcc_lo, 8192
	v_lshl_add_u64 v[160:161], v[188:189], 0, s[96:97]
	global_load_lds_dwordx4 v[160:161], off
	global_load_lds_dwordx4 v[160:161], off offset:1024
	ds_read_b128 v[196:199], v246 offset:16384
	ds_read_b128 v[200:203], v246 offset:17408
	ds_read_b128 v[204:207], v246 offset:18432
	ds_read_b128 v[242:245], v246 offset:19456
	s_add_i32 s9, s8, 7
	s_lshl_b32 s96, s9, 11
	v_lshl_add_u64 v[248:249], v[184:185], 0, s[96:97]
	v_lshl_add_u64 v[250:251], v[186:187], 0, s[96:97]
	s_waitcnt vmcnt(8) lgkmcnt(3)
	v_mfma_f32_16x16x32_bf16 v[112:115], v[144:147], v[196:199], v[112:115]
	v_mfma_f32_16x16x32_bf16 v[120:123], v[148:151], v[196:199], v[120:123]
	v_mfma_f32_16x16x32_bf16 v[48:51], v[152:155], v[196:199], v[48:51]
	v_mfma_f32_16x16x32_bf16 v[56:59], v[156:159], v[196:199], v[56:59]
	ds_read_b128 v[196:199], v246 offset:20480
	s_waitcnt lgkmcnt(3)
	v_mfma_f32_16x16x32_bf16 v[116:119], v[144:147], v[200:203], v[116:119]
	v_mfma_f32_16x16x32_bf16 v[124:127], v[148:151], v[200:203], v[124:127]
	v_mfma_f32_16x16x32_bf16 v[52:55], v[152:155], v[200:203], v[52:55]
	v_mfma_f32_16x16x32_bf16 v[60:63], v[156:159], v[200:203], v[60:63]
	ds_read_b128 v[200:203], v246 offset:21504
	s_waitcnt lgkmcnt(3)
	v_mfma_f32_16x16x32_bf16 v[96:99], v[144:147], v[204:207], v[96:99]
	v_mfma_f32_16x16x32_bf16 v[104:107], v[148:151], v[204:207], v[104:107]
	v_mfma_f32_16x16x32_bf16 v[32:35], v[152:155], v[204:207], v[32:35]
	v_mfma_f32_16x16x32_bf16 v[40:43], v[156:159], v[204:207], v[40:43]
	ds_read_b128 v[204:207], v246 offset:22528
	s_waitcnt lgkmcnt(3)
	v_mfma_f32_16x16x32_bf16 v[100:103], v[144:147], v[242:245], v[100:103]
	v_mfma_f32_16x16x32_bf16 v[108:111], v[148:151], v[242:245], v[108:111]
	v_mfma_f32_16x16x32_bf16 v[36:39], v[152:155], v[242:245], v[36:39]
	v_mfma_f32_16x16x32_bf16 v[44:47], v[156:159], v[242:245], v[44:47]
	ds_read_b128 v[242:245], v246 offset:23552
	s_waitcnt lgkmcnt(3)
	v_mfma_f32_16x16x32_bf16 v[80:83], v[144:147], v[196:199], v[80:83]
	v_mfma_f32_16x16x32_bf16 v[88:91], v[148:151], v[196:199], v[88:91]
	v_mfma_f32_16x16x32_bf16 v[16:19], v[152:155], v[196:199], v[16:19]
	v_mfma_f32_16x16x32_bf16 v[24:27], v[156:159], v[196:199], v[24:27]
	s_waitcnt lgkmcnt(2)
	v_mfma_f32_16x16x32_bf16 v[84:87], v[144:147], v[200:203], v[84:87]
	v_mfma_f32_16x16x32_bf16 v[92:95], v[148:151], v[200:203], v[92:95]
	v_mfma_f32_16x16x32_bf16 v[20:23], v[152:155], v[200:203], v[20:23]
	v_mfma_f32_16x16x32_bf16 v[28:31], v[156:159], v[200:203], v[28:31]
	s_waitcnt lgkmcnt(1)
	v_mfma_f32_16x16x32_bf16 v[64:67], v[144:147], v[204:207], v[64:67]
	v_mfma_f32_16x16x32_bf16 v[72:75], v[148:151], v[204:207], v[72:75]
	v_mfma_f32_16x16x32_bf16 v[0:3], v[152:155], v[204:207], v[0:3]
	v_mfma_f32_16x16x32_bf16 v[8:11], v[156:159], v[204:207], v[8:11]
	s_waitcnt lgkmcnt(0)
	v_mfma_f32_16x16x32_bf16 v[68:71], v[144:147], v[242:245], v[68:71]
	v_mfma_f32_16x16x32_bf16 v[76:79], v[148:151], v[242:245], v[76:79]
	v_mfma_f32_16x16x32_bf16 v[4:7], v[152:155], v[242:245], v[4:7]
	v_mfma_f32_16x16x32_bf16 v[12:15], v[156:159], v[242:245], v[12:15]
	global_load_dwordx4 v[144:147], v[248:249], off
	global_load_dwordx4 v[148:151], v[248:249], off offset:256
	global_load_dwordx4 v[152:155], v[250:251], off
	global_load_dwordx4 v[156:159], v[250:251], off offset:256
	s_waitcnt vmcnt(10)
	s_barrier
	s_add_i32 s8, s8, 6
	s_cmp_lt_u32 s8, 84
	s_cbranch_scc1 .Lg16_down_k
	s_mov_b32 s96, 0xac000
	s_add_i32 m0, vcc_lo, 16384
	v_lshl_add_u64 v[160:161], v[188:189], 0, s[96:97]
	global_load_lds_dwordx4 v[160:161], off
	global_load_lds_dwordx4 v[160:161], off offset:1024
	ds_read_b128 v[196:199], v246 offset:0
	ds_read_b128 v[200:203], v246 offset:1024
	ds_read_b128 v[204:207], v246 offset:2048
	ds_read_b128 v[242:245], v246 offset:3072
	s_mov_b32 s96, 0x2b000
	v_lshl_add_u64 v[248:249], v[184:185], 0, s[96:97]
	v_lshl_add_u64 v[250:251], v[186:187], 0, s[96:97]
	s_waitcnt vmcnt(8) lgkmcnt(3)
	v_mfma_f32_16x16x32_bf16 v[112:115], v[128:131], v[196:199], v[112:115]
	v_mfma_f32_16x16x32_bf16 v[120:123], v[132:135], v[196:199], v[120:123]
	v_mfma_f32_16x16x32_bf16 v[48:51], v[136:139], v[196:199], v[48:51]
	v_mfma_f32_16x16x32_bf16 v[56:59], v[140:143], v[196:199], v[56:59]
	ds_read_b128 v[196:199], v246 offset:4096
	s_waitcnt lgkmcnt(3)
	v_mfma_f32_16x16x32_bf16 v[116:119], v[128:131], v[200:203], v[116:119]
	v_mfma_f32_16x16x32_bf16 v[124:127], v[132:135], v[200:203], v[124:127]
	v_mfma_f32_16x16x32_bf16 v[52:55], v[136:139], v[200:203], v[52:55]
	v_mfma_f32_16x16x32_bf16 v[60:63], v[140:143], v[200:203], v[60:63]
	ds_read_b128 v[200:203], v246 offset:5120
	s_waitcnt lgkmcnt(3)
	v_mfma_f32_16x16x32_bf16 v[96:99], v[128:131], v[204:207], v[96:99]
	v_mfma_f32_16x16x32_bf16 v[104:107], v[132:135], v[204:207], v[104:107]
	v_mfma_f32_16x16x32_bf16 v[32:35], v[136:139], v[204:207], v[32:35]
	v_mfma_f32_16x16x32_bf16 v[40:43], v[140:143], v[204:207], v[40:43]
	ds_read_b128 v[204:207], v246 offset:6144
	s_waitcnt lgkmcnt(3)
	v_mfma_f32_16x16x32_bf16 v[100:103], v[128:131], v[242:245], v[100:103]
	v_mfma_f32_16x16x32_bf16 v[108:111], v[132:135], v[242:245], v[108:111]
	v_mfma_f32_16x16x32_bf16 v[36:39], v[136:139], v[242:245], v[36:39]
	v_mfma_f32_16x16x32_bf16 v[44:47], v[140:143], v[242:245], v[44:47]
	ds_read_b128 v[242:245], v246 offset:7168
	s_waitcnt lgkmcnt(3)
	v_mfma_f32_16x16x32_bf16 v[80:83], v[128:131], v[196:199], v[80:83]
	v_mfma_f32_16x16x32_bf16 v[88:91], v[132:135], v[196:199], v[88:91]
	v_mfma_f32_16x16x32_bf16 v[16:19], v[136:139], v[196:199], v[16:19]
	v_mfma_f32_16x16x32_bf16 v[24:27], v[140:143], v[196:199], v[24:27]
	s_waitcnt lgkmcnt(2)
	v_mfma_f32_16x16x32_bf16 v[84:87], v[128:131], v[200:203], v[84:87]
	v_mfma_f32_16x16x32_bf16 v[92:95], v[132:135], v[200:203], v[92:95]
	v_mfma_f32_16x16x32_bf16 v[20:23], v[136:139], v[200:203], v[20:23]
	v_mfma_f32_16x16x32_bf16 v[28:31], v[140:143], v[200:203], v[28:31]
	s_waitcnt lgkmcnt(1)
	v_mfma_f32_16x16x32_bf16 v[64:67], v[128:131], v[204:207], v[64:67]
	v_mfma_f32_16x16x32_bf16 v[72:75], v[132:135], v[204:207], v[72:75]
	v_mfma_f32_16x16x32_bf16 v[0:3], v[136:139], v[204:207], v[0:3]
	v_mfma_f32_16x16x32_bf16 v[8:11], v[140:143], v[204:207], v[8:11]
	s_waitcnt lgkmcnt(0)
	v_mfma_f32_16x16x32_bf16 v[68:71], v[128:131], v[242:245], v[68:71]
	v_mfma_f32_16x16x32_bf16 v[76:79], v[132:135], v[242:245], v[76:79]
	v_mfma_f32_16x16x32_bf16 v[4:7], v[136:139], v[242:245], v[4:7]
	v_mfma_f32_16x16x32_bf16 v[12:15], v[140:143], v[242:245], v[12:15]
	global_load_dwordx4 v[128:131], v[248:249], off
	global_load_dwordx4 v[132:135], v[248:249], off offset:256
	global_load_dwordx4 v[136:139], v[250:251], off
	global_load_dwordx4 v[140:143], v[250:251], off offset:256
	s_waitcnt vmcnt(10)
	s_barrier
	s_mov_b32 s96, 0xae000
	s_mov_b32 m0, vcc_lo
	v_lshl_add_u64 v[160:161], v[188:189], 0, s[96:97]
	global_load_lds_dwordx4 v[160:161], off
	global_load_lds_dwordx4 v[160:161], off offset:1024
	ds_read_b128 v[196:199], v246 offset:8192
	ds_read_b128 v[200:203], v246 offset:9216
	ds_read_b128 v[204:207], v246 offset:10240
	ds_read_b128 v[242:245], v246 offset:11264
	s_mov_b32 s96, 0x2b800
	v_lshl_add_u64 v[248:249], v[184:185], 0, s[96:97]
	v_lshl_add_u64 v[250:251], v[186:187], 0, s[96:97]
	s_waitcnt vmcnt(8) lgkmcnt(3)
	v_mfma_f32_16x16x32_bf16 v[112:115], v[144:147], v[196:199], v[112:115]
	v_mfma_f32_16x16x32_bf16 v[120:123], v[148:151], v[196:199], v[120:123]
	v_mfma_f32_16x16x32_bf16 v[48:51], v[152:155], v[196:199], v[48:51]
	v_mfma_f32_16x16x32_bf16 v[56:59], v[156:159], v[196:199], v[56:59]
	ds_read_b128 v[196:199], v246 offset:12288
	s_waitcnt lgkmcnt(3)
	v_mfma_f32_16x16x32_bf16 v[116:119], v[144:147], v[200:203], v[116:119]
	v_mfma_f32_16x16x32_bf16 v[124:127], v[148:151], v[200:203], v[124:127]
	v_mfma_f32_16x16x32_bf16 v[52:55], v[152:155], v[200:203], v[52:55]
	v_mfma_f32_16x16x32_bf16 v[60:63], v[156:159], v[200:203], v[60:63]
	ds_read_b128 v[200:203], v246 offset:13312
	s_waitcnt lgkmcnt(3)
	v_mfma_f32_16x16x32_bf16 v[96:99], v[144:147], v[204:207], v[96:99]
	v_mfma_f32_16x16x32_bf16 v[104:107], v[148:151], v[204:207], v[104:107]
	v_mfma_f32_16x16x32_bf16 v[32:35], v[152:155], v[204:207], v[32:35]
	v_mfma_f32_16x16x32_bf16 v[40:43], v[156:159], v[204:207], v[40:43]
	ds_read_b128 v[204:207], v246 offset:14336
	s_waitcnt lgkmcnt(3)
	v_mfma_f32_16x16x32_bf16 v[100:103], v[144:147], v[242:245], v[100:103]
	v_mfma_f32_16x16x32_bf16 v[108:111], v[148:151], v[242:245], v[108:111]
	v_mfma_f32_16x16x32_bf16 v[36:39], v[152:155], v[242:245], v[36:39]
	v_mfma_f32_16x16x32_bf16 v[44:47], v[156:159], v[242:245], v[44:47]
	ds_read_b128 v[242:245], v246 offset:15360
	s_waitcnt lgkmcnt(3)
	v_mfma_f32_16x16x32_bf16 v[80:83], v[144:147], v[196:199], v[80:83]
	v_mfma_f32_16x16x32_bf16 v[88:91], v[148:151], v[196:199], v[88:91]
	v_mfma_f32_16x16x32_bf16 v[16:19], v[152:155], v[196:199], v[16:19]
	v_mfma_f32_16x16x32_bf16 v[24:27], v[156:159], v[196:199], v[24:27]
	s_waitcnt lgkmcnt(2)
	v_mfma_f32_16x16x32_bf16 v[84:87], v[144:147], v[200:203], v[84:87]
	v_mfma_f32_16x16x32_bf16 v[92:95], v[148:151], v[200:203], v[92:95]
	v_mfma_f32_16x16x32_bf16 v[20:23], v[152:155], v[200:203], v[20:23]
	v_mfma_f32_16x16x32_bf16 v[28:31], v[156:159], v[200:203], v[28:31]
	s_waitcnt lgkmcnt(1)
	v_mfma_f32_16x16x32_bf16 v[64:67], v[144:147], v[204:207], v[64:67]
	v_mfma_f32_16x16x32_bf16 v[72:75], v[148:151], v[204:207], v[72:75]
	v_mfma_f32_16x16x32_bf16 v[0:3], v[152:155], v[204:207], v[0:3]
	v_mfma_f32_16x16x32_bf16 v[8:11], v[156:159], v[204:207], v[8:11]
	s_waitcnt lgkmcnt(0)
	v_mfma_f32_16x16x32_bf16 v[68:71], v[144:147], v[242:245], v[68:71]
	v_mfma_f32_16x16x32_bf16 v[76:79], v[148:151], v[242:245], v[76:79]
	v_mfma_f32_16x16x32_bf16 v[4:7], v[152:155], v[242:245], v[4:7]
	v_mfma_f32_16x16x32_bf16 v[12:15], v[156:159], v[242:245], v[12:15]
	global_load_dwordx4 v[144:147], v[248:249], off
	global_load_dwordx4 v[148:151], v[248:249], off offset:256
	global_load_dwordx4 v[152:155], v[250:251], off
	global_load_dwordx4 v[156:159], v[250:251], off offset:256
	s_waitcnt vmcnt(10)
	s_barrier
	ds_read_b128 v[196:199], v246 offset:16384
	ds_read_b128 v[200:203], v246 offset:17408
	ds_read_b128 v[204:207], v246 offset:18432
	ds_read_b128 v[242:245], v246 offset:19456
	s_waitcnt vmcnt(6) lgkmcnt(3)
	v_mfma_f32_16x16x32_bf16 v[112:115], v[128:131], v[196:199], v[112:115]
	v_mfma_f32_16x16x32_bf16 v[120:123], v[132:135], v[196:199], v[120:123]
	v_mfma_f32_16x16x32_bf16 v[48:51], v[136:139], v[196:199], v[48:51]
	v_mfma_f32_16x16x32_bf16 v[56:59], v[140:143], v[196:199], v[56:59]
	ds_read_b128 v[196:199], v246 offset:20480
	s_waitcnt lgkmcnt(3)
	v_mfma_f32_16x16x32_bf16 v[116:119], v[128:131], v[200:203], v[116:119]
	v_mfma_f32_16x16x32_bf16 v[124:127], v[132:135], v[200:203], v[124:127]
	v_mfma_f32_16x16x32_bf16 v[52:55], v[136:139], v[200:203], v[52:55]
	v_mfma_f32_16x16x32_bf16 v[60:63], v[140:143], v[200:203], v[60:63]
	ds_read_b128 v[200:203], v246 offset:21504
	s_waitcnt lgkmcnt(3)
	v_mfma_f32_16x16x32_bf16 v[96:99], v[128:131], v[204:207], v[96:99]
	v_mfma_f32_16x16x32_bf16 v[104:107], v[132:135], v[204:207], v[104:107]
	v_mfma_f32_16x16x32_bf16 v[32:35], v[136:139], v[204:207], v[32:35]
	v_mfma_f32_16x16x32_bf16 v[40:43], v[140:143], v[204:207], v[40:43]
	ds_read_b128 v[204:207], v246 offset:22528
	s_waitcnt lgkmcnt(3)
	v_mfma_f32_16x16x32_bf16 v[100:103], v[128:131], v[242:245], v[100:103]
	v_mfma_f32_16x16x32_bf16 v[108:111], v[132:135], v[242:245], v[108:111]
	v_mfma_f32_16x16x32_bf16 v[36:39], v[136:139], v[242:245], v[36:39]
	v_mfma_f32_16x16x32_bf16 v[44:47], v[140:143], v[242:245], v[44:47]
	ds_read_b128 v[242:245], v246 offset:23552
	s_waitcnt lgkmcnt(3)
	v_mfma_f32_16x16x32_bf16 v[80:83], v[128:131], v[196:199], v[80:83]
	v_mfma_f32_16x16x32_bf16 v[88:91], v[132:135], v[196:199], v[88:91]
	v_mfma_f32_16x16x32_bf16 v[16:19], v[136:139], v[196:199], v[16:19]
	v_mfma_f32_16x16x32_bf16 v[24:27], v[140:143], v[196:199], v[24:27]
	s_waitcnt lgkmcnt(2)
	v_mfma_f32_16x16x32_bf16 v[84:87], v[128:131], v[200:203], v[84:87]
	v_mfma_f32_16x16x32_bf16 v[92:95], v[132:135], v[200:203], v[92:95]
	v_mfma_f32_16x16x32_bf16 v[20:23], v[136:139], v[200:203], v[20:23]
	v_mfma_f32_16x16x32_bf16 v[28:31], v[140:143], v[200:203], v[28:31]
	s_waitcnt lgkmcnt(1)
	v_mfma_f32_16x16x32_bf16 v[64:67], v[128:131], v[204:207], v[64:67]
	v_mfma_f32_16x16x32_bf16 v[72:75], v[132:135], v[204:207], v[72:75]
	v_mfma_f32_16x16x32_bf16 v[0:3], v[136:139], v[204:207], v[0:3]
	v_mfma_f32_16x16x32_bf16 v[8:11], v[140:143], v[204:207], v[8:11]
	s_waitcnt lgkmcnt(0)
	v_mfma_f32_16x16x32_bf16 v[68:71], v[128:131], v[242:245], v[68:71]
	v_mfma_f32_16x16x32_bf16 v[76:79], v[132:135], v[242:245], v[76:79]
	v_mfma_f32_16x16x32_bf16 v[4:7], v[136:139], v[242:245], v[4:7]
	v_mfma_f32_16x16x32_bf16 v[12:15], v[140:143], v[242:245], v[12:15]
	s_waitcnt vmcnt(4)
	s_barrier
	ds_read_b128 v[196:199], v246 offset:0
	ds_read_b128 v[200:203], v246 offset:1024
	ds_read_b128 v[204:207], v246 offset:2048
	ds_read_b128 v[242:245], v246 offset:3072
	s_waitcnt vmcnt(0) lgkmcnt(3)
	v_mfma_f32_16x16x32_bf16 v[112:115], v[144:147], v[196:199], v[112:115]
	v_mfma_f32_16x16x32_bf16 v[120:123], v[148:151], v[196:199], v[120:123]
	v_mfma_f32_16x16x32_bf16 v[48:51], v[152:155], v[196:199], v[48:51]
	v_mfma_f32_16x16x32_bf16 v[56:59], v[156:159], v[196:199], v[56:59]
	ds_read_b128 v[196:199], v246 offset:4096
	s_waitcnt lgkmcnt(3)
	v_mfma_f32_16x16x32_bf16 v[116:119], v[144:147], v[200:203], v[116:119]
	v_mfma_f32_16x16x32_bf16 v[124:127], v[148:151], v[200:203], v[124:127]
	v_mfma_f32_16x16x32_bf16 v[52:55], v[152:155], v[200:203], v[52:55]
	v_mfma_f32_16x16x32_bf16 v[60:63], v[156:159], v[200:203], v[60:63]
	ds_read_b128 v[200:203], v246 offset:5120
	s_waitcnt lgkmcnt(3)
	v_mfma_f32_16x16x32_bf16 v[96:99], v[144:147], v[204:207], v[96:99]
	v_mfma_f32_16x16x32_bf16 v[104:107], v[148:151], v[204:207], v[104:107]
	v_mfma_f32_16x16x32_bf16 v[32:35], v[152:155], v[204:207], v[32:35]
	v_mfma_f32_16x16x32_bf16 v[40:43], v[156:159], v[204:207], v[40:43]
	ds_read_b128 v[204:207], v246 offset:6144
	s_waitcnt lgkmcnt(3)
	v_mfma_f32_16x16x32_bf16 v[100:103], v[144:147], v[242:245], v[100:103]
	v_mfma_f32_16x16x32_bf16 v[108:111], v[148:151], v[242:245], v[108:111]
	v_mfma_f32_16x16x32_bf16 v[36:39], v[152:155], v[242:245], v[36:39]
	v_mfma_f32_16x16x32_bf16 v[44:47], v[156:159], v[242:245], v[44:47]
	ds_read_b128 v[242:245], v246 offset:7168
	v_permlane16_swap_b32_e32 v112, v116
	v_permlane16_swap_b32_e32 v113, v117
	v_permlane16_swap_b32_e32 v114, v118
	v_permlane16_swap_b32_e32 v115, v119
	v_permlane16_swap_b32_e32 v120, v124
	v_permlane16_swap_b32_e32 v121, v125
	v_permlane16_swap_b32_e32 v122, v126
	v_permlane16_swap_b32_e32 v123, v127
	v_permlane16_swap_b32_e32 v48, v52
	v_permlane16_swap_b32_e32 v49, v53
	v_permlane16_swap_b32_e32 v50, v54
	v_permlane16_swap_b32_e32 v51, v55
	v_permlane16_swap_b32_e32 v56, v60
	v_permlane16_swap_b32_e32 v57, v61
	v_permlane16_swap_b32_e32 v58, v62
	v_permlane16_swap_b32_e32 v59, v63
	v_permlane32_swap_b32_e32 v112, v116
	v_permlane32_swap_b32_e32 v113, v117
	v_permlane32_swap_b32_e32 v114, v118
	v_permlane32_swap_b32_e32 v115, v119
	v_permlane32_swap_b32_e32 v120, v124
	v_permlane32_swap_b32_e32 v121, v125
	v_permlane32_swap_b32_e32 v122, v126
	v_permlane32_swap_b32_e32 v123, v127
	v_permlane32_swap_b32_e32 v48, v52
	v_permlane32_swap_b32_e32 v49, v53
	v_permlane32_swap_b32_e32 v50, v54
	v_permlane32_swap_b32_e32 v51, v55
	v_permlane32_swap_b32_e32 v56, v60
	v_permlane32_swap_b32_e32 v57, v61
	v_permlane32_swap_b32_e32 v58, v62
	v_permlane32_swap_b32_e32 v59, v63
	s_waitcnt lgkmcnt(3)
	v_mfma_f32_16x16x32_bf16 v[80:83], v[144:147], v[196:199], v[80:83]
	v_mfma_f32_16x16x32_bf16 v[88:91], v[148:151], v[196:199], v[88:91]
	v_mfma_f32_16x16x32_bf16 v[16:19], v[152:155], v[196:199], v[16:19]
	v_mfma_f32_16x16x32_bf16 v[24:27], v[156:159], v[196:199], v[24:27]
	s_waitcnt lgkmcnt(2)
	v_mfma_f32_16x16x32_bf16 v[84:87], v[144:147], v[200:203], v[84:87]
	v_mfma_f32_16x16x32_bf16 v[92:95], v[148:151], v[200:203], v[92:95]
	v_mfma_f32_16x16x32_bf16 v[20:23], v[152:155], v[200:203], v[20:23]
	v_mfma_f32_16x16x32_bf16 v[28:31], v[156:159], v[200:203], v[28:31]
	v_permlane16_swap_b32_e32 v96, v100
	v_permlane16_swap_b32_e32 v97, v101
	v_permlane16_swap_b32_e32 v98, v102
	v_permlane16_swap_b32_e32 v99, v103
	v_permlane16_swap_b32_e32 v104, v108
	v_permlane16_swap_b32_e32 v105, v109
	v_permlane16_swap_b32_e32 v106, v110
	v_permlane16_swap_b32_e32 v107, v111
	v_permlane16_swap_b32_e32 v32, v36
	v_permlane16_swap_b32_e32 v33, v37
	v_permlane16_swap_b32_e32 v34, v38
	v_permlane16_swap_b32_e32 v35, v39
	v_permlane16_swap_b32_e32 v40, v44
	v_permlane16_swap_b32_e32 v41, v45
	v_permlane16_swap_b32_e32 v42, v46
	v_permlane16_swap_b32_e32 v43, v47
	v_permlane32_swap_b32_e32 v96, v100
	v_permlane32_swap_b32_e32 v97, v101
	v_permlane32_swap_b32_e32 v98, v102
	v_permlane32_swap_b32_e32 v99, v103
	v_permlane32_swap_b32_e32 v104, v108
	v_permlane32_swap_b32_e32 v105, v109
	v_permlane32_swap_b32_e32 v106, v110
	v_permlane32_swap_b32_e32 v107, v111
	v_permlane32_swap_b32_e32 v32, v36
	v_permlane32_swap_b32_e32 v33, v37
	v_permlane32_swap_b32_e32 v34, v38
	v_permlane32_swap_b32_e32 v35, v39
	v_permlane32_swap_b32_e32 v40, v44
	v_permlane32_swap_b32_e32 v41, v45
	v_permlane32_swap_b32_e32 v42, v46
	v_permlane32_swap_b32_e32 v43, v47
	s_waitcnt lgkmcnt(1)
	v_mfma_f32_16x16x32_bf16 v[64:67], v[144:147], v[204:207], v[64:67]
	v_mfma_f32_16x16x32_bf16 v[72:75], v[148:151], v[204:207], v[72:75]
	v_mfma_f32_16x16x32_bf16 v[0:3], v[152:155], v[204:207], v[0:3]
	v_mfma_f32_16x16x32_bf16 v[8:11], v[156:159], v[204:207], v[8:11]
	s_waitcnt lgkmcnt(0)
	v_mfma_f32_16x16x32_bf16 v[68:71], v[144:147], v[242:245], v[68:71]
	v_mfma_f32_16x16x32_bf16 v[76:79], v[148:151], v[242:245], v[76:79]
	v_mfma_f32_16x16x32_bf16 v[4:7], v[152:155], v[242:245], v[4:7]
	v_mfma_f32_16x16x32_bf16 v[12:15], v[156:159], v[242:245], v[12:15]
	v_permlane16_swap_b32_e32 v80, v84
	v_permlane16_swap_b32_e32 v81, v85
	v_permlane16_swap_b32_e32 v82, v86
	v_permlane16_swap_b32_e32 v83, v87
	v_permlane16_swap_b32_e32 v88, v92
	v_permlane16_swap_b32_e32 v89, v93
	v_permlane16_swap_b32_e32 v90, v94
	v_permlane16_swap_b32_e32 v91, v95
	v_permlane16_swap_b32_e32 v16, v20
	v_permlane16_swap_b32_e32 v17, v21
	v_permlane16_swap_b32_e32 v18, v22
	v_permlane16_swap_b32_e32 v19, v23
	v_permlane16_swap_b32_e32 v24, v28
	v_permlane16_swap_b32_e32 v25, v29
	v_permlane16_swap_b32_e32 v26, v30
	v_permlane16_swap_b32_e32 v27, v31
	v_permlane32_swap_b32_e32 v80, v84
	v_permlane32_swap_b32_e32 v81, v85
	v_permlane32_swap_b32_e32 v82, v86
	v_permlane32_swap_b32_e32 v83, v87
	v_permlane32_swap_b32_e32 v88, v92
	v_permlane32_swap_b32_e32 v89, v93
	v_permlane32_swap_b32_e32 v90, v94
	v_permlane32_swap_b32_e32 v91, v95
	v_permlane32_swap_b32_e32 v16, v20
	v_permlane32_swap_b32_e32 v17, v21
	v_permlane32_swap_b32_e32 v18, v22
	v_permlane32_swap_b32_e32 v19, v23
	v_permlane32_swap_b32_e32 v24, v28
	v_permlane32_swap_b32_e32 v25, v29
	v_permlane32_swap_b32_e32 v26, v30
	v_permlane32_swap_b32_e32 v27, v31
	s_barrier
	s_nop 7
	v_permlane16_swap_b32_e32 v64, v68
	v_permlane16_swap_b32_e32 v65, v69
	v_permlane16_swap_b32_e32 v66, v70
	v_permlane16_swap_b32_e32 v67, v71
	v_permlane16_swap_b32_e32 v72, v76
	v_permlane16_swap_b32_e32 v73, v77
	v_permlane16_swap_b32_e32 v74, v78
	v_permlane16_swap_b32_e32 v75, v79
	v_permlane16_swap_b32_e32 v0, v4
	v_permlane16_swap_b32_e32 v1, v5
	v_permlane16_swap_b32_e32 v2, v6
	v_permlane16_swap_b32_e32 v3, v7
	v_permlane16_swap_b32_e32 v8, v12
	v_permlane16_swap_b32_e32 v9, v13
	v_permlane16_swap_b32_e32 v10, v14
	v_permlane16_swap_b32_e32 v11, v15
	v_permlane32_swap_b32_e32 v64, v68
	v_permlane32_swap_b32_e32 v65, v69
	v_permlane32_swap_b32_e32 v66, v70
	v_permlane32_swap_b32_e32 v67, v71
	v_permlane32_swap_b32_e32 v72, v76
	v_permlane32_swap_b32_e32 v73, v77
	v_permlane32_swap_b32_e32 v74, v78
	v_permlane32_swap_b32_e32 v75, v79
	v_permlane32_swap_b32_e32 v0, v4
	v_permlane32_swap_b32_e32 v1, v5
	v_permlane32_swap_b32_e32 v2, v6
	v_permlane32_swap_b32_e32 v3, v7
	v_permlane32_swap_b32_e32 v8, v12
	v_permlane32_swap_b32_e32 v9, v13
	v_permlane32_swap_b32_e32 v10, v14
	v_permlane32_swap_b32_e32 v11, v15
	s_waitcnt vmcnt(0)
	s_movk_i32 s8, 0x2400
	s_waitcnt vmcnt(0)
	v_and_b32_e32 v132, 0xffffffc0, v181
	v_mul_lo_u32 v129, v237, s8
	v_lshlrev_b32_e32 v130, 2, v238
	v_lshl_add_u32 v156, s7, 8, v132
	v_mul_u32_u24_e32 v132, 0x110, v183
	v_or_b32_e32 v131, v129, v130
	v_lshlrev_b32_e32 v132, 2, v132
	v_add_u32_e32 v131, v131, v132
	v_add3_u32 v132, v129, v132, v130
	v_readlane_b32 s8, v253, 36
	v_lshlrev_b32_e32 v128, 2, v181
	v_add_u32_e32 v133, 0x800, v131
	v_add_u32_e32 v134, 0x800, v132
	v_lshrrev_b32_e32 v155, 4, v239
	v_readlane_b32 s12, v253, 40
	v_readlane_b32 s13, v253, 41
	v_readlane_b32 s14, v253, 42
	v_readlane_b32 s15, v253, 43
	v_readlane_b32 s16, v253, 44
	v_readlane_b32 s17, v253, 45
	v_readlane_b32 s18, v253, 46
	v_readlane_b32 s19, v253, 47
	v_and_b32_e32 v128, 60, v128
	ds_write2_b32 v131, v112, v113 offset1:68
	ds_write2_b32 v132, v96, v97 offset0:32 offset1:100
	ds_write2_b32 v131, v114, v115 offset0:136 offset1:204
	ds_write2_b32 v132, v98, v99 offset0:168 offset1:236
	ds_write2_b32 v133, v116, v117 offset0:32 offset1:100
	ds_write2_b32 v134, v100, v101 offset0:64 offset1:132
	ds_write2_b32 v133, v118, v119 offset0:168 offset1:236
	v_or_b32_e32 v100, v156, v155
	v_readlane_b32 s20, v253, 48
	v_readlane_b32 s21, v253, 49
	v_readlane_b32 s22, v253, 50
	v_readlane_b32 s23, v253, 51
	s_mov_b64 s[12:13], s[16:17]
	v_lshl_or_b32 v144, v128, 2, v129
	v_lshl_or_b32 v128, s6, 7, v128
	s_movk_i32 s6, 0x110
	v_cmp_gt_i32_e32 vcc, s39, v100
	v_add_u32_e32 v96, 0xffff8000, v100
	v_ashrrev_i32_e32 v97, 31, v100
	s_mov_b64 s[14:15], s[18:19]
	v_mad_u32_u24 v130, v155, s6, v144
	v_cndmask_b32_e32 v97, 0, v97, vcc
	v_cndmask_b32_e32 v96, v96, v100, vcc
	v_mov_b32_e32 v144, s63
	v_mov_b32_e32 v145, s15
	v_mov_b32_e32 v146, s62
	v_mov_b32_e32 v147, s14
	v_min_i32_e32 v100, 0x8000, v100
	v_add_u32_e32 v135, 0xa00, v132
	v_add_u32_e32 v136, 0x1000, v131
	v_add_u32_e32 v137, 0x1000, v132
	v_add_u32_e32 v138, 0x1200, v131
	v_add_u32_e32 v139, 0x1200, v132
	v_add_u32_e32 v140, 0x1800, v131
	v_add_u32_e32 v141, 0x1800, v132
	v_add_u32_e32 v142, 0x1a00, v131
	v_add_u32_e32 v143, 0x1c00, v132
	v_ashrrev_i32_e32 v129, 31, v128
	v_cndmask_b32_e32 v99, v144, v145, vcc
	v_cndmask_b32_e32 v98, v146, v147, vcc
	v_lshlrev_b64 v[96:97], 12, v[96:97]
	v_ashrrev_i32_e32 v100, 12, v100
	ds_write2_b32 v135, v102, v103 offset0:72 offset1:140
	ds_write2_b32 v136, v120, v121 offset0:64 offset1:132
	ds_write2_b32 v137, v104, v105 offset0:96 offset1:164
	ds_write2_b32 v138, v122, v123 offset0:72 offset1:140
	ds_write2_b32 v139, v106, v107 offset0:104 offset1:172
	ds_write2_b32 v140, v124, v125 offset0:96 offset1:164
	ds_write2_b32 v141, v108, v109 offset0:128 offset1:196
	ds_write2_b32 v142, v126, v127 offset0:104 offset1:172
	ds_write2_b32 v143, v110, v111 offset0:8 offset1:76
	v_lshl_add_u64 v[98:99], v[98:99], 0, v[96:97]
	v_lshlrev_b64 v[96:97], 2, v[128:129]
	v_mul_hi_i32_i24_e32 v101, 0x6000, v100
	v_mul_i32_i24_e32 v100, 0x6000, v100
	s_waitcnt lgkmcnt(0)
	v_lshl_add_u64 v[98:99], v[98:99], 0, v[96:97]
	v_lshl_add_u64 v[100:101], s[0:1], 0, v[100:101]
	v_lshl_add_u64 v[100:101], v[100:101], 0, v[96:97]
	ds_read_b128 v[102:105], v130
	global_load_dwordx4 v[106:109], v[98:99], off
	global_load_dwordx4 v[110:113], v[100:101], off
	v_or_b32_e32 v148, 4, v155
	v_or_b32_e32 v149, 8, v155
	v_or_b32_e32 v150, 12, v155
	v_or_b32_e32 v151, 16, v155
	v_or_b32_e32 v152, 20, v155
	v_or_b32_e32 v153, 24, v155
	v_or_b32_e32 v154, 28, v155
	v_or_b32_e32 v157, v156, v154
	v_readlane_b32 s6, v254, 11
	s_add_i32 s2, s2, s6
	s_cmp_lt_i32 s2, s26
	v_readlane_b32 s9, v253, 37
	v_readlane_b32 s10, v253, 38
	v_readlane_b32 s11, v253, 39
	s_mov_b64 s[16:17], s[20:21]
	s_mov_b64 s[18:19], s[22:23]
	s_waitcnt vmcnt(0) lgkmcnt(0)
	v_pk_fma_f32 v[102:103], v[102:103], v[110:111], v[106:107]
	v_pk_fma_f32 v[104:105], v[104:105], v[112:113], v[108:109]
	v_or_b32_e32 v106, v156, v148
	global_store_dwordx4 v[98:99], v[102:105], off
	v_cmp_gt_i32_e32 vcc, s39, v106
	s_nop 0
	v_ashrrev_i32_e32 v102, 31, v106
	v_add_u32_e32 v104, 0xffff8000, v106
	v_cndmask_b32_e32 v103, 0, v102, vcc
	v_cndmask_b32_e32 v102, v104, v106, vcc
	v_cndmask_b32_e32 v105, v144, v145, vcc
	v_cndmask_b32_e32 v104, v146, v147, vcc
	v_lshlrev_b64 v[102:103], 12, v[102:103]
	v_lshl_add_u64 v[102:103], v[104:105], 0, v[102:103]
	v_min_i32_e32 v104, 0x8000, v106
	v_ashrrev_i32_e32 v104, 12, v104
	v_mul_hi_i32_i24_e32 v105, 0x6000, v104
	v_mul_i32_i24_e32 v104, 0x6000, v104
	v_lshl_add_u64 v[102:103], v[102:103], 0, v[96:97]
	v_lshl_add_u64 v[104:105], s[0:1], 0, v[104:105]
	v_lshl_add_u64 v[104:105], v[104:105], 0, v[96:97]
	ds_read_b128 v[106:109], v130 offset:1088
	global_load_dwordx4 v[110:113], v[102:103], off
	global_load_dwordx4 v[114:117], v[104:105], off
	s_waitcnt vmcnt(0) lgkmcnt(0)
	v_pk_fma_f32 v[106:107], v[106:107], v[114:115], v[110:111]
	v_pk_fma_f32 v[108:109], v[108:109], v[116:117], v[112:113]
	v_or_b32_e32 v110, v156, v149
	global_store_dwordx4 v[102:103], v[106:109], off
	v_cmp_gt_i32_e32 vcc, s39, v110
	s_nop 0
	v_ashrrev_i32_e32 v106, 31, v110
	v_add_u32_e32 v108, 0xffff8000, v110
	v_cndmask_b32_e32 v107, 0, v106, vcc
	v_cndmask_b32_e32 v106, v108, v110, vcc
	v_cndmask_b32_e32 v109, v144, v145, vcc
	v_cndmask_b32_e32 v108, v146, v147, vcc
	v_lshlrev_b64 v[106:107], 12, v[106:107]
	v_lshl_add_u64 v[106:107], v[108:109], 0, v[106:107]
	v_min_i32_e32 v108, 0x8000, v110
	v_ashrrev_i32_e32 v108, 12, v108
	v_mul_hi_i32_i24_e32 v109, 0x6000, v108
	v_mul_i32_i24_e32 v108, 0x6000, v108
	v_lshl_add_u64 v[106:107], v[106:107], 0, v[96:97]
	v_lshl_add_u64 v[108:109], s[0:1], 0, v[108:109]
	v_lshl_add_u64 v[108:109], v[108:109], 0, v[96:97]
	ds_read_b128 v[110:113], v130 offset:2176
	global_load_dwordx4 v[114:117], v[106:107], off
	global_load_dwordx4 v[118:121], v[108:109], off
	s_waitcnt vmcnt(0) lgkmcnt(0)
	v_pk_fma_f32 v[110:111], v[110:111], v[118:119], v[114:115]
	v_pk_fma_f32 v[112:113], v[112:113], v[120:121], v[116:117]
	v_or_b32_e32 v114, v156, v150
	global_store_dwordx4 v[106:107], v[110:113], off
	v_cmp_gt_i32_e32 vcc, s39, v114
	s_nop 0
	v_ashrrev_i32_e32 v110, 31, v114
	v_add_u32_e32 v112, 0xffff8000, v114
	v_cndmask_b32_e32 v111, 0, v110, vcc
	v_cndmask_b32_e32 v110, v112, v114, vcc
	v_cndmask_b32_e32 v113, v144, v145, vcc
	v_cndmask_b32_e32 v112, v146, v147, vcc
	v_lshlrev_b64 v[110:111], 12, v[110:111]
	v_lshl_add_u64 v[110:111], v[112:113], 0, v[110:111]
	v_min_i32_e32 v112, 0x8000, v114
	v_ashrrev_i32_e32 v112, 12, v112
	v_mul_hi_i32_i24_e32 v113, 0x6000, v112
	v_mul_i32_i24_e32 v112, 0x6000, v112
	v_lshl_add_u64 v[110:111], v[110:111], 0, v[96:97]
	v_lshl_add_u64 v[112:113], s[0:1], 0, v[112:113]
	v_lshl_add_u64 v[112:113], v[112:113], 0, v[96:97]
	ds_read_b128 v[114:117], v130 offset:3264
	global_load_dwordx4 v[118:121], v[110:111], off
	global_load_dwordx4 v[122:125], v[112:113], off
	s_waitcnt vmcnt(0) lgkmcnt(0)
	v_pk_fma_f32 v[114:115], v[114:115], v[122:123], v[118:119]
	v_pk_fma_f32 v[116:117], v[116:117], v[124:125], v[120:121]
	v_or_b32_e32 v118, v156, v151
	global_store_dwordx4 v[110:111], v[114:117], off
	v_cmp_gt_i32_e32 vcc, s39, v118
	s_nop 0
	v_ashrrev_i32_e32 v114, 31, v118
	v_add_u32_e32 v116, 0xffff8000, v118
	v_cndmask_b32_e32 v115, 0, v114, vcc
	v_cndmask_b32_e32 v114, v116, v118, vcc
	v_cndmask_b32_e32 v117, v144, v145, vcc
	v_cndmask_b32_e32 v116, v146, v147, vcc
	v_lshlrev_b64 v[114:115], 12, v[114:115]
	v_lshl_add_u64 v[114:115], v[116:117], 0, v[114:115]
	v_min_i32_e32 v116, 0x8000, v118
	v_ashrrev_i32_e32 v116, 12, v116
	v_mul_hi_i32_i24_e32 v117, 0x6000, v116
	v_mul_i32_i24_e32 v116, 0x6000, v116
	v_lshl_add_u64 v[114:115], v[114:115], 0, v[96:97]
	v_lshl_add_u64 v[116:117], s[0:1], 0, v[116:117]
	v_lshl_add_u64 v[116:117], v[116:117], 0, v[96:97]
	ds_read_b128 v[118:121], v130 offset:4352
	global_load_dwordx4 v[122:125], v[114:115], off
	global_load_dwordx4 v[126:129], v[116:117], off
	s_waitcnt vmcnt(0) lgkmcnt(0)
	v_pk_fma_f32 v[118:119], v[118:119], v[126:127], v[122:123]
	v_pk_fma_f32 v[120:121], v[120:121], v[128:129], v[124:125]
	v_or_b32_e32 v122, v156, v152
	global_store_dwordx4 v[114:115], v[118:121], off
	v_cmp_gt_i32_e32 vcc, s39, v122
	s_nop 0
	v_ashrrev_i32_e32 v118, 31, v122
	v_add_u32_e32 v120, 0xffff8000, v122
	v_cndmask_b32_e32 v119, 0, v118, vcc
	v_cndmask_b32_e32 v118, v120, v122, vcc
	v_cndmask_b32_e32 v121, v144, v145, vcc
	v_cndmask_b32_e32 v120, v146, v147, vcc
	v_lshlrev_b64 v[118:119], 12, v[118:119]
	v_lshl_add_u64 v[118:119], v[120:121], 0, v[118:119]
	v_min_i32_e32 v120, 0x8000, v122
	v_ashrrev_i32_e32 v120, 12, v120
	v_mul_hi_i32_i24_e32 v121, 0x6000, v120
	v_mul_i32_i24_e32 v120, 0x6000, v120
	v_lshl_add_u64 v[118:119], v[118:119], 0, v[96:97]
	v_lshl_add_u64 v[120:121], s[0:1], 0, v[120:121]
	v_lshl_add_u64 v[120:121], v[120:121], 0, v[96:97]
	ds_read_b128 v[122:125], v130 offset:5440
	global_load_dwordx4 v[126:129], v[118:119], off
	global_load_dwordx4 v[158:161], v[120:121], off
	s_waitcnt vmcnt(0) lgkmcnt(0)
	v_pk_fma_f32 v[122:123], v[122:123], v[158:159], v[126:127]
	v_pk_fma_f32 v[124:125], v[124:125], v[160:161], v[128:129]
	v_or_b32_e32 v126, v156, v153
	global_store_dwordx4 v[118:119], v[122:125], off
	v_cmp_gt_i32_e32 vcc, s39, v126
	s_nop 0
	v_ashrrev_i32_e32 v122, 31, v126
	v_add_u32_e32 v124, 0xffff8000, v126
	v_cndmask_b32_e32 v123, 0, v122, vcc
	v_cndmask_b32_e32 v122, v124, v126, vcc
	v_cndmask_b32_e32 v125, v144, v145, vcc
	v_cndmask_b32_e32 v124, v146, v147, vcc
	v_lshlrev_b64 v[122:123], 12, v[122:123]
	v_lshl_add_u64 v[122:123], v[124:125], 0, v[122:123]
	v_min_i32_e32 v124, 0x8000, v126
	v_ashrrev_i32_e32 v124, 12, v124
	v_mul_hi_i32_i24_e32 v125, 0x6000, v124
	v_mul_i32_i24_e32 v124, 0x6000, v124
	v_lshl_add_u64 v[122:123], v[122:123], 0, v[96:97]
	v_lshl_add_u64 v[124:125], s[0:1], 0, v[124:125]
	v_lshl_add_u64 v[124:125], v[124:125], 0, v[96:97]
	ds_read_b128 v[126:129], v130 offset:6528
	global_load_dwordx4 v[158:161], v[122:123], off
	global_load_dwordx4 v[162:165], v[124:125], off
	v_cmp_gt_i32_e32 vcc, s39, v157
	s_waitcnt vmcnt(0) lgkmcnt(0)
	v_pk_fma_f32 v[126:127], v[126:127], v[162:163], v[158:159]
	v_pk_fma_f32 v[128:129], v[128:129], v[164:165], v[160:161]
	global_store_dwordx4 v[122:123], v[126:129], off
	ds_read_b128 v[158:161], v130 offset:7616
	s_nop 0
	v_ashrrev_i32_e32 v126, 31, v157
	v_add_u32_e32 v128, 0xffff8000, v157
	v_cndmask_b32_e32 v127, 0, v126, vcc
	v_cndmask_b32_e32 v126, v128, v157, vcc
	v_cndmask_b32_e32 v129, v144, v145, vcc
	v_cndmask_b32_e32 v128, v146, v147, vcc
	v_lshlrev_b64 v[126:127], 12, v[126:127]
	v_lshl_add_u64 v[126:127], v[128:129], 0, v[126:127]
	v_min_i32_e32 v128, 0x8000, v157
	v_ashrrev_i32_e32 v128, 12, v128
	v_mul_hi_i32_i24_e32 v129, 0x6000, v128
	v_mul_i32_i24_e32 v128, 0x6000, v128
	v_lshl_add_u64 v[126:127], v[126:127], 0, v[96:97]
	v_lshl_add_u64 v[128:129], s[0:1], 0, v[128:129]
	v_lshl_add_u64 v[128:129], v[128:129], 0, v[96:97]
	global_load_dwordx4 v[162:165], v[126:127], off
	global_load_dwordx4 v[166:169], v[128:129], off
	s_waitcnt vmcnt(0) lgkmcnt(0)
	v_pk_fma_f32 v[158:159], v[158:159], v[166:167], v[162:163]
	v_pk_fma_f32 v[160:161], v[160:161], v[168:169], v[164:165]
	global_store_dwordx4 v[126:127], v[158:161], off
	s_waitcnt lgkmcnt(0)
	ds_write2_b32 v131, v80, v81 offset1:68
	ds_write2_b32 v132, v64, v65 offset0:32 offset1:100
	ds_write2_b32 v131, v82, v83 offset0:136 offset1:204
	ds_write2_b32 v132, v66, v67 offset0:168 offset1:236
	ds_write2_b32 v133, v84, v85 offset0:32 offset1:100
	ds_write2_b32 v134, v68, v69 offset0:64 offset1:132
	ds_write2_b32 v133, v86, v87 offset0:168 offset1:236
	ds_write2_b32 v135, v70, v71 offset0:72 offset1:140
	ds_write2_b32 v136, v88, v89 offset0:64 offset1:132
	ds_write2_b32 v137, v72, v73 offset0:96 offset1:164
	ds_write2_b32 v138, v90, v91 offset0:72 offset1:140
	ds_write2_b32 v139, v74, v75 offset0:104 offset1:172
	ds_write2_b32 v140, v92, v93 offset0:96 offset1:164
	ds_write2_b32 v141, v76, v77 offset0:128 offset1:196
	ds_write2_b32 v142, v94, v95 offset0:104 offset1:172
	ds_write2_b32 v143, v78, v79 offset0:8 offset1:76
	s_waitcnt lgkmcnt(0)
	ds_read_b128 v[64:67], v130
	global_load_dwordx4 v[68:71], v[98:99], off offset:256
	global_load_dwordx4 v[72:75], v[100:101], off offset:256
	s_waitcnt vmcnt(0) lgkmcnt(0)
	v_pk_fma_f32 v[64:65], v[64:65], v[72:73], v[68:69]
	v_pk_fma_f32 v[66:67], v[66:67], v[74:75], v[70:71]
	global_store_dwordx4 v[98:99], v[64:67], off offset:256
	ds_read_b128 v[64:67], v130 offset:1088
	global_load_dwordx4 v[68:71], v[102:103], off offset:256
	global_load_dwordx4 v[72:75], v[104:105], off offset:256
	s_waitcnt vmcnt(0) lgkmcnt(0)
	v_pk_fma_f32 v[64:65], v[64:65], v[72:73], v[68:69]
	v_pk_fma_f32 v[66:67], v[66:67], v[74:75], v[70:71]
	global_store_dwordx4 v[102:103], v[64:67], off offset:256
	ds_read_b128 v[64:67], v130 offset:2176
	global_load_dwordx4 v[68:71], v[106:107], off offset:256
	global_load_dwordx4 v[72:75], v[108:109], off offset:256
	s_waitcnt vmcnt(0) lgkmcnt(0)
	v_pk_fma_f32 v[64:65], v[64:65], v[72:73], v[68:69]
	v_pk_fma_f32 v[66:67], v[66:67], v[74:75], v[70:71]
	global_store_dwordx4 v[106:107], v[64:67], off offset:256
	ds_read_b128 v[64:67], v130 offset:3264
	global_load_dwordx4 v[68:71], v[110:111], off offset:256
	global_load_dwordx4 v[72:75], v[112:113], off offset:256
	s_waitcnt vmcnt(0) lgkmcnt(0)
	v_pk_fma_f32 v[64:65], v[64:65], v[72:73], v[68:69]
	v_pk_fma_f32 v[66:67], v[66:67], v[74:75], v[70:71]
	global_store_dwordx4 v[110:111], v[64:67], off offset:256
	ds_read_b128 v[64:67], v130 offset:4352
	global_load_dwordx4 v[68:71], v[114:115], off offset:256
	global_load_dwordx4 v[72:75], v[116:117], off offset:256
	s_waitcnt vmcnt(0) lgkmcnt(0)
	v_pk_fma_f32 v[64:65], v[64:65], v[72:73], v[68:69]
	v_pk_fma_f32 v[66:67], v[66:67], v[74:75], v[70:71]
	global_store_dwordx4 v[114:115], v[64:67], off offset:256
	ds_read_b128 v[64:67], v130 offset:5440
	global_load_dwordx4 v[68:71], v[118:119], off offset:256
	global_load_dwordx4 v[72:75], v[120:121], off offset:256
	s_waitcnt vmcnt(0) lgkmcnt(0)
	v_pk_fma_f32 v[64:65], v[64:65], v[72:73], v[68:69]
	v_pk_fma_f32 v[66:67], v[66:67], v[74:75], v[70:71]
	global_store_dwordx4 v[118:119], v[64:67], off offset:256
	ds_read_b128 v[64:67], v130 offset:6528
	global_load_dwordx4 v[68:71], v[122:123], off offset:256
	global_load_dwordx4 v[72:75], v[124:125], off offset:256
	s_waitcnt vmcnt(0) lgkmcnt(0)
	v_pk_fma_f32 v[64:65], v[64:65], v[72:73], v[68:69]
	v_pk_fma_f32 v[66:67], v[66:67], v[74:75], v[70:71]
	global_store_dwordx4 v[122:123], v[64:67], off offset:256
	ds_read_b128 v[64:67], v130 offset:7616
	global_load_dwordx4 v[68:71], v[126:127], off offset:256
	global_load_dwordx4 v[72:75], v[128:129], off offset:256
	s_waitcnt vmcnt(0) lgkmcnt(0)
	v_pk_fma_f32 v[64:65], v[64:65], v[72:73], v[68:69]
	v_pk_fma_f32 v[66:67], v[66:67], v[74:75], v[70:71]
	global_store_dwordx4 v[126:127], v[64:67], off offset:256
	s_waitcnt lgkmcnt(0)
	ds_write2_b32 v131, v48, v49 offset1:68
	ds_write2_b32 v132, v32, v33 offset0:32 offset1:100
	ds_write2_b32 v131, v50, v51 offset0:136 offset1:204
	ds_write2_b32 v132, v34, v35 offset0:168 offset1:236
	ds_write2_b32 v133, v52, v53 offset0:32 offset1:100
	ds_write2_b32 v134, v36, v37 offset0:64 offset1:132
	ds_write2_b32 v133, v54, v55 offset0:168 offset1:236
	ds_write2_b32 v135, v38, v39 offset0:72 offset1:140
	ds_write2_b32 v136, v56, v57 offset0:64 offset1:132
	ds_write2_b32 v137, v40, v41 offset0:96 offset1:164
	ds_write2_b32 v138, v58, v59 offset0:72 offset1:140
	ds_write2_b32 v139, v42, v43 offset0:104 offset1:172
	ds_write2_b32 v140, v60, v61 offset0:96 offset1:164
	ds_write2_b32 v141, v44, v45 offset0:128 offset1:196
	ds_write2_b32 v142, v62, v63 offset0:104 offset1:172
	ds_write2_b32 v143, v46, v47 offset0:8 offset1:76
	v_or_b32_e32 v64, 32, v156
	v_or_b32_e32 v36, v64, v155
	v_cmp_gt_i32_e32 vcc, s39, v36
	v_ashrrev_i32_e32 v32, 31, v36
	v_add_u32_e32 v34, 0xffff8000, v36
	v_cndmask_b32_e32 v33, 0, v32, vcc
	v_cndmask_b32_e32 v32, v34, v36, vcc
	v_cndmask_b32_e32 v35, v144, v145, vcc
	v_cndmask_b32_e32 v34, v146, v147, vcc
	v_lshlrev_b64 v[32:33], 12, v[32:33]
	v_lshl_add_u64 v[32:33], v[34:35], 0, v[32:33]
	v_min_i32_e32 v34, 0x8000, v36
	v_ashrrev_i32_e32 v34, 12, v34
	v_mul_hi_i32_i24_e32 v35, 0x6000, v34
	v_mul_i32_i24_e32 v34, 0x6000, v34
	s_waitcnt lgkmcnt(0)
	v_lshl_add_u64 v[32:33], v[32:33], 0, v[96:97]
	v_lshl_add_u64 v[34:35], s[0:1], 0, v[34:35]
	v_lshl_add_u64 v[34:35], v[34:35], 0, v[96:97]
	ds_read_b128 v[36:39], v130
	global_load_dwordx4 v[40:43], v[32:33], off
	global_load_dwordx4 v[44:47], v[34:35], off
	s_waitcnt vmcnt(0) lgkmcnt(0)
	v_pk_fma_f32 v[36:37], v[36:37], v[44:45], v[40:41]
	v_pk_fma_f32 v[38:39], v[38:39], v[46:47], v[42:43]
	v_or_b32_e32 v40, v64, v148
	global_store_dwordx4 v[32:33], v[36:39], off
	v_cmp_gt_i32_e32 vcc, s39, v40
	s_nop 0
	v_ashrrev_i32_e32 v36, 31, v40
	v_add_u32_e32 v38, 0xffff8000, v40
	v_cndmask_b32_e32 v37, 0, v36, vcc
	v_cndmask_b32_e32 v36, v38, v40, vcc
	v_cndmask_b32_e32 v39, v144, v145, vcc
	v_cndmask_b32_e32 v38, v146, v147, vcc
	v_lshlrev_b64 v[36:37], 12, v[36:37]
	v_lshl_add_u64 v[36:37], v[38:39], 0, v[36:37]
	v_min_i32_e32 v38, 0x8000, v40
	v_ashrrev_i32_e32 v38, 12, v38
	v_mul_hi_i32_i24_e32 v39, 0x6000, v38
	v_mul_i32_i24_e32 v38, 0x6000, v38
	v_lshl_add_u64 v[36:37], v[36:37], 0, v[96:97]
	v_lshl_add_u64 v[38:39], s[0:1], 0, v[38:39]
	v_lshl_add_u64 v[38:39], v[38:39], 0, v[96:97]
	ds_read_b128 v[40:43], v130 offset:1088
	global_load_dwordx4 v[44:47], v[36:37], off
	global_load_dwordx4 v[48:51], v[38:39], off
	s_waitcnt vmcnt(0) lgkmcnt(0)
	v_pk_fma_f32 v[40:41], v[40:41], v[48:49], v[44:45]
	v_pk_fma_f32 v[42:43], v[42:43], v[50:51], v[46:47]
	v_or_b32_e32 v44, v64, v149
	global_store_dwordx4 v[36:37], v[40:43], off
	v_cmp_gt_i32_e32 vcc, s39, v44
	s_nop 0
	v_ashrrev_i32_e32 v40, 31, v44
	v_add_u32_e32 v42, 0xffff8000, v44
	v_cndmask_b32_e32 v41, 0, v40, vcc
	v_cndmask_b32_e32 v40, v42, v44, vcc
	v_cndmask_b32_e32 v43, v144, v145, vcc
	v_cndmask_b32_e32 v42, v146, v147, vcc
	v_lshlrev_b64 v[40:41], 12, v[40:41]
	v_lshl_add_u64 v[40:41], v[42:43], 0, v[40:41]
	v_min_i32_e32 v42, 0x8000, v44
	v_ashrrev_i32_e32 v42, 12, v42
	v_mul_hi_i32_i24_e32 v43, 0x6000, v42
	v_mul_i32_i24_e32 v42, 0x6000, v42
	v_lshl_add_u64 v[40:41], v[40:41], 0, v[96:97]
	v_lshl_add_u64 v[42:43], s[0:1], 0, v[42:43]
	v_lshl_add_u64 v[42:43], v[42:43], 0, v[96:97]
	ds_read_b128 v[44:47], v130 offset:2176
	global_load_dwordx4 v[48:51], v[40:41], off
	global_load_dwordx4 v[52:55], v[42:43], off
	s_waitcnt vmcnt(0) lgkmcnt(0)
	v_pk_fma_f32 v[44:45], v[44:45], v[52:53], v[48:49]
	v_pk_fma_f32 v[46:47], v[46:47], v[54:55], v[50:51]
	v_or_b32_e32 v48, v64, v150
	global_store_dwordx4 v[40:41], v[44:47], off
	v_cmp_gt_i32_e32 vcc, s39, v48
	s_nop 0
	v_ashrrev_i32_e32 v44, 31, v48
	v_add_u32_e32 v46, 0xffff8000, v48
	v_cndmask_b32_e32 v45, 0, v44, vcc
	v_cndmask_b32_e32 v44, v46, v48, vcc
	v_cndmask_b32_e32 v47, v144, v145, vcc
	v_cndmask_b32_e32 v46, v146, v147, vcc
	v_lshlrev_b64 v[44:45], 12, v[44:45]
	v_lshl_add_u64 v[44:45], v[46:47], 0, v[44:45]
	v_min_i32_e32 v46, 0x8000, v48
	v_ashrrev_i32_e32 v46, 12, v46
	v_mul_hi_i32_i24_e32 v47, 0x6000, v46
	v_mul_i32_i24_e32 v46, 0x6000, v46
	v_lshl_add_u64 v[44:45], v[44:45], 0, v[96:97]
	v_lshl_add_u64 v[46:47], s[0:1], 0, v[46:47]
	v_lshl_add_u64 v[46:47], v[46:47], 0, v[96:97]
	ds_read_b128 v[48:51], v130 offset:3264
	global_load_dwordx4 v[52:55], v[44:45], off
	global_load_dwordx4 v[56:59], v[46:47], off
	s_waitcnt vmcnt(0) lgkmcnt(0)
	v_pk_fma_f32 v[48:49], v[48:49], v[56:57], v[52:53]
	v_pk_fma_f32 v[50:51], v[50:51], v[58:59], v[54:55]
	v_or_b32_e32 v52, v64, v151
	global_store_dwordx4 v[44:45], v[48:51], off
	v_cmp_gt_i32_e32 vcc, s39, v52
	s_nop 0
	v_ashrrev_i32_e32 v48, 31, v52
	v_add_u32_e32 v50, 0xffff8000, v52
	v_cndmask_b32_e32 v49, 0, v48, vcc
	v_cndmask_b32_e32 v48, v50, v52, vcc
	v_cndmask_b32_e32 v51, v144, v145, vcc
	v_cndmask_b32_e32 v50, v146, v147, vcc
	v_lshlrev_b64 v[48:49], 12, v[48:49]
	v_lshl_add_u64 v[48:49], v[50:51], 0, v[48:49]
	v_min_i32_e32 v50, 0x8000, v52
	v_ashrrev_i32_e32 v50, 12, v50
	v_mul_hi_i32_i24_e32 v51, 0x6000, v50
	v_mul_i32_i24_e32 v50, 0x6000, v50
	v_lshl_add_u64 v[48:49], v[48:49], 0, v[96:97]
	v_lshl_add_u64 v[50:51], s[0:1], 0, v[50:51]
	v_lshl_add_u64 v[50:51], v[50:51], 0, v[96:97]
	ds_read_b128 v[52:55], v130 offset:4352
	global_load_dwordx4 v[56:59], v[48:49], off
	global_load_dwordx4 v[60:63], v[50:51], off
	s_waitcnt vmcnt(0) lgkmcnt(0)
	v_pk_fma_f32 v[52:53], v[52:53], v[60:61], v[56:57]
	v_pk_fma_f32 v[54:55], v[54:55], v[62:63], v[58:59]
	v_or_b32_e32 v56, v64, v152
	global_store_dwordx4 v[48:49], v[52:55], off
	v_cmp_gt_i32_e32 vcc, s39, v56
	s_nop 0
	v_ashrrev_i32_e32 v52, 31, v56
	v_add_u32_e32 v54, 0xffff8000, v56
	v_cndmask_b32_e32 v53, 0, v52, vcc
	v_cndmask_b32_e32 v52, v54, v56, vcc
	v_cndmask_b32_e32 v55, v144, v145, vcc
	v_cndmask_b32_e32 v54, v146, v147, vcc
	v_lshlrev_b64 v[52:53], 12, v[52:53]
	v_lshl_add_u64 v[52:53], v[54:55], 0, v[52:53]
	v_min_i32_e32 v54, 0x8000, v56
	v_ashrrev_i32_e32 v54, 12, v54
	v_mul_hi_i32_i24_e32 v55, 0x6000, v54
	v_mul_i32_i24_e32 v54, 0x6000, v54
	v_lshl_add_u64 v[52:53], v[52:53], 0, v[96:97]
	v_lshl_add_u64 v[54:55], s[0:1], 0, v[54:55]
	v_lshl_add_u64 v[54:55], v[54:55], 0, v[96:97]
	ds_read_b128 v[56:59], v130 offset:5440
	global_load_dwordx4 v[60:63], v[52:53], off
	global_load_dwordx4 v[66:69], v[54:55], off
	s_waitcnt vmcnt(0) lgkmcnt(0)
	v_pk_fma_f32 v[56:57], v[56:57], v[66:67], v[60:61]
	v_pk_fma_f32 v[58:59], v[58:59], v[68:69], v[62:63]
	v_or_b32_e32 v60, v64, v153
	global_store_dwordx4 v[52:53], v[56:59], off
	v_cmp_gt_i32_e32 vcc, s39, v60
	v_or_b32_e32 v64, v64, v154
	v_ashrrev_i32_e32 v56, 31, v60
	v_add_u32_e32 v58, 0xffff8000, v60
	v_cndmask_b32_e32 v57, 0, v56, vcc
	v_cndmask_b32_e32 v56, v58, v60, vcc
	v_cndmask_b32_e32 v59, v144, v145, vcc
	v_cndmask_b32_e32 v58, v146, v147, vcc
	v_lshlrev_b64 v[56:57], 12, v[56:57]
	v_lshl_add_u64 v[56:57], v[58:59], 0, v[56:57]
	v_min_i32_e32 v58, 0x8000, v60
	v_ashrrev_i32_e32 v58, 12, v58
	v_mul_hi_i32_i24_e32 v59, 0x6000, v58
	v_mul_i32_i24_e32 v58, 0x6000, v58
	v_lshl_add_u64 v[56:57], v[56:57], 0, v[96:97]
	v_lshl_add_u64 v[58:59], s[0:1], 0, v[58:59]
	v_lshl_add_u64 v[58:59], v[58:59], 0, v[96:97]
	ds_read_b128 v[60:63], v130 offset:6528
	global_load_dwordx4 v[66:69], v[56:57], off
	global_load_dwordx4 v[70:73], v[58:59], off
	v_cmp_gt_i32_e32 vcc, s39, v64
	s_waitcnt vmcnt(0) lgkmcnt(0)
	v_pk_fma_f32 v[60:61], v[60:61], v[70:71], v[66:67]
	v_pk_fma_f32 v[62:63], v[62:63], v[72:73], v[68:69]
	global_store_dwordx4 v[56:57], v[60:63], off
	s_nop 1
	v_ashrrev_i32_e32 v60, 31, v64
	v_add_u32_e32 v62, 0xffff8000, v64
	v_cndmask_b32_e32 v61, 0, v60, vcc
	v_cndmask_b32_e32 v60, v62, v64, vcc
	v_cndmask_b32_e32 v63, v144, v145, vcc
	v_cndmask_b32_e32 v62, v146, v147, vcc
	v_lshlrev_b64 v[60:61], 12, v[60:61]
	v_lshl_add_u64 v[60:61], v[62:63], 0, v[60:61]
	v_min_i32_e32 v62, 0x8000, v64
	v_ashrrev_i32_e32 v62, 12, v62
	v_mul_hi_i32_i24_e32 v63, 0x6000, v62
	v_mul_i32_i24_e32 v62, 0x6000, v62
	v_lshl_add_u64 v[60:61], v[60:61], 0, v[96:97]
	v_lshl_add_u64 v[62:63], s[0:1], 0, v[62:63]
	v_lshl_add_u64 v[62:63], v[62:63], 0, v[96:97]
	ds_read_b128 v[64:67], v130 offset:7616
	global_load_dwordx4 v[68:71], v[60:61], off
	global_load_dwordx4 v[72:75], v[62:63], off
	s_waitcnt vmcnt(0) lgkmcnt(0)
	v_pk_fma_f32 v[64:65], v[64:65], v[72:73], v[68:69]
	v_pk_fma_f32 v[66:67], v[66:67], v[74:75], v[70:71]
	global_store_dwordx4 v[60:61], v[64:67], off
	s_waitcnt lgkmcnt(0)
	ds_write2_b32 v131, v16, v17 offset1:68
	ds_write2_b32 v132, v0, v1 offset0:32 offset1:100
	ds_write2_b32 v131, v18, v19 offset0:136 offset1:204
	ds_write2_b32 v132, v2, v3 offset0:168 offset1:236
	ds_write2_b32 v133, v20, v21 offset0:32 offset1:100
	ds_write2_b32 v134, v4, v5 offset0:64 offset1:132
	ds_write2_b32 v133, v22, v23 offset0:168 offset1:236
	ds_write2_b32 v135, v6, v7 offset0:72 offset1:140
	ds_write2_b32 v136, v24, v25 offset0:64 offset1:132
	ds_write2_b32 v137, v8, v9 offset0:96 offset1:164
	ds_write2_b32 v138, v26, v27 offset0:72 offset1:140
	ds_write2_b32 v139, v10, v11 offset0:104 offset1:172
	ds_write2_b32 v140, v28, v29 offset0:96 offset1:164
	ds_write2_b32 v141, v12, v13 offset0:128 offset1:196
	ds_write2_b32 v142, v30, v31 offset0:104 offset1:172
	ds_write2_b32 v143, v14, v15 offset0:8 offset1:76
	s_waitcnt lgkmcnt(0)
	ds_read_b128 v[0:3], v130
	global_load_dwordx4 v[4:7], v[32:33], off offset:256
	global_load_dwordx4 v[8:11], v[34:35], off offset:256
	s_waitcnt vmcnt(0) lgkmcnt(0)
	v_pk_fma_f32 v[0:1], v[0:1], v[8:9], v[4:5]
	v_pk_fma_f32 v[2:3], v[2:3], v[10:11], v[6:7]
	global_store_dwordx4 v[32:33], v[0:3], off offset:256
	ds_read_b128 v[0:3], v130 offset:1088
	global_load_dwordx4 v[4:7], v[36:37], off offset:256
	global_load_dwordx4 v[8:11], v[38:39], off offset:256
	s_waitcnt vmcnt(0) lgkmcnt(0)
	v_pk_fma_f32 v[0:1], v[0:1], v[8:9], v[4:5]
	v_pk_fma_f32 v[2:3], v[2:3], v[10:11], v[6:7]
	global_store_dwordx4 v[36:37], v[0:3], off offset:256
	ds_read_b128 v[0:3], v130 offset:2176
	global_load_dwordx4 v[4:7], v[40:41], off offset:256
	global_load_dwordx4 v[8:11], v[42:43], off offset:256
	s_waitcnt vmcnt(0) lgkmcnt(0)
	v_pk_fma_f32 v[0:1], v[0:1], v[8:9], v[4:5]
	v_pk_fma_f32 v[2:3], v[2:3], v[10:11], v[6:7]
	global_store_dwordx4 v[40:41], v[0:3], off offset:256
	ds_read_b128 v[0:3], v130 offset:3264
	global_load_dwordx4 v[4:7], v[44:45], off offset:256
	global_load_dwordx4 v[8:11], v[46:47], off offset:256
	s_waitcnt vmcnt(0) lgkmcnt(0)
	v_pk_fma_f32 v[0:1], v[0:1], v[8:9], v[4:5]
	v_pk_fma_f32 v[2:3], v[2:3], v[10:11], v[6:7]
	global_store_dwordx4 v[44:45], v[0:3], off offset:256
	ds_read_b128 v[0:3], v130 offset:4352
	global_load_dwordx4 v[4:7], v[48:49], off offset:256
	global_load_dwordx4 v[8:11], v[50:51], off offset:256
	s_waitcnt vmcnt(0) lgkmcnt(0)
	v_pk_fma_f32 v[0:1], v[0:1], v[8:9], v[4:5]
	v_pk_fma_f32 v[2:3], v[2:3], v[10:11], v[6:7]
	global_store_dwordx4 v[48:49], v[0:3], off offset:256
	ds_read_b128 v[0:3], v130 offset:5440
	global_load_dwordx4 v[4:7], v[52:53], off offset:256
	global_load_dwordx4 v[8:11], v[54:55], off offset:256
	s_waitcnt vmcnt(0) lgkmcnt(0)
	v_pk_fma_f32 v[0:1], v[0:1], v[8:9], v[4:5]
	v_pk_fma_f32 v[2:3], v[2:3], v[10:11], v[6:7]
	global_store_dwordx4 v[52:53], v[0:3], off offset:256
	ds_read_b128 v[0:3], v130 offset:6528
	global_load_dwordx4 v[4:7], v[56:57], off offset:256
	global_load_dwordx4 v[8:11], v[58:59], off offset:256
	s_waitcnt vmcnt(0) lgkmcnt(0)
	v_pk_fma_f32 v[0:1], v[0:1], v[8:9], v[4:5]
	v_pk_fma_f32 v[2:3], v[2:3], v[10:11], v[6:7]
	global_store_dwordx4 v[56:57], v[0:3], off offset:256
	ds_read_b128 v[0:3], v130 offset:7616
	global_load_dwordx4 v[4:7], v[60:61], off offset:256
	global_load_dwordx4 v[8:11], v[62:63], off offset:256
	s_waitcnt vmcnt(0) lgkmcnt(0)
	v_pk_fma_f32 v[0:1], v[0:1], v[8:9], v[4:5]
	v_pk_fma_f32 v[2:3], v[2:3], v[10:11], v[6:7]
	global_store_dwordx4 v[60:61], v[0:3], off offset:256
	s_waitcnt lgkmcnt(0)
	s_barrier
	s_cbranch_scc1 .LBB0_1086
